# on top of the best version: SGU epilogue bias loads hoisted (no store-draining wait) and mid-phase reductions/partner shuffles via DPP instead of ds_bpermute
# speedup vs baseline: 1.0040x; 1.0040x over previous
.LBB0_277:
	s_lshl_b32 s11, s10, 7
	v_add_u32_e32 v4, s11, v102
	v_mad_i64_i32 v[2:3], s[14:15], v4, s55, v[76:77]
	global_load_dwordx4 v[62:65], v[2:3], off offset:1536 nt
	global_load_dwordx4 v[58:61], v[2:3], off offset:2048 nt
	v_add_u32_e32 v2, 16, v4
	v_mad_i64_i32 v[2:3], s[14:15], v2, s55, v[76:77]
	global_load_dwordx4 v[54:57], v[2:3], off offset:1536 nt
	global_load_dwordx4 v[50:53], v[2:3], off offset:2048 nt
	v_add_u32_e32 v2, 32, v4
	v_mad_i64_i32 v[2:3], s[14:15], v2, s55, v[76:77]
	global_load_dwordx4 v[46:49], v[2:3], off offset:1536 nt
	global_load_dwordx4 v[42:45], v[2:3], off offset:2048 nt
	v_add_u32_e32 v2, 48, v4
	v_mad_i64_i32 v[2:3], s[14:15], v2, s55, v[76:77]
	global_load_dwordx4 v[38:41], v[2:3], off offset:1536 nt
	global_load_dwordx4 v[34:37], v[2:3], off offset:2048 nt
	v_add_u32_e32 v2, 64, v4
	v_mad_i64_i32 v[2:3], s[14:15], v2, s55, v[76:77]
	global_load_dwordx4 v[30:33], v[2:3], off offset:1536 nt
	global_load_dwordx4 v[26:29], v[2:3], off offset:2048 nt
	v_add_u32_e32 v2, 0x50, v4
	v_mad_i64_i32 v[2:3], s[14:15], v2, s55, v[76:77]
	global_load_dwordx4 v[22:25], v[2:3], off offset:1536 nt
	global_load_dwordx4 v[18:21], v[2:3], off offset:2048 nt
	v_add_u32_e32 v2, 0x60, v4
	v_mad_i64_i32 v[2:3], s[14:15], v2, s55, v[76:77]
	global_load_dwordx4 v[14:17], v[2:3], off offset:1536 nt
	global_load_dwordx4 v[10:13], v[2:3], off offset:2048 nt
	v_add_u32_e32 v2, 0x70, v4
	v_mad_i64_i32 v[2:3], s[14:15], v2, s55, v[76:77]
	global_load_dwordx4 v[6:9], v[2:3], off offset:1536 nt
	s_nop 0
	global_load_dwordx4 v[2:5], v[2:3], off offset:2048 nt
	s_mov_b32 s5, 0
	s_waitcnt vmcnt(0)
	v_lshlrev_b32_e32 v98, 16, v62
	v_mul_f32_e32 v99, 0x3d372713, v98
	v_mul_f32_e32 v99, v99, v98
	v_fma_f32 v99, v99, v98, v98
	v_mul_f32_e32 v99, 0x3f4c422a, v99
	v_add_f32_e32 v99, v99, v99
	v_mul_f32_e32 v99, 0x3fb8aa3b, v99
	v_exp_f32_e32 v99, v99
	v_mul_f32_e32 v98, 0.5, v98
	v_and_b32_e32 v62, 0xffff0000, v62
	v_add_f32_e32 v99, 1.0, v99
	v_div_scale_f32 v100, s[14:15], v99, v99, 2.0
	v_rcp_f32_e32 v101, v100
	s_nop 0
	v_fma_f32 v115, -v100, v101, 1.0
	v_fmac_f32_e32 v101, v115, v101
	v_div_scale_f32 v115, vcc, 2.0, v99, 2.0
	v_mul_f32_e32 v116, v115, v101
	v_fma_f32 v117, -v100, v116, v115
	v_fmac_f32_e32 v116, v117, v101
	v_fma_f32 v100, -v100, v116, v115
	v_div_fmas_f32 v100, v100, v101, v116
	v_div_fixup_f32 v99, v100, v99, 2.0
	v_sub_f32_e32 v99, 1.0, v99
	v_add_f32_e32 v99, 1.0, v99
	v_mul_f32_e32 v98, v98, v99
	v_mul_f32_e32 v99, 0x3d372713, v62
	v_mul_f32_e32 v99, v99, v62
	v_fma_f32 v99, v99, v62, v62
	v_mul_f32_e32 v99, 0x3f4c422a, v99
	v_add_f32_e32 v99, v99, v99
	v_mul_f32_e32 v99, 0x3fb8aa3b, v99
	v_exp_f32_e32 v99, v99
	v_mul_f32_e32 v62, 0.5, v62
	v_add_f32_e32 v99, 1.0, v99
	v_div_scale_f32 v100, s[14:15], v99, v99, 2.0
	v_rcp_f32_e32 v101, v100
	s_nop 0
	v_fma_f32 v115, -v100, v101, 1.0
	v_fmac_f32_e32 v101, v115, v101
	v_div_scale_f32 v115, vcc, 2.0, v99, 2.0
	v_mul_f32_e32 v116, v115, v101
	v_fma_f32 v117, -v100, v116, v115
	v_fmac_f32_e32 v116, v117, v101
	v_fma_f32 v100, -v100, v116, v115
	v_div_fmas_f32 v100, v100, v101, v116
	v_div_fixup_f32 v99, v100, v99, 2.0
	v_sub_f32_e32 v99, 1.0, v99
	v_add_f32_e32 v99, 1.0, v99
	v_mul_f32_e32 v99, v62, v99
	v_lshlrev_b32_e32 v62, 16, v58
	v_mul_f32_e32 v100, 0x3d372713, v62
	v_mul_f32_e32 v100, v100, v62
	v_fma_f32 v100, v100, v62, v62
	v_mul_f32_e32 v100, 0x3f4c422a, v100
	v_add_f32_e32 v100, v100, v100
	v_mul_f32_e32 v100, 0x3fb8aa3b, v100
	v_exp_f32_e32 v100, v100
	v_mul_f32_e32 v62, 0.5, v62
	v_and_b32_e32 v58, 0xffff0000, v58
	v_cvt_pk_bf16_f32 v98, v98, v99
	v_add_f32_e32 v100, 1.0, v100
	v_div_scale_f32 v101, s[14:15], v100, v100, 2.0
	v_rcp_f32_e32 v115, v101
	s_nop 0
	v_fma_f32 v116, -v101, v115, 1.0
	v_fmac_f32_e32 v115, v116, v115
	v_div_scale_f32 v116, vcc, 2.0, v100, 2.0
	v_mul_f32_e32 v117, v116, v115
	v_fma_f32 v118, -v101, v117, v116
	v_fmac_f32_e32 v117, v118, v115
	v_fma_f32 v101, -v101, v117, v116
	v_div_fmas_f32 v101, v101, v115, v117
	v_div_fixup_f32 v100, v101, v100, 2.0
	v_sub_f32_e32 v100, 1.0, v100
	v_add_f32_e32 v100, 1.0, v100
	v_mul_f32_e32 v100, v62, v100
	v_mul_f32_e32 v62, 0x3d372713, v58
	v_mul_f32_e32 v62, v62, v58
	v_fma_f32 v62, v62, v58, v58
	v_mul_f32_e32 v62, 0x3f4c422a, v62
	v_add_f32_e32 v62, v62, v62
	v_mul_f32_e32 v62, 0x3fb8aa3b, v62
	v_exp_f32_e32 v62, v62
	v_mul_f32_e32 v58, 0.5, v58
	v_add_f32_e32 v62, 1.0, v62
	v_div_scale_f32 v101, s[14:15], v62, v62, 2.0
	v_rcp_f32_e32 v115, v101
	s_nop 0
	v_fma_f32 v116, -v101, v115, 1.0
	v_fmac_f32_e32 v115, v116, v115
	v_div_scale_f32 v116, vcc, 2.0, v62, 2.0
	v_mul_f32_e32 v117, v116, v115
	v_fma_f32 v118, -v101, v117, v116
	v_fmac_f32_e32 v117, v118, v115
	v_fma_f32 v101, -v101, v117, v116
	v_div_fmas_f32 v101, v101, v115, v117
	v_div_fixup_f32 v62, v101, v62, 2.0
	v_sub_f32_e32 v62, 1.0, v62
	v_add_f32_e32 v62, 1.0, v62
	v_mul_f32_e32 v101, v58, v62
	v_lshlrev_b32_e32 v58, 16, v63
	v_mul_f32_e32 v62, 0x3d372713, v58
	v_mul_f32_e32 v62, v62, v58
	v_fma_f32 v62, v62, v58, v58
	v_mul_f32_e32 v62, 0x3f4c422a, v62
	v_add_f32_e32 v62, v62, v62
	v_mul_f32_e32 v62, 0x3fb8aa3b, v62
	v_exp_f32_e32 v62, v62
	v_mul_f32_e32 v58, 0.5, v58
	v_add_f32_e32 v62, 1.0, v62
	v_div_scale_f32 v115, s[14:15], v62, v62, 2.0
	v_rcp_f32_e32 v116, v115
	s_nop 0
	v_fma_f32 v117, -v115, v116, 1.0
	v_fmac_f32_e32 v116, v117, v116
	v_div_scale_f32 v117, vcc, 2.0, v62, 2.0
	v_mul_f32_e32 v118, v117, v116
	v_fma_f32 v119, -v115, v118, v117
	v_fmac_f32_e32 v118, v119, v116
	v_fma_f32 v115, -v115, v118, v117
	v_div_fmas_f32 v115, v115, v116, v118
	v_div_fixup_f32 v62, v115, v62, 2.0
	v_sub_f32_e32 v62, 1.0, v62
	v_add_f32_e32 v62, 1.0, v62
	v_mul_f32_e32 v115, v58, v62
	v_and_b32_e32 v58, 0xffff0000, v63
	v_mul_f32_e32 v62, 0x3d372713, v58
	v_mul_f32_e32 v62, v62, v58
	v_fma_f32 v62, v62, v58, v58
	v_mul_f32_e32 v62, 0x3f4c422a, v62
	v_add_f32_e32 v62, v62, v62
	v_mul_f32_e32 v62, 0x3fb8aa3b, v62
	v_exp_f32_e32 v62, v62
	v_mul_f32_e32 v58, 0.5, v58
	v_add_f32_e32 v62, 1.0, v62
	v_div_scale_f32 v63, s[14:15], v62, v62, 2.0
	v_rcp_f32_e32 v116, v63
	s_nop 0
	v_fma_f32 v117, -v63, v116, 1.0
	v_fmac_f32_e32 v116, v117, v116
	v_div_scale_f32 v117, vcc, 2.0, v62, 2.0
	v_mul_f32_e32 v118, v117, v116
	v_fma_f32 v119, -v63, v118, v117
	v_fmac_f32_e32 v118, v119, v116
	v_fma_f32 v63, -v63, v118, v117
	v_div_fmas_f32 v63, v63, v116, v118
	v_div_fixup_f32 v62, v63, v62, 2.0
	v_sub_f32_e32 v62, 1.0, v62
	v_add_f32_e32 v62, 1.0, v62
	v_mul_f32_e32 v116, v58, v62
	v_lshlrev_b32_e32 v58, 16, v64
	v_mul_f32_e32 v62, 0x3d372713, v58
	v_mul_f32_e32 v62, v62, v58
	v_fma_f32 v62, v62, v58, v58
	v_mul_f32_e32 v62, 0x3f4c422a, v62
	v_add_f32_e32 v62, v62, v62
	v_mul_f32_e32 v62, 0x3fb8aa3b, v62
	v_exp_f32_e32 v62, v62
	v_mul_f32_e32 v58, 0.5, v58
	v_add_f32_e32 v62, 1.0, v62
	v_div_scale_f32 v63, s[14:15], v62, v62, 2.0
	v_rcp_f32_e32 v117, v63
	s_nop 0
	v_fma_f32 v118, -v63, v117, 1.0
	v_fmac_f32_e32 v117, v118, v117
	v_div_scale_f32 v118, vcc, 2.0, v62, 2.0
	v_mul_f32_e32 v119, v118, v117
	v_fma_f32 v120, -v63, v119, v118
	v_fmac_f32_e32 v119, v120, v117
	v_fma_f32 v63, -v63, v119, v118
	v_div_fmas_f32 v63, v63, v117, v119
	v_div_fixup_f32 v62, v63, v62, 2.0
	v_sub_f32_e32 v62, 1.0, v62
	v_add_f32_e32 v62, 1.0, v62
	v_mul_f32_e32 v117, v58, v62
	v_and_b32_e32 v58, 0xffff0000, v64
	v_mul_f32_e32 v62, 0x3d372713, v58
	v_mul_f32_e32 v62, v62, v58
	v_fma_f32 v62, v62, v58, v58
	v_mul_f32_e32 v62, 0x3f4c422a, v62
	v_add_f32_e32 v62, v62, v62
	v_mul_f32_e32 v62, 0x3fb8aa3b, v62
	v_exp_f32_e32 v62, v62
	v_mul_f32_e32 v58, 0.5, v58
	v_add_f32_e32 v62, 1.0, v62
	v_div_scale_f32 v63, s[14:15], v62, v62, 2.0
	v_rcp_f32_e32 v64, v63
	s_nop 0
	v_fma_f32 v118, -v63, v64, 1.0
	v_fmac_f32_e32 v64, v118, v64
	v_div_scale_f32 v118, vcc, 2.0, v62, 2.0
	v_mul_f32_e32 v119, v118, v64
	v_fma_f32 v120, -v63, v119, v118
	v_fmac_f32_e32 v119, v120, v64
	v_fma_f32 v63, -v63, v119, v118
	v_div_fmas_f32 v63, v63, v64, v119
	v_div_fixup_f32 v62, v63, v62, 2.0
	v_sub_f32_e32 v62, 1.0, v62
	v_add_f32_e32 v62, 1.0, v62
	v_mul_f32_e32 v64, v58, v62
	v_lshlrev_b32_e32 v58, 16, v65
	v_mul_f32_e32 v62, 0x3d372713, v58
	v_mul_f32_e32 v62, v62, v58
	v_fma_f32 v62, v62, v58, v58
	v_mul_f32_e32 v62, 0x3f4c422a, v62
	v_add_f32_e32 v62, v62, v62
	v_mul_f32_e32 v62, 0x3fb8aa3b, v62
	v_exp_f32_e32 v62, v62
	v_mul_f32_e32 v58, 0.5, v58
	v_add_f32_e32 v62, 1.0, v62
	v_div_scale_f32 v63, s[14:15], v62, v62, 2.0
	v_rcp_f32_e32 v118, v63
	s_nop 0
	v_fma_f32 v119, -v63, v118, 1.0
	v_fmac_f32_e32 v118, v119, v118
	v_div_scale_f32 v119, vcc, 2.0, v62, 2.0
	v_mul_f32_e32 v120, v119, v118
	v_fma_f32 v121, -v63, v120, v119
	v_fmac_f32_e32 v120, v121, v118
	v_fma_f32 v63, -v63, v120, v119
	v_div_fmas_f32 v63, v63, v118, v120
	v_div_fixup_f32 v62, v63, v62, 2.0
	v_sub_f32_e32 v62, 1.0, v62
	v_add_f32_e32 v62, 1.0, v62
	v_mul_f32_e32 v118, v58, v62
	v_and_b32_e32 v58, 0xffff0000, v65
	v_mul_f32_e32 v62, 0x3d372713, v58
	v_mul_f32_e32 v62, v62, v58
	v_fma_f32 v62, v62, v58, v58
	v_mul_f32_e32 v62, 0x3f4c422a, v62
	v_add_f32_e32 v62, v62, v62
	v_mul_f32_e32 v62, 0x3fb8aa3b, v62
	v_exp_f32_e32 v62, v62
	v_mul_f32_e32 v58, 0.5, v58
	v_add_f32_e32 v62, 1.0, v62
	v_div_scale_f32 v63, s[14:15], v62, v62, 2.0
	v_rcp_f32_e32 v65, v63
	s_nop 0
	v_fma_f32 v119, -v63, v65, 1.0
	v_fmac_f32_e32 v65, v119, v65
	v_div_scale_f32 v119, vcc, 2.0, v62, 2.0
	v_mul_f32_e32 v120, v119, v65
	v_fma_f32 v121, -v63, v120, v119
	v_fmac_f32_e32 v120, v121, v65
	v_fma_f32 v63, -v63, v120, v119
	v_div_fmas_f32 v63, v63, v65, v120
	v_div_fixup_f32 v62, v63, v62, 2.0
	v_sub_f32_e32 v62, 1.0, v62
	v_add_f32_e32 v62, 1.0, v62
	v_mul_f32_e32 v65, v58, v62
	v_and_b32_e32 v58, 0xffff0000, v59
	v_lshlrev_b32_e32 v59, 16, v59
	v_mul_f32_e32 v62, 0x3d372713, v59
	v_mul_f32_e32 v62, v62, v59
	v_mov_b32_e32 v63, v59
	v_fmac_f32_e32 v63, v62, v63
	v_mul_f32_e32 v62, 0x3f4c422a, v63
	v_add_f32_e32 v62, v62, v62
	v_mul_f32_e32 v62, 0x3fb8aa3b, v62
	v_exp_f32_e32 v63, v62
	v_mul_f32_e32 v62, 0x3d372713, v58
	v_mul_f32_e32 v62, v62, v58
	v_mov_b32_e32 v120, v58
	v_fmac_f32_e32 v120, v62, v120
	v_mul_f32_e32 v62, 0x3f4c422a, v120
	v_add_f32_e32 v62, v62, v62
	v_mul_f32_e32 v62, 0x3fb8aa3b, v62
	v_exp_f32_e32 v62, v62
	v_pk_mul_f32 v[58:59], v[58:59], 0.5 op_sel_hi:[1,0]
	v_mul_f32_e32 v119, v101, v101
	v_fmac_f32_e32 v119, v100, v100
	v_pk_add_f32 v[62:63], v[62:63], 1.0 op_sel_hi:[1,0]
	s_nop 0
	v_div_scale_f32 v120, s[14:15], v63, v63, 2.0
	v_rcp_f32_e32 v121, v120
	s_nop 0
	v_fma_f32 v122, -v120, v121, 1.0
	v_fmac_f32_e32 v121, v122, v121
	v_div_scale_f32 v122, vcc, 2.0, v63, 2.0
	v_mul_f32_e32 v123, v122, v121
	v_fma_f32 v124, -v120, v123, v122
	v_fmac_f32_e32 v123, v124, v121
	v_fma_f32 v120, -v120, v123, v122
	v_div_fmas_f32 v120, v120, v121, v123
	v_div_fixup_f32 v63, v120, v63, 2.0
	v_div_scale_f32 v120, s[14:15], v62, v62, 2.0
	v_rcp_f32_e32 v121, v120
	s_nop 0
	v_fma_f32 v122, -v120, v121, 1.0
	v_fmac_f32_e32 v121, v122, v121
	v_div_scale_f32 v122, vcc, 2.0, v62, 2.0
	v_mul_f32_e32 v123, v122, v121
	v_fma_f32 v124, -v120, v123, v122
	v_fmac_f32_e32 v123, v124, v121
	v_fma_f32 v120, -v120, v123, v122
	v_div_fmas_f32 v120, v120, v121, v123
	v_div_fixup_f32 v62, v120, v62, 2.0
	v_pk_add_f32 v[62:63], v[62:63], 1.0 op_sel_hi:[1,0] neg_lo:[1,0] neg_hi:[1,0]
	s_nop 0
	v_pk_add_f32 v[62:63], v[62:63], 1.0 op_sel_hi:[1,0]
	s_nop 0
	v_pk_mul_f32 v[58:59], v[58:59], v[62:63]
	s_nop 0
	v_pk_mul_f32 v[62:63], v[58:59], v[58:59]
	s_nop 0
	v_add_f32_e32 v63, v63, v119
	v_add_f32_e32 v119, v62, v63
	v_lshlrev_b32_e32 v63, 16, v60
	v_and_b32_e32 v62, 0xffff0000, v60
	v_mul_f32_e32 v60, 0x3d372713, v63
	v_mul_f32_e32 v60, v60, v63
	v_mov_b32_e32 v120, v63
	v_fmac_f32_e32 v120, v60, v120
	v_mul_f32_e32 v60, 0x3f4c422a, v120
	v_add_f32_e32 v60, v60, v60
	v_mul_f32_e32 v60, 0x3fb8aa3b, v60
	v_exp_f32_e32 v121, v60
	v_mul_f32_e32 v60, 0x3d372713, v62
	v_mul_f32_e32 v60, v60, v62
	v_mov_b32_e32 v120, v62
	v_fmac_f32_e32 v120, v60, v120
	v_mul_f32_e32 v60, 0x3f4c422a, v120
	v_add_f32_e32 v60, v60, v60
	v_mul_f32_e32 v60, 0x3fb8aa3b, v60
	v_exp_f32_e32 v120, v60
	v_pk_mul_f32 v[62:63], v[62:63], 0.5 op_sel_hi:[1,0]
	v_pk_add_f32 v[120:121], v[120:121], 1.0 op_sel_hi:[1,0]
	s_nop 0
	v_div_scale_f32 v60, s[14:15], v121, v121, 2.0
	v_rcp_f32_e32 v122, v60
	s_nop 0
	v_fma_f32 v123, -v60, v122, 1.0
	v_fmac_f32_e32 v122, v123, v122
	v_div_scale_f32 v123, vcc, 2.0, v121, 2.0
	v_mul_f32_e32 v124, v123, v122
	v_fma_f32 v125, -v60, v124, v123
	v_fmac_f32_e32 v124, v125, v122
	v_fma_f32 v60, -v60, v124, v123
	v_div_fmas_f32 v60, v60, v122, v124
	v_div_fixup_f32 v121, v60, v121, 2.0
	v_div_scale_f32 v60, s[14:15], v120, v120, 2.0
	v_rcp_f32_e32 v122, v60
	s_nop 0
	v_fma_f32 v123, -v60, v122, 1.0
	v_fmac_f32_e32 v122, v123, v122
	v_div_scale_f32 v123, vcc, 2.0, v120, 2.0
	v_mul_f32_e32 v124, v123, v122
	v_fma_f32 v125, -v60, v124, v123
	v_fmac_f32_e32 v124, v125, v122
	v_fma_f32 v60, -v60, v124, v123
	v_div_fmas_f32 v60, v60, v122, v124
	v_div_fixup_f32 v120, v60, v120, 2.0
	v_pk_add_f32 v[120:121], v[120:121], 1.0 op_sel_hi:[1,0] neg_lo:[1,0] neg_hi:[1,0]
	s_nop 0
	v_pk_add_f32 v[120:121], v[120:121], 1.0 op_sel_hi:[1,0]
	s_nop 0
	v_pk_mul_f32 v[62:63], v[62:63], v[120:121]
	s_nop 0
	v_pk_mul_f32 v[120:121], v[62:63], v[62:63]
	s_nop 0
	v_add_f32_e32 v60, v121, v119
	v_add_f32_e32 v119, v120, v60
	v_and_b32_e32 v60, 0xffff0000, v61
	v_lshlrev_b32_e32 v61, 16, v61
	v_mul_f32_e32 v120, 0x3d372713, v61
	v_mul_f32_e32 v120, v120, v61
	v_mov_b32_e32 v121, v61
	v_fmac_f32_e32 v121, v120, v121
	v_mul_f32_e32 v120, 0x3f4c422a, v121
	v_add_f32_e32 v120, v120, v120
	v_mul_f32_e32 v120, 0x3fb8aa3b, v120
	v_exp_f32_e32 v121, v120
	v_mul_f32_e32 v120, 0x3d372713, v60
	v_mul_f32_e32 v120, v120, v60
	v_mov_b32_e32 v122, v60
	v_fmac_f32_e32 v122, v120, v122
	v_mul_f32_e32 v120, 0x3f4c422a, v122
	v_add_f32_e32 v120, v120, v120
	v_mul_f32_e32 v120, 0x3fb8aa3b, v120
	v_exp_f32_e32 v120, v120
	v_pk_mul_f32 v[60:61], v[60:61], 0.5 op_sel_hi:[1,0]
	v_pk_add_f32 v[120:121], v[120:121], 1.0 op_sel_hi:[1,0]
	s_nop 0
	v_div_scale_f32 v122, s[14:15], v121, v121, 2.0
	v_rcp_f32_e32 v123, v122
	s_nop 0
	v_fma_f32 v124, -v122, v123, 1.0
	v_fmac_f32_e32 v123, v124, v123
	v_div_scale_f32 v124, vcc, 2.0, v121, 2.0
	v_mul_f32_e32 v125, v124, v123
	v_fma_f32 v126, -v122, v125, v124
	v_fmac_f32_e32 v125, v126, v123
	v_fma_f32 v122, -v122, v125, v124
	v_div_fmas_f32 v122, v122, v123, v125
	v_div_fixup_f32 v121, v122, v121, 2.0
	v_div_scale_f32 v122, s[14:15], v120, v120, 2.0
	v_rcp_f32_e32 v123, v122
	s_nop 0
	v_fma_f32 v124, -v122, v123, 1.0
	v_fmac_f32_e32 v123, v124, v123
	v_div_scale_f32 v124, vcc, 2.0, v120, 2.0
	v_mul_f32_e32 v125, v124, v123
	v_fma_f32 v126, -v122, v125, v124
	v_fmac_f32_e32 v125, v126, v123
	v_fma_f32 v122, -v122, v125, v124
	v_div_fmas_f32 v122, v122, v123, v125
	v_div_fixup_f32 v120, v122, v120, 2.0
	v_pk_add_f32 v[120:121], v[120:121], 1.0 op_sel_hi:[1,0] neg_lo:[1,0] neg_hi:[1,0]
	s_nop 0
	v_pk_add_f32 v[120:121], v[120:121], 1.0 op_sel_hi:[1,0]
	s_nop 0
	v_pk_mul_f32 v[120:121], v[60:61], v[120:121]
	s_nop 0
	v_pk_mul_f32 v[60:61], v[120:121], v[120:121]
	s_nop 0
	v_add_f32_e32 v61, v61, v119
	v_add_f32_e32 v60, v60, v61
	s_nop 1
	v_mov_b32_dpp v61, v60 quad_perm:[1,0,3,2] row_mask:0xf bank_mask:0xf
	s_waitcnt lgkmcnt(0)
	v_add_f32_e32 v60, v60, v61
	s_nop 1
	v_mov_b32_dpp v61, v60 quad_perm:[2,3,0,1] row_mask:0xf bank_mask:0xf
	s_waitcnt lgkmcnt(0)
	v_add_f32_e32 v60, v60, v61
	s_nop 1
	v_mov_b32_dpp v61, v60 row_half_mirror row_mask:0xf bank_mask:0xf
	s_waitcnt lgkmcnt(0)
	v_add_f32_e32 v60, v60, v61
	s_nop 1
	v_mov_b32_dpp v61, v60 row_mirror row_mask:0xf bank_mask:0xf
	s_waitcnt lgkmcnt(0)
	v_add_f32_e32 v60, v60, v61
	ds_bpermute_b32 v61, v110, v60
	s_waitcnt lgkmcnt(0)
	v_add_f32_e32 v60, v60, v61
	v_fmamk_f32 v60, v60, 0x3b800000, v243
	v_cmp_gt_f32_e32 vcc, s3, v60
	v_mul_f32_e32 v61, 0x4b800000, v60
	s_nop 0
	v_cndmask_b32_e32 v60, v60, v61, vcc
	v_rsq_f32_e32 v60, v60
	s_nop 0
	v_mul_f32_e32 v61, 0x45800000, v60
	v_cndmask_b32_e32 v119, v60, v61, vcc
	v_mul_f32_e32 v60, v100, v119
	v_mul_f32_e32 v61, v101, v119
	v_mul_f32_e32 v58, v58, v119
	v_mul_f32_e32 v60, v70, v60
	v_mul_f32_e32 v61, v71, v61
	v_mul_f32_e32 v59, v59, v119
	v_mul_f32_e32 v58, v73, v58
	v_cvt_pk_bf16_f32 v60, v60, v61
	v_cvt_pk_bf16_f32 v99, v115, v116
	v_mul_f32_e32 v59, v72, v59
	v_cvt_pk_bf16_f32 v61, v59, v58
	v_mul_f32_e32 v58, v63, v119
	v_mul_f32_e32 v58, v66, v58
	v_mul_f32_e32 v59, v62, v119
	v_cvt_pk_bf16_f32 v100, v117, v64
	v_mul_f32_e32 v59, v67, v59
	v_cvt_pk_bf16_f32 v62, v58, v59
	v_mul_f32_e32 v58, v121, v119
	v_mul_f32_e32 v58, v68, v58
	v_mul_f32_e32 v59, v120, v119
	v_cvt_pk_bf16_f32 v101, v118, v65
	v_mul_f32_e32 v59, v69, v59
	v_cvt_pk_bf16_f32 v63, v58, v59
	v_lshlrev_b32_e32 v58, 16, v54
	v_mul_f32_e32 v59, 0x3d372713, v58
	v_mul_f32_e32 v59, v59, v58
	v_fma_f32 v59, v59, v58, v58
	v_mul_f32_e32 v59, 0x3f4c422a, v59
	v_add_f32_e32 v59, v59, v59
	v_mul_f32_e32 v59, 0x3fb8aa3b, v59
	v_exp_f32_e32 v59, v59
	ds_write_b128 v111, v[98:101]
	ds_write_b128 v112, v[60:63]
	v_mul_f32_e32 v58, 0.5, v58
	v_and_b32_e32 v54, 0xffff0000, v54
	v_add_f32_e32 v59, 1.0, v59
	v_div_scale_f32 v60, s[14:15], v59, v59, 2.0
	v_rcp_f32_e32 v61, v60
	s_nop 0
	v_fma_f32 v62, -v60, v61, 1.0
	v_fmac_f32_e32 v61, v62, v61
	v_div_scale_f32 v62, vcc, 2.0, v59, 2.0
	v_mul_f32_e32 v63, v62, v61
	v_fma_f32 v64, -v60, v63, v62
	v_fmac_f32_e32 v63, v64, v61
	v_fma_f32 v60, -v60, v63, v62
	v_div_fmas_f32 v60, v60, v61, v63
	v_div_fixup_f32 v59, v60, v59, 2.0
	v_sub_f32_e32 v59, 1.0, v59
	v_add_f32_e32 v59, 1.0, v59
	v_mul_f32_e32 v58, v58, v59
	v_mul_f32_e32 v59, 0x3d372713, v54
	v_mul_f32_e32 v59, v59, v54
	v_fma_f32 v59, v59, v54, v54
	v_mul_f32_e32 v59, 0x3f4c422a, v59
	v_add_f32_e32 v59, v59, v59
	v_mul_f32_e32 v59, 0x3fb8aa3b, v59
	v_exp_f32_e32 v59, v59
	v_mul_f32_e32 v54, 0.5, v54
	v_add_f32_e32 v59, 1.0, v59
	v_div_scale_f32 v60, s[14:15], v59, v59, 2.0
	v_rcp_f32_e32 v61, v60
	s_nop 0
	v_fma_f32 v62, -v60, v61, 1.0
	v_fmac_f32_e32 v61, v62, v61
	v_div_scale_f32 v62, vcc, 2.0, v59, 2.0
	v_mul_f32_e32 v63, v62, v61
	v_fma_f32 v64, -v60, v63, v62
	v_fmac_f32_e32 v63, v64, v61
	v_fma_f32 v60, -v60, v63, v62
	v_div_fmas_f32 v60, v60, v61, v63
	v_div_fixup_f32 v59, v60, v59, 2.0
	v_sub_f32_e32 v59, 1.0, v59
	v_add_f32_e32 v59, 1.0, v59
	v_mul_f32_e32 v59, v54, v59
	v_lshlrev_b32_e32 v54, 16, v50
	v_mul_f32_e32 v60, 0x3d372713, v54
	v_mul_f32_e32 v60, v60, v54
	v_fma_f32 v60, v60, v54, v54
	v_mul_f32_e32 v60, 0x3f4c422a, v60
	v_add_f32_e32 v60, v60, v60
	v_mul_f32_e32 v60, 0x3fb8aa3b, v60
	v_exp_f32_e32 v60, v60
	v_mul_f32_e32 v54, 0.5, v54
	v_and_b32_e32 v50, 0xffff0000, v50
	v_cvt_pk_bf16_f32 v58, v58, v59
	v_add_f32_e32 v60, 1.0, v60
	v_div_scale_f32 v61, s[14:15], v60, v60, 2.0
	v_rcp_f32_e32 v62, v61
	s_nop 0
	v_fma_f32 v63, -v61, v62, 1.0
	v_fmac_f32_e32 v62, v63, v62
	v_div_scale_f32 v63, vcc, 2.0, v60, 2.0
	v_mul_f32_e32 v64, v63, v62
	v_fma_f32 v65, -v61, v64, v63
	v_fmac_f32_e32 v64, v65, v62
	v_fma_f32 v61, -v61, v64, v63
	v_div_fmas_f32 v61, v61, v62, v64
	v_div_fixup_f32 v60, v61, v60, 2.0
	v_sub_f32_e32 v60, 1.0, v60
	v_add_f32_e32 v60, 1.0, v60
	v_mul_f32_e32 v60, v54, v60
	v_mul_f32_e32 v54, 0x3d372713, v50
	v_mul_f32_e32 v54, v54, v50
	v_fma_f32 v54, v54, v50, v50
	v_mul_f32_e32 v54, 0x3f4c422a, v54
	v_add_f32_e32 v54, v54, v54
	v_mul_f32_e32 v54, 0x3fb8aa3b, v54
	v_exp_f32_e32 v54, v54
	v_mul_f32_e32 v50, 0.5, v50
	v_add_f32_e32 v54, 1.0, v54
	v_div_scale_f32 v61, s[14:15], v54, v54, 2.0
	v_rcp_f32_e32 v62, v61
	s_nop 0
	v_fma_f32 v63, -v61, v62, 1.0
	v_fmac_f32_e32 v62, v63, v62
	v_div_scale_f32 v63, vcc, 2.0, v54, 2.0
	v_mul_f32_e32 v64, v63, v62
	v_fma_f32 v65, -v61, v64, v63
	v_fmac_f32_e32 v64, v65, v62
	v_fma_f32 v61, -v61, v64, v63
	v_div_fmas_f32 v61, v61, v62, v64
	v_div_fixup_f32 v54, v61, v54, 2.0
	v_sub_f32_e32 v54, 1.0, v54
	v_add_f32_e32 v54, 1.0, v54
	v_mul_f32_e32 v61, v50, v54
	v_lshlrev_b32_e32 v50, 16, v55
	v_mul_f32_e32 v54, 0x3d372713, v50
	v_mul_f32_e32 v54, v54, v50
	v_fma_f32 v54, v54, v50, v50
	v_mul_f32_e32 v54, 0x3f4c422a, v54
	v_add_f32_e32 v54, v54, v54
	v_mul_f32_e32 v54, 0x3fb8aa3b, v54
	v_exp_f32_e32 v54, v54
	v_mul_f32_e32 v50, 0.5, v50
	v_add_f32_e32 v54, 1.0, v54
	v_div_scale_f32 v62, s[14:15], v54, v54, 2.0
	v_rcp_f32_e32 v63, v62
	s_nop 0
	v_fma_f32 v64, -v62, v63, 1.0
	v_fmac_f32_e32 v63, v64, v63
	v_div_scale_f32 v64, vcc, 2.0, v54, 2.0
	v_mul_f32_e32 v65, v64, v63
	v_fma_f32 v98, -v62, v65, v64
	v_fmac_f32_e32 v65, v98, v63
	v_fma_f32 v62, -v62, v65, v64
	v_div_fmas_f32 v62, v62, v63, v65
	v_div_fixup_f32 v54, v62, v54, 2.0
	v_sub_f32_e32 v54, 1.0, v54
	v_add_f32_e32 v54, 1.0, v54
	v_mul_f32_e32 v62, v50, v54
	v_and_b32_e32 v50, 0xffff0000, v55
	v_mul_f32_e32 v54, 0x3d372713, v50
	v_mul_f32_e32 v54, v54, v50
	v_fma_f32 v54, v54, v50, v50
	v_mul_f32_e32 v54, 0x3f4c422a, v54
	v_add_f32_e32 v54, v54, v54
	v_mul_f32_e32 v54, 0x3fb8aa3b, v54
	v_exp_f32_e32 v54, v54
	v_mul_f32_e32 v50, 0.5, v50
	v_add_f32_e32 v54, 1.0, v54
	v_div_scale_f32 v55, s[14:15], v54, v54, 2.0
	v_rcp_f32_e32 v63, v55
	s_nop 0
	v_fma_f32 v64, -v55, v63, 1.0
	v_fmac_f32_e32 v63, v64, v63
	v_div_scale_f32 v64, vcc, 2.0, v54, 2.0
	v_mul_f32_e32 v65, v64, v63
	v_fma_f32 v98, -v55, v65, v64
	v_fmac_f32_e32 v65, v98, v63
	v_fma_f32 v55, -v55, v65, v64
	v_div_fmas_f32 v55, v55, v63, v65
	v_div_fixup_f32 v54, v55, v54, 2.0
	v_sub_f32_e32 v54, 1.0, v54
	v_add_f32_e32 v54, 1.0, v54
	v_mul_f32_e32 v63, v50, v54
	v_lshlrev_b32_e32 v50, 16, v56
	v_mul_f32_e32 v54, 0x3d372713, v50
	v_mul_f32_e32 v54, v54, v50
	v_fma_f32 v54, v54, v50, v50
	v_mul_f32_e32 v54, 0x3f4c422a, v54
	v_add_f32_e32 v54, v54, v54
	v_mul_f32_e32 v54, 0x3fb8aa3b, v54
	v_exp_f32_e32 v54, v54
	v_mul_f32_e32 v50, 0.5, v50
	v_add_f32_e32 v54, 1.0, v54
	v_div_scale_f32 v55, s[14:15], v54, v54, 2.0
	v_rcp_f32_e32 v64, v55
	s_nop 0
	v_fma_f32 v65, -v55, v64, 1.0
	v_fmac_f32_e32 v64, v65, v64
	v_div_scale_f32 v65, vcc, 2.0, v54, 2.0
	v_mul_f32_e32 v98, v65, v64
	v_fma_f32 v99, -v55, v98, v65
	v_fmac_f32_e32 v98, v99, v64
	v_fma_f32 v55, -v55, v98, v65
	v_div_fmas_f32 v55, v55, v64, v98
	v_div_fixup_f32 v54, v55, v54, 2.0
	v_sub_f32_e32 v54, 1.0, v54
	v_add_f32_e32 v54, 1.0, v54
	v_mul_f32_e32 v64, v50, v54
	v_and_b32_e32 v50, 0xffff0000, v56
	v_mul_f32_e32 v54, 0x3d372713, v50
	v_mul_f32_e32 v54, v54, v50
	v_fma_f32 v54, v54, v50, v50
	v_mul_f32_e32 v54, 0x3f4c422a, v54
	v_add_f32_e32 v54, v54, v54
	v_mul_f32_e32 v54, 0x3fb8aa3b, v54
	v_exp_f32_e32 v54, v54
	v_mul_f32_e32 v50, 0.5, v50
	v_add_f32_e32 v54, 1.0, v54
	v_div_scale_f32 v55, s[14:15], v54, v54, 2.0
	v_rcp_f32_e32 v56, v55
	s_nop 0
	v_fma_f32 v65, -v55, v56, 1.0
	v_fmac_f32_e32 v56, v65, v56
	v_div_scale_f32 v65, vcc, 2.0, v54, 2.0
	v_mul_f32_e32 v98, v65, v56
	v_fma_f32 v99, -v55, v98, v65
	v_fmac_f32_e32 v98, v99, v56
	v_fma_f32 v55, -v55, v98, v65
	v_div_fmas_f32 v55, v55, v56, v98
	v_div_fixup_f32 v54, v55, v54, 2.0
	v_sub_f32_e32 v54, 1.0, v54
	v_add_f32_e32 v54, 1.0, v54
	v_mul_f32_e32 v56, v50, v54
	v_lshlrev_b32_e32 v50, 16, v57
	v_mul_f32_e32 v54, 0x3d372713, v50
	v_mul_f32_e32 v54, v54, v50
	v_fma_f32 v54, v54, v50, v50
	v_mul_f32_e32 v54, 0x3f4c422a, v54
	v_add_f32_e32 v54, v54, v54
	v_mul_f32_e32 v54, 0x3fb8aa3b, v54
	v_exp_f32_e32 v54, v54
	v_mul_f32_e32 v50, 0.5, v50
	v_add_f32_e32 v54, 1.0, v54
	v_div_scale_f32 v55, s[14:15], v54, v54, 2.0
	v_rcp_f32_e32 v65, v55
	s_nop 0
	v_fma_f32 v98, -v55, v65, 1.0
	v_fmac_f32_e32 v65, v98, v65
	v_div_scale_f32 v98, vcc, 2.0, v54, 2.0
	v_mul_f32_e32 v99, v98, v65
	v_fma_f32 v100, -v55, v99, v98
	v_fmac_f32_e32 v99, v100, v65
	v_fma_f32 v55, -v55, v99, v98
	v_div_fmas_f32 v55, v55, v65, v99
	v_div_fixup_f32 v54, v55, v54, 2.0
	v_sub_f32_e32 v54, 1.0, v54
	v_add_f32_e32 v54, 1.0, v54
	v_mul_f32_e32 v65, v50, v54
	v_and_b32_e32 v50, 0xffff0000, v57
	v_mul_f32_e32 v54, 0x3d372713, v50
	v_mul_f32_e32 v54, v54, v50
	v_fma_f32 v54, v54, v50, v50
	v_mul_f32_e32 v54, 0x3f4c422a, v54
	v_add_f32_e32 v54, v54, v54
	v_mul_f32_e32 v54, 0x3fb8aa3b, v54
	v_exp_f32_e32 v54, v54
	v_mul_f32_e32 v50, 0.5, v50
	v_add_f32_e32 v54, 1.0, v54
	v_div_scale_f32 v55, s[14:15], v54, v54, 2.0
	v_rcp_f32_e32 v57, v55
	s_nop 0
	v_fma_f32 v98, -v55, v57, 1.0
	v_fmac_f32_e32 v57, v98, v57
	v_div_scale_f32 v98, vcc, 2.0, v54, 2.0
	v_mul_f32_e32 v99, v98, v57
	v_fma_f32 v100, -v55, v99, v98
	v_fmac_f32_e32 v99, v100, v57
	v_fma_f32 v55, -v55, v99, v98
	v_div_fmas_f32 v55, v55, v57, v99
	v_div_fixup_f32 v54, v55, v54, 2.0
	v_sub_f32_e32 v54, 1.0, v54
	v_add_f32_e32 v54, 1.0, v54
	v_mul_f32_e32 v57, v50, v54
	v_and_b32_e32 v50, 0xffff0000, v51
	v_lshlrev_b32_e32 v51, 16, v51
	v_mul_f32_e32 v54, 0x3d372713, v51
	v_mul_f32_e32 v54, v54, v51
	v_mov_b32_e32 v55, v51
	v_fmac_f32_e32 v55, v54, v55
	v_mul_f32_e32 v54, 0x3f4c422a, v55
	v_add_f32_e32 v54, v54, v54
	v_mul_f32_e32 v54, 0x3fb8aa3b, v54
	v_exp_f32_e32 v55, v54
	v_mul_f32_e32 v54, 0x3d372713, v50
	v_mul_f32_e32 v54, v54, v50
	v_mov_b32_e32 v99, v50
	v_fmac_f32_e32 v99, v54, v99
	v_mul_f32_e32 v54, 0x3f4c422a, v99
	v_add_f32_e32 v54, v54, v54
	v_mul_f32_e32 v54, 0x3fb8aa3b, v54
	v_exp_f32_e32 v54, v54
	v_pk_mul_f32 v[50:51], v[50:51], 0.5 op_sel_hi:[1,0]
	v_mul_f32_e32 v98, v61, v61
	v_fmac_f32_e32 v98, v60, v60
	v_pk_add_f32 v[54:55], v[54:55], 1.0 op_sel_hi:[1,0]
	s_nop 0
	v_div_scale_f32 v99, s[14:15], v55, v55, 2.0
	v_rcp_f32_e32 v100, v99
	s_nop 0
	v_fma_f32 v101, -v99, v100, 1.0
	v_fmac_f32_e32 v100, v101, v100
	v_div_scale_f32 v101, vcc, 2.0, v55, 2.0
	v_mul_f32_e32 v115, v101, v100
	v_fma_f32 v116, -v99, v115, v101
	v_fmac_f32_e32 v115, v116, v100
	v_fma_f32 v99, -v99, v115, v101
	v_div_fmas_f32 v99, v99, v100, v115
	v_div_fixup_f32 v55, v99, v55, 2.0
	v_div_scale_f32 v99, s[14:15], v54, v54, 2.0
	v_rcp_f32_e32 v100, v99
	s_nop 0
	v_fma_f32 v101, -v99, v100, 1.0
	v_fmac_f32_e32 v100, v101, v100
	v_div_scale_f32 v101, vcc, 2.0, v54, 2.0
	v_mul_f32_e32 v115, v101, v100
	v_fma_f32 v116, -v99, v115, v101
	v_fmac_f32_e32 v115, v116, v100
	v_fma_f32 v99, -v99, v115, v101
	v_div_fmas_f32 v99, v99, v100, v115
	v_div_fixup_f32 v54, v99, v54, 2.0
	v_pk_add_f32 v[54:55], v[54:55], 1.0 op_sel_hi:[1,0] neg_lo:[1,0] neg_hi:[1,0]
	s_nop 0
	v_pk_add_f32 v[54:55], v[54:55], 1.0 op_sel_hi:[1,0]
	s_nop 0
	v_pk_mul_f32 v[50:51], v[50:51], v[54:55]
	s_nop 0
	v_pk_mul_f32 v[54:55], v[50:51], v[50:51]
	s_nop 0
	v_add_f32_e32 v55, v55, v98
	v_add_f32_e32 v100, v54, v55
	v_lshlrev_b32_e32 v55, 16, v52
	v_and_b32_e32 v54, 0xffff0000, v52
	v_mul_f32_e32 v52, 0x3d372713, v55
	v_mul_f32_e32 v52, v52, v55
	v_mov_b32_e32 v98, v55
	v_fmac_f32_e32 v98, v52, v98
	v_mul_f32_e32 v52, 0x3f4c422a, v98
	v_add_f32_e32 v52, v52, v52
	v_mul_f32_e32 v52, 0x3fb8aa3b, v52
	v_exp_f32_e32 v99, v52
	v_mul_f32_e32 v52, 0x3d372713, v54
	v_mul_f32_e32 v52, v52, v54
	v_mov_b32_e32 v98, v54
	v_fmac_f32_e32 v98, v52, v98
	v_mul_f32_e32 v52, 0x3f4c422a, v98
	v_add_f32_e32 v52, v52, v52
	v_mul_f32_e32 v52, 0x3fb8aa3b, v52
	v_exp_f32_e32 v98, v52
	v_pk_mul_f32 v[54:55], v[54:55], 0.5 op_sel_hi:[1,0]
	v_pk_add_f32 v[98:99], v[98:99], 1.0 op_sel_hi:[1,0]
	s_nop 0
	v_div_scale_f32 v52, s[14:15], v99, v99, 2.0
	v_rcp_f32_e32 v101, v52
	s_nop 0
	v_fma_f32 v115, -v52, v101, 1.0
	v_fmac_f32_e32 v101, v115, v101
	v_div_scale_f32 v115, vcc, 2.0, v99, 2.0
	v_mul_f32_e32 v116, v115, v101
	v_fma_f32 v117, -v52, v116, v115
	v_fmac_f32_e32 v116, v117, v101
	v_fma_f32 v52, -v52, v116, v115
	v_div_fmas_f32 v52, v52, v101, v116
	v_div_fixup_f32 v99, v52, v99, 2.0
	v_div_scale_f32 v52, s[14:15], v98, v98, 2.0
	v_rcp_f32_e32 v101, v52
	s_nop 0
	v_fma_f32 v115, -v52, v101, 1.0
	v_fmac_f32_e32 v101, v115, v101
	v_div_scale_f32 v115, vcc, 2.0, v98, 2.0
	v_mul_f32_e32 v116, v115, v101
	v_fma_f32 v117, -v52, v116, v115
	v_fmac_f32_e32 v116, v117, v101
	v_fma_f32 v52, -v52, v116, v115
	v_div_fmas_f32 v52, v52, v101, v116
	v_div_fixup_f32 v98, v52, v98, 2.0
	v_pk_add_f32 v[98:99], v[98:99], 1.0 op_sel_hi:[1,0] neg_lo:[1,0] neg_hi:[1,0]
	s_nop 0
	v_pk_add_f32 v[98:99], v[98:99], 1.0 op_sel_hi:[1,0]
	s_nop 0
	v_pk_mul_f32 v[54:55], v[54:55], v[98:99]
	s_nop 0
	v_pk_mul_f32 v[98:99], v[54:55], v[54:55]
	s_nop 0
	v_add_f32_e32 v52, v99, v100
	v_add_f32_e32 v100, v98, v52
	v_and_b32_e32 v52, 0xffff0000, v53
	v_lshlrev_b32_e32 v53, 16, v53
	v_mul_f32_e32 v98, 0x3d372713, v53
	v_mul_f32_e32 v98, v98, v53
	v_mov_b32_e32 v99, v53
	v_fmac_f32_e32 v99, v98, v99
	v_mul_f32_e32 v98, 0x3f4c422a, v99
	v_add_f32_e32 v98, v98, v98
	v_mul_f32_e32 v98, 0x3fb8aa3b, v98
	v_exp_f32_e32 v99, v98
	v_mul_f32_e32 v98, 0x3d372713, v52
	v_mul_f32_e32 v98, v98, v52
	v_mov_b32_e32 v101, v52
	v_fmac_f32_e32 v101, v98, v101
	v_mul_f32_e32 v98, 0x3f4c422a, v101
	v_add_f32_e32 v98, v98, v98
	v_mul_f32_e32 v98, 0x3fb8aa3b, v98
	v_exp_f32_e32 v98, v98
	v_pk_mul_f32 v[52:53], v[52:53], 0.5 op_sel_hi:[1,0]
	v_pk_add_f32 v[98:99], v[98:99], 1.0 op_sel_hi:[1,0]
	s_nop 0
	v_div_scale_f32 v101, s[14:15], v99, v99, 2.0
	v_rcp_f32_e32 v115, v101
	s_nop 0
	v_fma_f32 v116, -v101, v115, 1.0
	v_fmac_f32_e32 v115, v116, v115
	v_div_scale_f32 v116, vcc, 2.0, v99, 2.0
	v_mul_f32_e32 v117, v116, v115
	v_fma_f32 v118, -v101, v117, v116
	v_fmac_f32_e32 v117, v118, v115
	v_fma_f32 v101, -v101, v117, v116
	v_div_fmas_f32 v101, v101, v115, v117
	v_div_fixup_f32 v99, v101, v99, 2.0
	v_div_scale_f32 v101, s[14:15], v98, v98, 2.0
	v_rcp_f32_e32 v115, v101
	s_nop 0
	v_fma_f32 v116, -v101, v115, 1.0
	v_fmac_f32_e32 v115, v116, v115
	v_div_scale_f32 v116, vcc, 2.0, v98, 2.0
	v_mul_f32_e32 v117, v116, v115
	v_fma_f32 v118, -v101, v117, v116
	v_fmac_f32_e32 v117, v118, v115
	v_fma_f32 v101, -v101, v117, v116
	v_div_fmas_f32 v101, v101, v115, v117
	v_div_fixup_f32 v98, v101, v98, 2.0
	v_pk_add_f32 v[98:99], v[98:99], 1.0 op_sel_hi:[1,0] neg_lo:[1,0] neg_hi:[1,0]
	s_nop 0
	v_pk_add_f32 v[98:99], v[98:99], 1.0 op_sel_hi:[1,0]
	s_nop 0
	v_pk_mul_f32 v[98:99], v[52:53], v[98:99]
	s_nop 0
	v_pk_mul_f32 v[52:53], v[98:99], v[98:99]
	s_nop 0
	v_add_f32_e32 v53, v53, v100
	v_add_f32_e32 v52, v52, v53
	s_nop 1
	v_mov_b32_dpp v53, v52 quad_perm:[1,0,3,2] row_mask:0xf bank_mask:0xf
	s_waitcnt lgkmcnt(0)
	v_add_f32_e32 v52, v52, v53
	s_nop 1
	v_mov_b32_dpp v53, v52 quad_perm:[2,3,0,1] row_mask:0xf bank_mask:0xf
	s_waitcnt lgkmcnt(0)
	v_add_f32_e32 v52, v52, v53
	s_nop 1
	v_mov_b32_dpp v53, v52 row_half_mirror row_mask:0xf bank_mask:0xf
	s_waitcnt lgkmcnt(0)
	v_add_f32_e32 v52, v52, v53
	s_nop 1
	v_mov_b32_dpp v53, v52 row_mirror row_mask:0xf bank_mask:0xf
	s_waitcnt lgkmcnt(0)
	v_add_f32_e32 v52, v52, v53
	ds_bpermute_b32 v53, v110, v52
	s_waitcnt lgkmcnt(0)
	v_add_f32_e32 v52, v52, v53
	v_fmamk_f32 v52, v52, 0x3b800000, v243
	v_cmp_gt_f32_e32 vcc, s3, v52
	v_mul_f32_e32 v53, 0x4b800000, v52
	s_nop 0
	v_cndmask_b32_e32 v52, v52, v53, vcc
	v_rsq_f32_e32 v52, v52
	s_nop 0
	v_mul_f32_e32 v53, 0x45800000, v52
	v_cndmask_b32_e32 v100, v52, v53, vcc
	v_mul_f32_e32 v52, v60, v100
	v_mul_f32_e32 v53, v61, v100
	v_mul_f32_e32 v50, v50, v100
	v_mul_f32_e32 v52, v70, v52
	v_mul_f32_e32 v53, v71, v53
	v_mul_f32_e32 v51, v51, v100
	v_mul_f32_e32 v50, v73, v50
	v_cvt_pk_bf16_f32 v52, v52, v53
	v_cvt_pk_bf16_f32 v59, v62, v63
	v_mul_f32_e32 v51, v72, v51
	v_cvt_pk_bf16_f32 v53, v51, v50
	v_mul_f32_e32 v50, v55, v100
	v_mul_f32_e32 v50, v66, v50
	v_mul_f32_e32 v51, v54, v100
	v_cvt_pk_bf16_f32 v60, v64, v56
	v_mul_f32_e32 v51, v67, v51
	v_cvt_pk_bf16_f32 v54, v50, v51
	v_mul_f32_e32 v50, v99, v100
	v_mul_f32_e32 v50, v68, v50
	v_mul_f32_e32 v51, v98, v100
	v_cvt_pk_bf16_f32 v61, v65, v57
	v_mul_f32_e32 v51, v69, v51
	v_cvt_pk_bf16_f32 v55, v50, v51
	v_lshlrev_b32_e32 v50, 16, v46
	v_mul_f32_e32 v51, 0x3d372713, v50
	v_mul_f32_e32 v51, v51, v50
	v_fma_f32 v51, v51, v50, v50
	v_mul_f32_e32 v51, 0x3f4c422a, v51
	v_add_f32_e32 v51, v51, v51
	v_mul_f32_e32 v51, 0x3fb8aa3b, v51
	v_exp_f32_e32 v51, v51
	ds_write_b128 v111, v[58:61] offset:8704
	ds_write_b128 v112, v[52:55] offset:8704
	v_mul_f32_e32 v50, 0.5, v50
	v_and_b32_e32 v46, 0xffff0000, v46
	v_add_f32_e32 v51, 1.0, v51
	v_div_scale_f32 v52, s[14:15], v51, v51, 2.0
	v_rcp_f32_e32 v53, v52
	v_mov_b64_e32 v[98:99], v[80:81]
	v_mov_b64_e32 v[100:101], v[78:79]
	v_fma_f32 v54, -v52, v53, 1.0
	v_fmac_f32_e32 v53, v54, v53
	v_div_scale_f32 v54, vcc, 2.0, v51, 2.0
	v_mul_f32_e32 v55, v54, v53
	v_fma_f32 v56, -v52, v55, v54
	v_fmac_f32_e32 v55, v56, v53
	v_fma_f32 v52, -v52, v55, v54
	v_div_fmas_f32 v52, v52, v53, v55
	v_div_fixup_f32 v51, v52, v51, 2.0
	v_sub_f32_e32 v51, 1.0, v51
	v_add_f32_e32 v51, 1.0, v51
	v_mul_f32_e32 v50, v50, v51
	v_mul_f32_e32 v51, 0x3d372713, v46
	v_mul_f32_e32 v51, v51, v46
	v_fma_f32 v51, v51, v46, v46
	v_mul_f32_e32 v51, 0x3f4c422a, v51
	v_add_f32_e32 v51, v51, v51
	v_mul_f32_e32 v51, 0x3fb8aa3b, v51
	v_exp_f32_e32 v51, v51
	v_mul_f32_e32 v46, 0.5, v46
	v_add_f32_e32 v51, 1.0, v51
	v_div_scale_f32 v52, s[14:15], v51, v51, 2.0
	v_rcp_f32_e32 v53, v52
	s_nop 0
	v_fma_f32 v54, -v52, v53, 1.0
	v_fmac_f32_e32 v53, v54, v53
	v_div_scale_f32 v54, vcc, 2.0, v51, 2.0
	v_mul_f32_e32 v55, v54, v53
	v_fma_f32 v56, -v52, v55, v54
	v_fmac_f32_e32 v55, v56, v53
	v_fma_f32 v52, -v52, v55, v54
	v_div_fmas_f32 v52, v52, v53, v55
	v_div_fixup_f32 v51, v52, v51, 2.0
	v_sub_f32_e32 v51, 1.0, v51
	v_add_f32_e32 v51, 1.0, v51
	v_mul_f32_e32 v51, v46, v51
	v_lshlrev_b32_e32 v46, 16, v42
	v_mul_f32_e32 v52, 0x3d372713, v46
	v_mul_f32_e32 v52, v52, v46
	v_fma_f32 v52, v52, v46, v46
	v_mul_f32_e32 v52, 0x3f4c422a, v52
	v_add_f32_e32 v52, v52, v52
	v_mul_f32_e32 v52, 0x3fb8aa3b, v52
	v_exp_f32_e32 v52, v52
	v_mul_f32_e32 v46, 0.5, v46
	v_and_b32_e32 v42, 0xffff0000, v42
	v_cvt_pk_bf16_f32 v50, v50, v51
	v_add_f32_e32 v52, 1.0, v52
	v_div_scale_f32 v53, s[14:15], v52, v52, 2.0
	v_rcp_f32_e32 v54, v53
	s_nop 0
	v_fma_f32 v55, -v53, v54, 1.0
	v_fmac_f32_e32 v54, v55, v54
	v_div_scale_f32 v55, vcc, 2.0, v52, 2.0
	v_mul_f32_e32 v56, v55, v54
	v_fma_f32 v57, -v53, v56, v55
	v_fmac_f32_e32 v56, v57, v54
	v_fma_f32 v53, -v53, v56, v55
	v_div_fmas_f32 v53, v53, v54, v56
	v_div_fixup_f32 v52, v53, v52, 2.0
	v_sub_f32_e32 v52, 1.0, v52
	v_add_f32_e32 v52, 1.0, v52
	v_mul_f32_e32 v52, v46, v52
	v_mul_f32_e32 v46, 0x3d372713, v42
	v_mul_f32_e32 v46, v46, v42
	v_fma_f32 v46, v46, v42, v42
	v_mul_f32_e32 v46, 0x3f4c422a, v46
	v_add_f32_e32 v46, v46, v46
	v_mul_f32_e32 v46, 0x3fb8aa3b, v46
	v_exp_f32_e32 v46, v46
	v_mul_f32_e32 v42, 0.5, v42
	v_add_f32_e32 v46, 1.0, v46
	v_div_scale_f32 v53, s[14:15], v46, v46, 2.0
	v_rcp_f32_e32 v54, v53
	s_nop 0
	v_fma_f32 v55, -v53, v54, 1.0
	v_fmac_f32_e32 v54, v55, v54
	v_div_scale_f32 v55, vcc, 2.0, v46, 2.0
	v_mul_f32_e32 v56, v55, v54
	v_fma_f32 v57, -v53, v56, v55
	v_fmac_f32_e32 v56, v57, v54
	v_fma_f32 v53, -v53, v56, v55
	v_div_fmas_f32 v53, v53, v54, v56
	v_div_fixup_f32 v46, v53, v46, 2.0
	v_sub_f32_e32 v46, 1.0, v46
	v_add_f32_e32 v46, 1.0, v46
	v_mul_f32_e32 v53, v42, v46
	v_lshlrev_b32_e32 v42, 16, v47
	v_mul_f32_e32 v46, 0x3d372713, v42
	v_mul_f32_e32 v46, v46, v42
	v_fma_f32 v46, v46, v42, v42
	v_mul_f32_e32 v46, 0x3f4c422a, v46
	v_add_f32_e32 v46, v46, v46
	v_mul_f32_e32 v46, 0x3fb8aa3b, v46
	v_exp_f32_e32 v46, v46
	v_mul_f32_e32 v42, 0.5, v42
	v_add_f32_e32 v46, 1.0, v46
	v_div_scale_f32 v54, s[14:15], v46, v46, 2.0
	v_rcp_f32_e32 v55, v54
	s_nop 0
	v_fma_f32 v56, -v54, v55, 1.0
	v_fmac_f32_e32 v55, v56, v55
	v_div_scale_f32 v56, vcc, 2.0, v46, 2.0
	v_mul_f32_e32 v57, v56, v55
	v_fma_f32 v58, -v54, v57, v56
	v_fmac_f32_e32 v57, v58, v55
	v_fma_f32 v54, -v54, v57, v56
	v_div_fmas_f32 v54, v54, v55, v57
	v_div_fixup_f32 v46, v54, v46, 2.0
	v_sub_f32_e32 v46, 1.0, v46
	v_add_f32_e32 v46, 1.0, v46
	v_mul_f32_e32 v54, v42, v46
	v_and_b32_e32 v42, 0xffff0000, v47
	v_mul_f32_e32 v46, 0x3d372713, v42
	v_mul_f32_e32 v46, v46, v42
	v_fma_f32 v46, v46, v42, v42
	v_mul_f32_e32 v46, 0x3f4c422a, v46
	v_add_f32_e32 v46, v46, v46
	v_mul_f32_e32 v46, 0x3fb8aa3b, v46
	v_exp_f32_e32 v46, v46
	v_mul_f32_e32 v42, 0.5, v42
	v_add_f32_e32 v46, 1.0, v46
	v_div_scale_f32 v47, s[14:15], v46, v46, 2.0
	v_rcp_f32_e32 v55, v47
	s_nop 0
	v_fma_f32 v56, -v47, v55, 1.0
	v_fmac_f32_e32 v55, v56, v55
	v_div_scale_f32 v56, vcc, 2.0, v46, 2.0
	v_mul_f32_e32 v57, v56, v55
	v_fma_f32 v58, -v47, v57, v56
	v_fmac_f32_e32 v57, v58, v55
	v_fma_f32 v47, -v47, v57, v56
	v_div_fmas_f32 v47, v47, v55, v57
	v_div_fixup_f32 v46, v47, v46, 2.0
	v_sub_f32_e32 v46, 1.0, v46
	v_add_f32_e32 v46, 1.0, v46
	v_mul_f32_e32 v55, v42, v46
	v_lshlrev_b32_e32 v42, 16, v48
	v_mul_f32_e32 v46, 0x3d372713, v42
	v_mul_f32_e32 v46, v46, v42
	v_fma_f32 v46, v46, v42, v42
	v_mul_f32_e32 v46, 0x3f4c422a, v46
	v_add_f32_e32 v46, v46, v46
	v_mul_f32_e32 v46, 0x3fb8aa3b, v46
	v_exp_f32_e32 v46, v46
	v_mul_f32_e32 v42, 0.5, v42
	v_add_f32_e32 v46, 1.0, v46
	v_div_scale_f32 v47, s[14:15], v46, v46, 2.0
	v_rcp_f32_e32 v56, v47
	s_nop 0
	v_fma_f32 v57, -v47, v56, 1.0
	v_fmac_f32_e32 v56, v57, v56
	v_div_scale_f32 v57, vcc, 2.0, v46, 2.0
	v_mul_f32_e32 v58, v57, v56
	v_fma_f32 v59, -v47, v58, v57
	v_fmac_f32_e32 v58, v59, v56
	v_fma_f32 v47, -v47, v58, v57
	v_div_fmas_f32 v47, v47, v56, v58
	v_div_fixup_f32 v46, v47, v46, 2.0
	v_sub_f32_e32 v46, 1.0, v46
	v_add_f32_e32 v46, 1.0, v46
	v_mul_f32_e32 v56, v42, v46
	v_and_b32_e32 v42, 0xffff0000, v48
	v_mul_f32_e32 v46, 0x3d372713, v42
	v_mul_f32_e32 v46, v46, v42
	v_fma_f32 v46, v46, v42, v42
	v_mul_f32_e32 v46, 0x3f4c422a, v46
	v_add_f32_e32 v46, v46, v46
	v_mul_f32_e32 v46, 0x3fb8aa3b, v46
	v_exp_f32_e32 v46, v46
	v_mul_f32_e32 v42, 0.5, v42
	v_add_f32_e32 v46, 1.0, v46
	v_div_scale_f32 v47, s[14:15], v46, v46, 2.0
	v_rcp_f32_e32 v48, v47
	s_nop 0
	v_fma_f32 v57, -v47, v48, 1.0
	v_fmac_f32_e32 v48, v57, v48
	v_div_scale_f32 v57, vcc, 2.0, v46, 2.0
	v_mul_f32_e32 v58, v57, v48
	v_fma_f32 v59, -v47, v58, v57
	v_fmac_f32_e32 v58, v59, v48
	v_fma_f32 v47, -v47, v58, v57
	v_div_fmas_f32 v47, v47, v48, v58
	v_div_fixup_f32 v46, v47, v46, 2.0
	v_sub_f32_e32 v46, 1.0, v46
	v_add_f32_e32 v46, 1.0, v46
	v_mul_f32_e32 v48, v42, v46
	v_lshlrev_b32_e32 v42, 16, v49
	v_mul_f32_e32 v46, 0x3d372713, v42
	v_mul_f32_e32 v46, v46, v42
	v_fma_f32 v46, v46, v42, v42
	v_mul_f32_e32 v46, 0x3f4c422a, v46
	v_add_f32_e32 v46, v46, v46
	v_mul_f32_e32 v46, 0x3fb8aa3b, v46
	v_exp_f32_e32 v46, v46
	v_mul_f32_e32 v42, 0.5, v42
	v_add_f32_e32 v46, 1.0, v46
	v_div_scale_f32 v47, s[14:15], v46, v46, 2.0
	v_rcp_f32_e32 v57, v47
	s_nop 0
	v_fma_f32 v58, -v47, v57, 1.0
	v_fmac_f32_e32 v57, v58, v57
	v_div_scale_f32 v58, vcc, 2.0, v46, 2.0
	v_mul_f32_e32 v59, v58, v57
	v_fma_f32 v60, -v47, v59, v58
	v_fmac_f32_e32 v59, v60, v57
	v_fma_f32 v47, -v47, v59, v58
	v_div_fmas_f32 v47, v47, v57, v59
	v_div_fixup_f32 v46, v47, v46, 2.0
	v_sub_f32_e32 v46, 1.0, v46
	v_add_f32_e32 v46, 1.0, v46
	v_mul_f32_e32 v57, v42, v46
	v_and_b32_e32 v42, 0xffff0000, v49
	v_mul_f32_e32 v46, 0x3d372713, v42
	v_mul_f32_e32 v46, v46, v42
	v_fma_f32 v46, v46, v42, v42
	v_mul_f32_e32 v46, 0x3f4c422a, v46
	v_add_f32_e32 v46, v46, v46
	v_mul_f32_e32 v46, 0x3fb8aa3b, v46
	v_exp_f32_e32 v46, v46
	v_mul_f32_e32 v42, 0.5, v42
	v_add_f32_e32 v46, 1.0, v46
	v_div_scale_f32 v47, s[14:15], v46, v46, 2.0
	v_rcp_f32_e32 v49, v47
	s_nop 0
	v_fma_f32 v58, -v47, v49, 1.0
	v_fmac_f32_e32 v49, v58, v49
	v_div_scale_f32 v58, vcc, 2.0, v46, 2.0
	v_mul_f32_e32 v59, v58, v49
	v_fma_f32 v60, -v47, v59, v58
	v_fmac_f32_e32 v59, v60, v49
	v_fma_f32 v47, -v47, v59, v58
	v_div_fmas_f32 v47, v47, v49, v59
	v_div_fixup_f32 v46, v47, v46, 2.0
	v_sub_f32_e32 v46, 1.0, v46
	v_add_f32_e32 v46, 1.0, v46
	v_mul_f32_e32 v49, v42, v46
	v_and_b32_e32 v42, 0xffff0000, v43
	v_lshlrev_b32_e32 v43, 16, v43
	v_mul_f32_e32 v46, 0x3d372713, v43
	v_mul_f32_e32 v46, v46, v43
	v_mov_b32_e32 v47, v43
	v_fmac_f32_e32 v47, v46, v47
	v_mul_f32_e32 v46, 0x3f4c422a, v47
	v_add_f32_e32 v46, v46, v46
	v_mul_f32_e32 v46, 0x3fb8aa3b, v46
	v_exp_f32_e32 v47, v46
	v_mul_f32_e32 v46, 0x3d372713, v42
	v_mul_f32_e32 v46, v46, v42
	v_mov_b32_e32 v59, v42
	v_fmac_f32_e32 v59, v46, v59
	v_mul_f32_e32 v46, 0x3f4c422a, v59
	v_add_f32_e32 v46, v46, v46
	v_mul_f32_e32 v46, 0x3fb8aa3b, v46
	v_exp_f32_e32 v46, v46
	v_pk_mul_f32 v[42:43], v[42:43], 0.5 op_sel_hi:[1,0]
	v_mul_f32_e32 v58, v53, v53
	v_fmac_f32_e32 v58, v52, v52
	v_pk_add_f32 v[46:47], v[46:47], 1.0 op_sel_hi:[1,0]
	s_nop 0
	v_div_scale_f32 v59, s[14:15], v47, v47, 2.0
	v_rcp_f32_e32 v60, v59
	s_nop 0
	v_fma_f32 v61, -v59, v60, 1.0
	v_fmac_f32_e32 v60, v61, v60
	v_div_scale_f32 v61, vcc, 2.0, v47, 2.0
	v_mul_f32_e32 v62, v61, v60
	v_fma_f32 v63, -v59, v62, v61
	v_fmac_f32_e32 v62, v63, v60
	v_fma_f32 v59, -v59, v62, v61
	v_div_fmas_f32 v59, v59, v60, v62
	v_div_fixup_f32 v47, v59, v47, 2.0
	v_div_scale_f32 v59, s[14:15], v46, v46, 2.0
	v_rcp_f32_e32 v60, v59
	s_nop 0
	v_fma_f32 v61, -v59, v60, 1.0
	v_fmac_f32_e32 v60, v61, v60
	v_div_scale_f32 v61, vcc, 2.0, v46, 2.0
	v_mul_f32_e32 v62, v61, v60
	v_fma_f32 v63, -v59, v62, v61
	v_fmac_f32_e32 v62, v63, v60
	v_fma_f32 v59, -v59, v62, v61
	v_div_fmas_f32 v59, v59, v60, v62
	v_div_fixup_f32 v46, v59, v46, 2.0
	v_pk_add_f32 v[46:47], v[46:47], 1.0 op_sel_hi:[1,0] neg_lo:[1,0] neg_hi:[1,0]
	s_nop 0
	v_pk_add_f32 v[46:47], v[46:47], 1.0 op_sel_hi:[1,0]
	s_nop 0
	v_pk_mul_f32 v[42:43], v[42:43], v[46:47]
	s_nop 0
	v_pk_mul_f32 v[46:47], v[42:43], v[42:43]
	s_nop 0
	v_add_f32_e32 v47, v47, v58
	v_add_f32_e32 v60, v46, v47
	v_lshlrev_b32_e32 v47, 16, v44
	v_and_b32_e32 v46, 0xffff0000, v44
	v_mul_f32_e32 v44, 0x3d372713, v47
	v_mul_f32_e32 v44, v44, v47
	v_mov_b32_e32 v58, v47
	v_fmac_f32_e32 v58, v44, v58
	v_mul_f32_e32 v44, 0x3f4c422a, v58
	v_add_f32_e32 v44, v44, v44
	v_mul_f32_e32 v44, 0x3fb8aa3b, v44
	v_exp_f32_e32 v59, v44
	v_mul_f32_e32 v44, 0x3d372713, v46
	v_mul_f32_e32 v44, v44, v46
	v_mov_b32_e32 v58, v46
	v_fmac_f32_e32 v58, v44, v58
	v_mul_f32_e32 v44, 0x3f4c422a, v58
	v_add_f32_e32 v44, v44, v44
	v_mul_f32_e32 v44, 0x3fb8aa3b, v44
	v_exp_f32_e32 v58, v44
	v_pk_mul_f32 v[46:47], v[46:47], 0.5 op_sel_hi:[1,0]
	v_pk_add_f32 v[58:59], v[58:59], 1.0 op_sel_hi:[1,0]
	s_nop 0
	v_div_scale_f32 v44, s[14:15], v59, v59, 2.0
	v_rcp_f32_e32 v61, v44
	s_nop 0
	v_fma_f32 v62, -v44, v61, 1.0
	v_fmac_f32_e32 v61, v62, v61
	v_div_scale_f32 v62, vcc, 2.0, v59, 2.0
	v_mul_f32_e32 v63, v62, v61
	v_fma_f32 v64, -v44, v63, v62
	v_fmac_f32_e32 v63, v64, v61
	v_fma_f32 v44, -v44, v63, v62
	v_div_fmas_f32 v44, v44, v61, v63
	v_div_fixup_f32 v59, v44, v59, 2.0
	v_div_scale_f32 v44, s[14:15], v58, v58, 2.0
	v_rcp_f32_e32 v61, v44
	s_nop 0
	v_fma_f32 v62, -v44, v61, 1.0
	v_fmac_f32_e32 v61, v62, v61
	v_div_scale_f32 v62, vcc, 2.0, v58, 2.0
	v_mul_f32_e32 v63, v62, v61
	v_fma_f32 v64, -v44, v63, v62
	v_fmac_f32_e32 v63, v64, v61
	v_fma_f32 v44, -v44, v63, v62
	v_div_fmas_f32 v44, v44, v61, v63
	v_div_fixup_f32 v58, v44, v58, 2.0
	v_pk_add_f32 v[58:59], v[58:59], 1.0 op_sel_hi:[1,0] neg_lo:[1,0] neg_hi:[1,0]
	s_nop 0
	v_pk_add_f32 v[58:59], v[58:59], 1.0 op_sel_hi:[1,0]
	s_nop 0
	v_pk_mul_f32 v[46:47], v[46:47], v[58:59]
	s_nop 0
	v_pk_mul_f32 v[58:59], v[46:47], v[46:47]
	s_nop 0
	v_add_f32_e32 v44, v59, v60
	v_add_f32_e32 v60, v58, v44
	v_and_b32_e32 v44, 0xffff0000, v45
	v_lshlrev_b32_e32 v45, 16, v45
	v_mul_f32_e32 v58, 0x3d372713, v45
	v_mul_f32_e32 v58, v58, v45
	v_mov_b32_e32 v59, v45
	v_fmac_f32_e32 v59, v58, v59
	v_mul_f32_e32 v58, 0x3f4c422a, v59
	v_add_f32_e32 v58, v58, v58
	v_mul_f32_e32 v58, 0x3fb8aa3b, v58
	v_exp_f32_e32 v59, v58
	v_mul_f32_e32 v58, 0x3d372713, v44
	v_mul_f32_e32 v58, v58, v44
	v_mov_b32_e32 v61, v44
	v_fmac_f32_e32 v61, v58, v61
	v_mul_f32_e32 v58, 0x3f4c422a, v61
	v_add_f32_e32 v58, v58, v58
	v_mul_f32_e32 v58, 0x3fb8aa3b, v58
	v_exp_f32_e32 v58, v58
	v_pk_mul_f32 v[44:45], v[44:45], 0.5 op_sel_hi:[1,0]
	v_pk_add_f32 v[58:59], v[58:59], 1.0 op_sel_hi:[1,0]
	s_nop 0
	v_div_scale_f32 v61, s[14:15], v59, v59, 2.0
	v_rcp_f32_e32 v62, v61
	s_nop 0
	v_fma_f32 v63, -v61, v62, 1.0
	v_fmac_f32_e32 v62, v63, v62
	v_div_scale_f32 v63, vcc, 2.0, v59, 2.0
	v_mul_f32_e32 v64, v63, v62
	v_fma_f32 v65, -v61, v64, v63
	v_fmac_f32_e32 v64, v65, v62
	v_fma_f32 v61, -v61, v64, v63
	v_div_fmas_f32 v61, v61, v62, v64
	v_div_fixup_f32 v59, v61, v59, 2.0
	v_div_scale_f32 v61, s[14:15], v58, v58, 2.0
	v_rcp_f32_e32 v62, v61
	s_nop 0
	v_fma_f32 v63, -v61, v62, 1.0
	v_fmac_f32_e32 v62, v63, v62
	v_div_scale_f32 v63, vcc, 2.0, v58, 2.0
	v_mul_f32_e32 v64, v63, v62
	v_fma_f32 v65, -v61, v64, v63
	v_fmac_f32_e32 v64, v65, v62
	v_fma_f32 v61, -v61, v64, v63
	v_div_fmas_f32 v61, v61, v62, v64
	v_div_fixup_f32 v58, v61, v58, 2.0
	v_pk_add_f32 v[58:59], v[58:59], 1.0 op_sel_hi:[1,0] neg_lo:[1,0] neg_hi:[1,0]
	s_nop 0
	v_pk_add_f32 v[58:59], v[58:59], 1.0 op_sel_hi:[1,0]
	s_nop 0
	v_pk_mul_f32 v[58:59], v[44:45], v[58:59]
	s_nop 0
	v_pk_mul_f32 v[44:45], v[58:59], v[58:59]
	s_nop 0
	v_add_f32_e32 v45, v45, v60
	v_add_f32_e32 v44, v44, v45
	s_nop 1
	v_mov_b32_dpp v45, v44 quad_perm:[1,0,3,2] row_mask:0xf bank_mask:0xf
	s_waitcnt lgkmcnt(0)
	v_add_f32_e32 v44, v44, v45
	s_nop 1
	v_mov_b32_dpp v45, v44 quad_perm:[2,3,0,1] row_mask:0xf bank_mask:0xf
	s_waitcnt lgkmcnt(0)
	v_add_f32_e32 v44, v44, v45
	s_nop 1
	v_mov_b32_dpp v45, v44 row_half_mirror row_mask:0xf bank_mask:0xf
	s_waitcnt lgkmcnt(0)
	v_add_f32_e32 v44, v44, v45
	s_nop 1
	v_mov_b32_dpp v45, v44 row_mirror row_mask:0xf bank_mask:0xf
	s_waitcnt lgkmcnt(0)
	v_add_f32_e32 v44, v44, v45
	ds_bpermute_b32 v45, v110, v44
	s_waitcnt lgkmcnt(0)
	v_add_f32_e32 v44, v44, v45
	v_fmamk_f32 v44, v44, 0x3b800000, v243
	v_cmp_gt_f32_e32 vcc, s3, v44
	v_mul_f32_e32 v45, 0x4b800000, v44
	s_nop 0
	v_cndmask_b32_e32 v44, v44, v45, vcc
	v_rsq_f32_e32 v44, v44
	s_nop 0
	v_mul_f32_e32 v45, 0x45800000, v44
	v_cndmask_b32_e32 v60, v44, v45, vcc
	v_mul_f32_e32 v44, v52, v60
	v_mul_f32_e32 v45, v53, v60
	v_mul_f32_e32 v42, v42, v60
	v_mul_f32_e32 v44, v70, v44
	v_mul_f32_e32 v45, v71, v45
	v_mul_f32_e32 v43, v43, v60
	v_mul_f32_e32 v42, v73, v42
	v_cvt_pk_bf16_f32 v44, v44, v45
	v_cvt_pk_bf16_f32 v51, v54, v55
	v_mul_f32_e32 v43, v72, v43
	v_cvt_pk_bf16_f32 v45, v43, v42
	v_mul_f32_e32 v42, v47, v60
	v_mul_f32_e32 v42, v66, v42
	v_mul_f32_e32 v43, v46, v60
	v_cvt_pk_bf16_f32 v52, v56, v48
	v_mul_f32_e32 v43, v67, v43
	v_cvt_pk_bf16_f32 v46, v42, v43
	v_mul_f32_e32 v42, v59, v60
	v_mul_f32_e32 v42, v68, v42
	v_mul_f32_e32 v43, v58, v60
	v_cvt_pk_bf16_f32 v53, v57, v49
	v_mul_f32_e32 v43, v69, v43
	v_cvt_pk_bf16_f32 v47, v42, v43
	v_lshlrev_b32_e32 v42, 16, v38
	v_mul_f32_e32 v43, 0x3d372713, v42
	v_mul_f32_e32 v43, v43, v42
	v_fma_f32 v43, v43, v42, v42
	v_mul_f32_e32 v43, 0x3f4c422a, v43
	v_add_f32_e32 v43, v43, v43
	v_mul_f32_e32 v43, 0x3fb8aa3b, v43
	v_exp_f32_e32 v43, v43
	ds_write_b128 v111, v[50:53] offset:17408
	ds_write_b128 v112, v[44:47] offset:17408
	v_mul_f32_e32 v42, 0.5, v42
	v_and_b32_e32 v38, 0xffff0000, v38
	v_add_f32_e32 v43, 1.0, v43
	v_div_scale_f32 v44, s[14:15], v43, v43, 2.0
	v_rcp_f32_e32 v45, v44
	s_nop 0
	v_fma_f32 v46, -v44, v45, 1.0
	v_fmac_f32_e32 v45, v46, v45
	v_div_scale_f32 v46, vcc, 2.0, v43, 2.0
	v_mul_f32_e32 v47, v46, v45
	v_fma_f32 v48, -v44, v47, v46
	v_fmac_f32_e32 v47, v48, v45
	v_fma_f32 v44, -v44, v47, v46
	v_div_fmas_f32 v44, v44, v45, v47
	v_div_fixup_f32 v43, v44, v43, 2.0
	v_sub_f32_e32 v43, 1.0, v43
	v_add_f32_e32 v43, 1.0, v43
	v_mul_f32_e32 v42, v42, v43
	v_mul_f32_e32 v43, 0x3d372713, v38
	v_mul_f32_e32 v43, v43, v38
	v_fma_f32 v43, v43, v38, v38
	v_mul_f32_e32 v43, 0x3f4c422a, v43
	v_add_f32_e32 v43, v43, v43
	v_mul_f32_e32 v43, 0x3fb8aa3b, v43
	v_exp_f32_e32 v43, v43
	v_mul_f32_e32 v38, 0.5, v38
	v_add_f32_e32 v43, 1.0, v43
	v_div_scale_f32 v44, s[14:15], v43, v43, 2.0
	v_rcp_f32_e32 v45, v44
	s_nop 0
	v_fma_f32 v46, -v44, v45, 1.0
	v_fmac_f32_e32 v45, v46, v45
	v_div_scale_f32 v46, vcc, 2.0, v43, 2.0
	v_mul_f32_e32 v47, v46, v45
	v_fma_f32 v48, -v44, v47, v46
	v_fmac_f32_e32 v47, v48, v45
	v_fma_f32 v44, -v44, v47, v46
	v_div_fmas_f32 v44, v44, v45, v47
	v_div_fixup_f32 v43, v44, v43, 2.0
	v_sub_f32_e32 v43, 1.0, v43
	v_add_f32_e32 v43, 1.0, v43
	v_mul_f32_e32 v43, v38, v43
	v_lshlrev_b32_e32 v38, 16, v34
	v_mul_f32_e32 v44, 0x3d372713, v38
	v_mul_f32_e32 v44, v44, v38
	v_fma_f32 v44, v44, v38, v38
	v_mul_f32_e32 v44, 0x3f4c422a, v44
	v_add_f32_e32 v44, v44, v44
	v_mul_f32_e32 v44, 0x3fb8aa3b, v44
	v_exp_f32_e32 v44, v44
	v_mul_f32_e32 v38, 0.5, v38
	v_and_b32_e32 v34, 0xffff0000, v34
	v_cvt_pk_bf16_f32 v42, v42, v43
	v_add_f32_e32 v44, 1.0, v44
	v_div_scale_f32 v45, s[14:15], v44, v44, 2.0
	v_rcp_f32_e32 v46, v45
	s_nop 0
	v_fma_f32 v47, -v45, v46, 1.0
	v_fmac_f32_e32 v46, v47, v46
	v_div_scale_f32 v47, vcc, 2.0, v44, 2.0
	v_mul_f32_e32 v48, v47, v46
	v_fma_f32 v49, -v45, v48, v47
	v_fmac_f32_e32 v48, v49, v46
	v_fma_f32 v45, -v45, v48, v47
	v_div_fmas_f32 v45, v45, v46, v48
	v_div_fixup_f32 v44, v45, v44, 2.0
	v_sub_f32_e32 v44, 1.0, v44
	v_add_f32_e32 v44, 1.0, v44
	v_mul_f32_e32 v44, v38, v44
	v_mul_f32_e32 v38, 0x3d372713, v34
	v_mul_f32_e32 v38, v38, v34
	v_fma_f32 v38, v38, v34, v34
	v_mul_f32_e32 v38, 0x3f4c422a, v38
	v_add_f32_e32 v38, v38, v38
	v_mul_f32_e32 v38, 0x3fb8aa3b, v38
	v_exp_f32_e32 v38, v38
	v_mul_f32_e32 v34, 0.5, v34
	v_add_f32_e32 v38, 1.0, v38
	v_div_scale_f32 v45, s[14:15], v38, v38, 2.0
	v_rcp_f32_e32 v46, v45
	s_nop 0
	v_fma_f32 v47, -v45, v46, 1.0
	v_fmac_f32_e32 v46, v47, v46
	v_div_scale_f32 v47, vcc, 2.0, v38, 2.0
	v_mul_f32_e32 v48, v47, v46
	v_fma_f32 v49, -v45, v48, v47
	v_fmac_f32_e32 v48, v49, v46
	v_fma_f32 v45, -v45, v48, v47
	v_div_fmas_f32 v45, v45, v46, v48
	v_div_fixup_f32 v38, v45, v38, 2.0
	v_sub_f32_e32 v38, 1.0, v38
	v_add_f32_e32 v38, 1.0, v38
	v_mul_f32_e32 v45, v34, v38
	v_lshlrev_b32_e32 v34, 16, v39
	v_mul_f32_e32 v38, 0x3d372713, v34
	v_mul_f32_e32 v38, v38, v34
	v_fma_f32 v38, v38, v34, v34
	v_mul_f32_e32 v38, 0x3f4c422a, v38
	v_add_f32_e32 v38, v38, v38
	v_mul_f32_e32 v38, 0x3fb8aa3b, v38
	v_exp_f32_e32 v38, v38
	v_mul_f32_e32 v34, 0.5, v34
	v_add_f32_e32 v38, 1.0, v38
	v_div_scale_f32 v46, s[14:15], v38, v38, 2.0
	v_rcp_f32_e32 v47, v46
	s_nop 0
	v_fma_f32 v48, -v46, v47, 1.0
	v_fmac_f32_e32 v47, v48, v47
	v_div_scale_f32 v48, vcc, 2.0, v38, 2.0
	v_mul_f32_e32 v49, v48, v47
	v_fma_f32 v50, -v46, v49, v48
	v_fmac_f32_e32 v49, v50, v47
	v_fma_f32 v46, -v46, v49, v48
	v_div_fmas_f32 v46, v46, v47, v49
	v_div_fixup_f32 v38, v46, v38, 2.0
	v_sub_f32_e32 v38, 1.0, v38
	v_add_f32_e32 v38, 1.0, v38
	v_mul_f32_e32 v46, v34, v38
	v_and_b32_e32 v34, 0xffff0000, v39
	v_mul_f32_e32 v38, 0x3d372713, v34
	v_mul_f32_e32 v38, v38, v34
	v_fma_f32 v38, v38, v34, v34
	v_mul_f32_e32 v38, 0x3f4c422a, v38
	v_add_f32_e32 v38, v38, v38
	v_mul_f32_e32 v38, 0x3fb8aa3b, v38
	v_exp_f32_e32 v38, v38
	v_mul_f32_e32 v34, 0.5, v34
	v_add_f32_e32 v38, 1.0, v38
	v_div_scale_f32 v39, s[14:15], v38, v38, 2.0
	v_rcp_f32_e32 v47, v39
	s_nop 0
	v_fma_f32 v48, -v39, v47, 1.0
	v_fmac_f32_e32 v47, v48, v47
	v_div_scale_f32 v48, vcc, 2.0, v38, 2.0
	v_mul_f32_e32 v49, v48, v47
	v_fma_f32 v50, -v39, v49, v48
	v_fmac_f32_e32 v49, v50, v47
	v_fma_f32 v39, -v39, v49, v48
	v_div_fmas_f32 v39, v39, v47, v49
	v_div_fixup_f32 v38, v39, v38, 2.0
	v_sub_f32_e32 v38, 1.0, v38
	v_add_f32_e32 v38, 1.0, v38
	v_mul_f32_e32 v47, v34, v38
	v_lshlrev_b32_e32 v34, 16, v40
	v_mul_f32_e32 v38, 0x3d372713, v34
	v_mul_f32_e32 v38, v38, v34
	v_fma_f32 v38, v38, v34, v34
	v_mul_f32_e32 v38, 0x3f4c422a, v38
	v_add_f32_e32 v38, v38, v38
	v_mul_f32_e32 v38, 0x3fb8aa3b, v38
	v_exp_f32_e32 v38, v38
	v_mul_f32_e32 v34, 0.5, v34
	v_add_f32_e32 v38, 1.0, v38
	v_div_scale_f32 v39, s[14:15], v38, v38, 2.0
	v_rcp_f32_e32 v48, v39
	s_nop 0
	v_fma_f32 v49, -v39, v48, 1.0
	v_fmac_f32_e32 v48, v49, v48
	v_div_scale_f32 v49, vcc, 2.0, v38, 2.0
	v_mul_f32_e32 v50, v49, v48
	v_fma_f32 v51, -v39, v50, v49
	v_fmac_f32_e32 v50, v51, v48
	v_fma_f32 v39, -v39, v50, v49
	v_div_fmas_f32 v39, v39, v48, v50
	v_div_fixup_f32 v38, v39, v38, 2.0
	v_sub_f32_e32 v38, 1.0, v38
	v_add_f32_e32 v38, 1.0, v38
	v_mul_f32_e32 v48, v34, v38
	v_and_b32_e32 v34, 0xffff0000, v40
	v_mul_f32_e32 v38, 0x3d372713, v34
	v_mul_f32_e32 v38, v38, v34
	v_fma_f32 v38, v38, v34, v34
	v_mul_f32_e32 v38, 0x3f4c422a, v38
	v_add_f32_e32 v38, v38, v38
	v_mul_f32_e32 v38, 0x3fb8aa3b, v38
	v_exp_f32_e32 v38, v38
	v_mul_f32_e32 v34, 0.5, v34
	v_add_f32_e32 v38, 1.0, v38
	v_div_scale_f32 v39, s[14:15], v38, v38, 2.0
	v_rcp_f32_e32 v40, v39
	s_nop 0
	v_fma_f32 v49, -v39, v40, 1.0
	v_fmac_f32_e32 v40, v49, v40
	v_div_scale_f32 v49, vcc, 2.0, v38, 2.0
	v_mul_f32_e32 v50, v49, v40
	v_fma_f32 v51, -v39, v50, v49
	v_fmac_f32_e32 v50, v51, v40
	v_fma_f32 v39, -v39, v50, v49
	v_div_fmas_f32 v39, v39, v40, v50
	v_div_fixup_f32 v38, v39, v38, 2.0
	v_sub_f32_e32 v38, 1.0, v38
	v_add_f32_e32 v38, 1.0, v38
	v_mul_f32_e32 v40, v34, v38
	v_lshlrev_b32_e32 v34, 16, v41
	v_mul_f32_e32 v38, 0x3d372713, v34
	v_mul_f32_e32 v38, v38, v34
	v_fma_f32 v38, v38, v34, v34
	v_mul_f32_e32 v38, 0x3f4c422a, v38
	v_add_f32_e32 v38, v38, v38
	v_mul_f32_e32 v38, 0x3fb8aa3b, v38
	v_exp_f32_e32 v38, v38
	v_mul_f32_e32 v34, 0.5, v34
	v_add_f32_e32 v38, 1.0, v38
	v_div_scale_f32 v39, s[14:15], v38, v38, 2.0
	v_rcp_f32_e32 v49, v39
	s_nop 0
	v_fma_f32 v50, -v39, v49, 1.0
	v_fmac_f32_e32 v49, v50, v49
	v_div_scale_f32 v50, vcc, 2.0, v38, 2.0
	v_mul_f32_e32 v51, v50, v49
	v_fma_f32 v52, -v39, v51, v50
	v_fmac_f32_e32 v51, v52, v49
	v_fma_f32 v39, -v39, v51, v50
	v_div_fmas_f32 v39, v39, v49, v51
	v_div_fixup_f32 v38, v39, v38, 2.0
	v_sub_f32_e32 v38, 1.0, v38
	v_add_f32_e32 v38, 1.0, v38
	v_mul_f32_e32 v49, v34, v38
	v_and_b32_e32 v34, 0xffff0000, v41
	v_mul_f32_e32 v38, 0x3d372713, v34
	v_mul_f32_e32 v38, v38, v34
	v_fma_f32 v38, v38, v34, v34
	v_mul_f32_e32 v38, 0x3f4c422a, v38
	v_add_f32_e32 v38, v38, v38
	v_mul_f32_e32 v38, 0x3fb8aa3b, v38
	v_exp_f32_e32 v38, v38
	v_mul_f32_e32 v34, 0.5, v34
	v_add_f32_e32 v38, 1.0, v38
	v_div_scale_f32 v39, s[14:15], v38, v38, 2.0
	v_rcp_f32_e32 v41, v39
	s_nop 0
	v_fma_f32 v50, -v39, v41, 1.0
	v_fmac_f32_e32 v41, v50, v41
	v_div_scale_f32 v50, vcc, 2.0, v38, 2.0
	v_mul_f32_e32 v51, v50, v41
	v_fma_f32 v52, -v39, v51, v50
	v_fmac_f32_e32 v51, v52, v41
	v_fma_f32 v39, -v39, v51, v50
	v_div_fmas_f32 v39, v39, v41, v51
	v_div_fixup_f32 v38, v39, v38, 2.0
	v_sub_f32_e32 v38, 1.0, v38
	v_add_f32_e32 v38, 1.0, v38
	v_mul_f32_e32 v41, v34, v38
	v_and_b32_e32 v34, 0xffff0000, v35
	v_lshlrev_b32_e32 v35, 16, v35
	v_mul_f32_e32 v38, 0x3d372713, v35
	v_mul_f32_e32 v38, v38, v35
	v_mov_b32_e32 v39, v35
	v_fmac_f32_e32 v39, v38, v39
	v_mul_f32_e32 v38, 0x3f4c422a, v39
	v_add_f32_e32 v38, v38, v38
	v_mul_f32_e32 v38, 0x3fb8aa3b, v38
	v_exp_f32_e32 v39, v38
	v_mul_f32_e32 v38, 0x3d372713, v34
	v_mul_f32_e32 v38, v38, v34
	v_mov_b32_e32 v51, v34
	v_fmac_f32_e32 v51, v38, v51
	v_mul_f32_e32 v38, 0x3f4c422a, v51
	v_add_f32_e32 v38, v38, v38
	v_mul_f32_e32 v38, 0x3fb8aa3b, v38
	v_exp_f32_e32 v38, v38
	v_pk_mul_f32 v[34:35], v[34:35], 0.5 op_sel_hi:[1,0]
	v_mul_f32_e32 v50, v45, v45
	v_fmac_f32_e32 v50, v44, v44
	v_pk_add_f32 v[38:39], v[38:39], 1.0 op_sel_hi:[1,0]
	s_nop 0
	v_div_scale_f32 v51, s[14:15], v39, v39, 2.0
	v_rcp_f32_e32 v52, v51
	s_nop 0
	v_fma_f32 v53, -v51, v52, 1.0
	v_fmac_f32_e32 v52, v53, v52
	v_div_scale_f32 v53, vcc, 2.0, v39, 2.0
	v_mul_f32_e32 v54, v53, v52
	v_fma_f32 v55, -v51, v54, v53
	v_fmac_f32_e32 v54, v55, v52
	v_fma_f32 v51, -v51, v54, v53
	v_div_fmas_f32 v51, v51, v52, v54
	v_div_fixup_f32 v39, v51, v39, 2.0
	v_div_scale_f32 v51, s[14:15], v38, v38, 2.0
	v_rcp_f32_e32 v52, v51
	s_nop 0
	v_fma_f32 v53, -v51, v52, 1.0
	v_fmac_f32_e32 v52, v53, v52
	v_div_scale_f32 v53, vcc, 2.0, v38, 2.0
	v_mul_f32_e32 v54, v53, v52
	v_fma_f32 v55, -v51, v54, v53
	v_fmac_f32_e32 v54, v55, v52
	v_fma_f32 v51, -v51, v54, v53
	v_div_fmas_f32 v51, v51, v52, v54
	v_div_fixup_f32 v38, v51, v38, 2.0
	v_pk_add_f32 v[38:39], v[38:39], 1.0 op_sel_hi:[1,0] neg_lo:[1,0] neg_hi:[1,0]
	s_nop 0
	v_pk_add_f32 v[38:39], v[38:39], 1.0 op_sel_hi:[1,0]
	s_nop 0
	v_pk_mul_f32 v[34:35], v[34:35], v[38:39]
	s_nop 0
	v_pk_mul_f32 v[38:39], v[34:35], v[34:35]
	s_nop 0
	v_add_f32_e32 v39, v39, v50
	v_add_f32_e32 v52, v38, v39
	v_lshlrev_b32_e32 v39, 16, v36
	v_and_b32_e32 v38, 0xffff0000, v36
	v_mul_f32_e32 v36, 0x3d372713, v39
	v_mul_f32_e32 v36, v36, v39
	v_mov_b32_e32 v50, v39
	v_fmac_f32_e32 v50, v36, v50
	v_mul_f32_e32 v36, 0x3f4c422a, v50
	v_add_f32_e32 v36, v36, v36
	v_mul_f32_e32 v36, 0x3fb8aa3b, v36
	v_exp_f32_e32 v51, v36
	v_mul_f32_e32 v36, 0x3d372713, v38
	v_mul_f32_e32 v36, v36, v38
	v_mov_b32_e32 v50, v38
	v_fmac_f32_e32 v50, v36, v50
	v_mul_f32_e32 v36, 0x3f4c422a, v50
	v_add_f32_e32 v36, v36, v36
	v_mul_f32_e32 v36, 0x3fb8aa3b, v36
	v_exp_f32_e32 v50, v36
	v_pk_mul_f32 v[38:39], v[38:39], 0.5 op_sel_hi:[1,0]
	v_pk_add_f32 v[50:51], v[50:51], 1.0 op_sel_hi:[1,0]
	s_nop 0
	v_div_scale_f32 v36, s[14:15], v51, v51, 2.0
	v_rcp_f32_e32 v53, v36
	s_nop 0
	v_fma_f32 v54, -v36, v53, 1.0
	v_fmac_f32_e32 v53, v54, v53
	v_div_scale_f32 v54, vcc, 2.0, v51, 2.0
	v_mul_f32_e32 v55, v54, v53
	v_fma_f32 v56, -v36, v55, v54
	v_fmac_f32_e32 v55, v56, v53
	v_fma_f32 v36, -v36, v55, v54
	v_div_fmas_f32 v36, v36, v53, v55
	v_div_fixup_f32 v51, v36, v51, 2.0
	v_div_scale_f32 v36, s[14:15], v50, v50, 2.0
	v_rcp_f32_e32 v53, v36
	s_nop 0
	v_fma_f32 v54, -v36, v53, 1.0
	v_fmac_f32_e32 v53, v54, v53
	v_div_scale_f32 v54, vcc, 2.0, v50, 2.0
	v_mul_f32_e32 v55, v54, v53
	v_fma_f32 v56, -v36, v55, v54
	v_fmac_f32_e32 v55, v56, v53
	v_fma_f32 v36, -v36, v55, v54
	v_div_fmas_f32 v36, v36, v53, v55
	v_div_fixup_f32 v50, v36, v50, 2.0
	v_pk_add_f32 v[50:51], v[50:51], 1.0 op_sel_hi:[1,0] neg_lo:[1,0] neg_hi:[1,0]
	s_nop 0
	v_pk_add_f32 v[50:51], v[50:51], 1.0 op_sel_hi:[1,0]
	s_nop 0
	v_pk_mul_f32 v[38:39], v[38:39], v[50:51]
	s_nop 0
	v_pk_mul_f32 v[50:51], v[38:39], v[38:39]
	s_nop 0
	v_add_f32_e32 v36, v51, v52
	v_add_f32_e32 v52, v50, v36
	v_and_b32_e32 v36, 0xffff0000, v37
	v_lshlrev_b32_e32 v37, 16, v37
	v_mul_f32_e32 v50, 0x3d372713, v37
	v_mul_f32_e32 v50, v50, v37
	v_mov_b32_e32 v51, v37
	v_fmac_f32_e32 v51, v50, v51
	v_mul_f32_e32 v50, 0x3f4c422a, v51
	v_add_f32_e32 v50, v50, v50
	v_mul_f32_e32 v50, 0x3fb8aa3b, v50
	v_exp_f32_e32 v51, v50
	v_mul_f32_e32 v50, 0x3d372713, v36
	v_mul_f32_e32 v50, v50, v36
	v_mov_b32_e32 v53, v36
	v_fmac_f32_e32 v53, v50, v53
	v_mul_f32_e32 v50, 0x3f4c422a, v53
	v_add_f32_e32 v50, v50, v50
	v_mul_f32_e32 v50, 0x3fb8aa3b, v50
	v_exp_f32_e32 v50, v50
	v_pk_mul_f32 v[36:37], v[36:37], 0.5 op_sel_hi:[1,0]
	v_pk_add_f32 v[50:51], v[50:51], 1.0 op_sel_hi:[1,0]
	s_nop 0
	v_div_scale_f32 v53, s[14:15], v51, v51, 2.0
	v_rcp_f32_e32 v54, v53
	s_nop 0
	v_fma_f32 v55, -v53, v54, 1.0
	v_fmac_f32_e32 v54, v55, v54
	v_div_scale_f32 v55, vcc, 2.0, v51, 2.0
	v_mul_f32_e32 v56, v55, v54
	v_fma_f32 v57, -v53, v56, v55
	v_fmac_f32_e32 v56, v57, v54
	v_fma_f32 v53, -v53, v56, v55
	v_div_fmas_f32 v53, v53, v54, v56
	v_div_fixup_f32 v51, v53, v51, 2.0
	v_div_scale_f32 v53, s[14:15], v50, v50, 2.0
	v_rcp_f32_e32 v54, v53
	s_nop 0
	v_fma_f32 v55, -v53, v54, 1.0
	v_fmac_f32_e32 v54, v55, v54
	v_div_scale_f32 v55, vcc, 2.0, v50, 2.0
	v_mul_f32_e32 v56, v55, v54
	v_fma_f32 v57, -v53, v56, v55
	v_fmac_f32_e32 v56, v57, v54
	v_fma_f32 v53, -v53, v56, v55
	v_div_fmas_f32 v53, v53, v54, v56
	v_div_fixup_f32 v50, v53, v50, 2.0
	v_pk_add_f32 v[50:51], v[50:51], 1.0 op_sel_hi:[1,0] neg_lo:[1,0] neg_hi:[1,0]
	s_nop 0
	v_pk_add_f32 v[50:51], v[50:51], 1.0 op_sel_hi:[1,0]
	s_nop 0
	v_pk_mul_f32 v[50:51], v[36:37], v[50:51]
	s_nop 0
	v_pk_mul_f32 v[36:37], v[50:51], v[50:51]
	s_nop 0
	v_add_f32_e32 v37, v37, v52
	v_add_f32_e32 v36, v36, v37
	s_nop 1
	v_mov_b32_dpp v37, v36 quad_perm:[1,0,3,2] row_mask:0xf bank_mask:0xf
	s_waitcnt lgkmcnt(0)
	v_add_f32_e32 v36, v36, v37
	s_nop 1
	v_mov_b32_dpp v37, v36 quad_perm:[2,3,0,1] row_mask:0xf bank_mask:0xf
	s_waitcnt lgkmcnt(0)
	v_add_f32_e32 v36, v36, v37
	s_nop 1
	v_mov_b32_dpp v37, v36 row_half_mirror row_mask:0xf bank_mask:0xf
	s_waitcnt lgkmcnt(0)
	v_add_f32_e32 v36, v36, v37
	s_nop 1
	v_mov_b32_dpp v37, v36 row_mirror row_mask:0xf bank_mask:0xf
	s_waitcnt lgkmcnt(0)
	v_add_f32_e32 v36, v36, v37
	ds_bpermute_b32 v37, v110, v36
	s_waitcnt lgkmcnt(0)
	v_add_f32_e32 v36, v36, v37
	v_fmamk_f32 v36, v36, 0x3b800000, v243
	v_cmp_gt_f32_e32 vcc, s3, v36
	v_mul_f32_e32 v37, 0x4b800000, v36
	s_nop 0
	v_cndmask_b32_e32 v36, v36, v37, vcc
	v_rsq_f32_e32 v36, v36
	s_nop 0
	v_mul_f32_e32 v37, 0x45800000, v36
	v_cndmask_b32_e32 v52, v36, v37, vcc
	v_mul_f32_e32 v36, v44, v52
	v_mul_f32_e32 v37, v45, v52
	v_mul_f32_e32 v34, v34, v52
	v_mul_f32_e32 v36, v70, v36
	v_mul_f32_e32 v37, v71, v37
	v_mul_f32_e32 v35, v35, v52
	v_mul_f32_e32 v34, v73, v34
	v_cvt_pk_bf16_f32 v36, v36, v37
	v_cvt_pk_bf16_f32 v43, v46, v47
	v_mul_f32_e32 v35, v72, v35
	v_cvt_pk_bf16_f32 v37, v35, v34
	v_mul_f32_e32 v34, v39, v52
	v_mul_f32_e32 v34, v66, v34
	v_mul_f32_e32 v35, v38, v52
	v_cvt_pk_bf16_f32 v44, v48, v40
	v_mul_f32_e32 v35, v67, v35
	v_cvt_pk_bf16_f32 v38, v34, v35
	v_mul_f32_e32 v34, v51, v52
	v_mul_f32_e32 v34, v68, v34
	v_mul_f32_e32 v35, v50, v52
	v_cvt_pk_bf16_f32 v45, v49, v41
	v_mul_f32_e32 v35, v69, v35
	v_cvt_pk_bf16_f32 v39, v34, v35
	v_lshlrev_b32_e32 v34, 16, v30
	v_mul_f32_e32 v35, 0x3d372713, v34
	v_mul_f32_e32 v35, v35, v34
	v_fma_f32 v35, v35, v34, v34
	v_mul_f32_e32 v35, 0x3f4c422a, v35
	v_add_f32_e32 v35, v35, v35
	v_mul_f32_e32 v35, 0x3fb8aa3b, v35
	v_exp_f32_e32 v35, v35
	ds_write_b128 v111, v[42:45] offset:26112
	ds_write_b128 v112, v[36:39] offset:26112
	v_mul_f32_e32 v34, 0.5, v34
	v_and_b32_e32 v30, 0xffff0000, v30
	v_add_f32_e32 v35, 1.0, v35
	v_div_scale_f32 v36, s[14:15], v35, v35, 2.0
	v_rcp_f32_e32 v37, v36
	s_nop 0
	v_fma_f32 v38, -v36, v37, 1.0
	v_fmac_f32_e32 v37, v38, v37
	v_div_scale_f32 v38, vcc, 2.0, v35, 2.0
	v_mul_f32_e32 v39, v38, v37
	v_fma_f32 v40, -v36, v39, v38
	v_fmac_f32_e32 v39, v40, v37
	v_fma_f32 v36, -v36, v39, v38
	v_div_fmas_f32 v36, v36, v37, v39
	v_div_fixup_f32 v35, v36, v35, 2.0
	v_sub_f32_e32 v35, 1.0, v35
	v_add_f32_e32 v35, 1.0, v35
	v_mul_f32_e32 v34, v34, v35
	v_mul_f32_e32 v35, 0x3d372713, v30
	v_mul_f32_e32 v35, v35, v30
	v_fma_f32 v35, v35, v30, v30
	v_mul_f32_e32 v35, 0x3f4c422a, v35
	v_add_f32_e32 v35, v35, v35
	v_mul_f32_e32 v35, 0x3fb8aa3b, v35
	v_exp_f32_e32 v35, v35
	v_mul_f32_e32 v30, 0.5, v30
	v_add_f32_e32 v35, 1.0, v35
	v_div_scale_f32 v36, s[14:15], v35, v35, 2.0
	v_rcp_f32_e32 v37, v36
	s_nop 0
	v_fma_f32 v38, -v36, v37, 1.0
	v_fmac_f32_e32 v37, v38, v37
	v_div_scale_f32 v38, vcc, 2.0, v35, 2.0
	v_mul_f32_e32 v39, v38, v37
	v_fma_f32 v40, -v36, v39, v38
	v_fmac_f32_e32 v39, v40, v37
	v_fma_f32 v36, -v36, v39, v38
	v_div_fmas_f32 v36, v36, v37, v39
	v_div_fixup_f32 v35, v36, v35, 2.0
	v_sub_f32_e32 v35, 1.0, v35
	v_add_f32_e32 v35, 1.0, v35
	v_mul_f32_e32 v35, v30, v35
	v_lshlrev_b32_e32 v30, 16, v26
	v_mul_f32_e32 v36, 0x3d372713, v30
	v_mul_f32_e32 v36, v36, v30
	v_fma_f32 v36, v36, v30, v30
	v_mul_f32_e32 v36, 0x3f4c422a, v36
	v_add_f32_e32 v36, v36, v36
	v_mul_f32_e32 v36, 0x3fb8aa3b, v36
	v_exp_f32_e32 v36, v36
	v_mul_f32_e32 v30, 0.5, v30
	v_and_b32_e32 v26, 0xffff0000, v26
	v_cvt_pk_bf16_f32 v34, v34, v35
	v_add_f32_e32 v36, 1.0, v36
	v_div_scale_f32 v37, s[14:15], v36, v36, 2.0
	v_rcp_f32_e32 v38, v37
	s_nop 0
	v_fma_f32 v39, -v37, v38, 1.0
	v_fmac_f32_e32 v38, v39, v38
	v_div_scale_f32 v39, vcc, 2.0, v36, 2.0
	v_mul_f32_e32 v40, v39, v38
	v_fma_f32 v41, -v37, v40, v39
	v_fmac_f32_e32 v40, v41, v38
	v_fma_f32 v37, -v37, v40, v39
	v_div_fmas_f32 v37, v37, v38, v40
	v_div_fixup_f32 v36, v37, v36, 2.0
	v_sub_f32_e32 v36, 1.0, v36
	v_add_f32_e32 v36, 1.0, v36
	v_mul_f32_e32 v36, v30, v36
	v_mul_f32_e32 v30, 0x3d372713, v26
	v_mul_f32_e32 v30, v30, v26
	v_fma_f32 v30, v30, v26, v26
	v_mul_f32_e32 v30, 0x3f4c422a, v30
	v_add_f32_e32 v30, v30, v30
	v_mul_f32_e32 v30, 0x3fb8aa3b, v30
	v_exp_f32_e32 v30, v30
	v_mul_f32_e32 v26, 0.5, v26
	v_add_f32_e32 v30, 1.0, v30
	v_div_scale_f32 v37, s[14:15], v30, v30, 2.0
	v_rcp_f32_e32 v38, v37
	s_nop 0
	v_fma_f32 v39, -v37, v38, 1.0
	v_fmac_f32_e32 v38, v39, v38
	v_div_scale_f32 v39, vcc, 2.0, v30, 2.0
	v_mul_f32_e32 v40, v39, v38
	v_fma_f32 v41, -v37, v40, v39
	v_fmac_f32_e32 v40, v41, v38
	v_fma_f32 v37, -v37, v40, v39
	v_div_fmas_f32 v37, v37, v38, v40
	v_div_fixup_f32 v30, v37, v30, 2.0
	v_sub_f32_e32 v30, 1.0, v30
	v_add_f32_e32 v30, 1.0, v30
	v_mul_f32_e32 v37, v26, v30
	v_lshlrev_b32_e32 v26, 16, v31
	v_mul_f32_e32 v30, 0x3d372713, v26
	v_mul_f32_e32 v30, v30, v26
	v_fma_f32 v30, v30, v26, v26
	v_mul_f32_e32 v30, 0x3f4c422a, v30
	v_add_f32_e32 v30, v30, v30
	v_mul_f32_e32 v30, 0x3fb8aa3b, v30
	v_exp_f32_e32 v30, v30
	v_mul_f32_e32 v26, 0.5, v26
	v_add_f32_e32 v30, 1.0, v30
	v_div_scale_f32 v38, s[14:15], v30, v30, 2.0
	v_rcp_f32_e32 v39, v38
	s_nop 0
	v_fma_f32 v40, -v38, v39, 1.0
	v_fmac_f32_e32 v39, v40, v39
	v_div_scale_f32 v40, vcc, 2.0, v30, 2.0
	v_mul_f32_e32 v41, v40, v39
	v_fma_f32 v42, -v38, v41, v40
	v_fmac_f32_e32 v41, v42, v39
	v_fma_f32 v38, -v38, v41, v40
	v_div_fmas_f32 v38, v38, v39, v41
	v_div_fixup_f32 v30, v38, v30, 2.0
	v_sub_f32_e32 v30, 1.0, v30
	v_add_f32_e32 v30, 1.0, v30
	v_mul_f32_e32 v38, v26, v30
	v_and_b32_e32 v26, 0xffff0000, v31
	v_mul_f32_e32 v30, 0x3d372713, v26
	v_mul_f32_e32 v30, v30, v26
	v_fma_f32 v30, v30, v26, v26
	v_mul_f32_e32 v30, 0x3f4c422a, v30
	v_add_f32_e32 v30, v30, v30
	v_mul_f32_e32 v30, 0x3fb8aa3b, v30
	v_exp_f32_e32 v30, v30
	v_mul_f32_e32 v26, 0.5, v26
	v_add_f32_e32 v30, 1.0, v30
	v_div_scale_f32 v31, s[14:15], v30, v30, 2.0
	v_rcp_f32_e32 v39, v31
	s_nop 0
	v_fma_f32 v40, -v31, v39, 1.0
	v_fmac_f32_e32 v39, v40, v39
	v_div_scale_f32 v40, vcc, 2.0, v30, 2.0
	v_mul_f32_e32 v41, v40, v39
	v_fma_f32 v42, -v31, v41, v40
	v_fmac_f32_e32 v41, v42, v39
	v_fma_f32 v31, -v31, v41, v40
	v_div_fmas_f32 v31, v31, v39, v41
	v_div_fixup_f32 v30, v31, v30, 2.0
	v_sub_f32_e32 v30, 1.0, v30
	v_add_f32_e32 v30, 1.0, v30
	v_mul_f32_e32 v39, v26, v30
	v_lshlrev_b32_e32 v26, 16, v32
	v_mul_f32_e32 v30, 0x3d372713, v26
	v_mul_f32_e32 v30, v30, v26
	v_fma_f32 v30, v30, v26, v26
	v_mul_f32_e32 v30, 0x3f4c422a, v30
	v_add_f32_e32 v30, v30, v30
	v_mul_f32_e32 v30, 0x3fb8aa3b, v30
	v_exp_f32_e32 v30, v30
	v_mul_f32_e32 v26, 0.5, v26
	v_add_f32_e32 v30, 1.0, v30
	v_div_scale_f32 v31, s[14:15], v30, v30, 2.0
	v_rcp_f32_e32 v40, v31
	s_nop 0
	v_fma_f32 v41, -v31, v40, 1.0
	v_fmac_f32_e32 v40, v41, v40
	v_div_scale_f32 v41, vcc, 2.0, v30, 2.0
	v_mul_f32_e32 v42, v41, v40
	v_fma_f32 v43, -v31, v42, v41
	v_fmac_f32_e32 v42, v43, v40
	v_fma_f32 v31, -v31, v42, v41
	v_div_fmas_f32 v31, v31, v40, v42
	v_div_fixup_f32 v30, v31, v30, 2.0
	v_sub_f32_e32 v30, 1.0, v30
	v_add_f32_e32 v30, 1.0, v30
	v_mul_f32_e32 v40, v26, v30
	v_and_b32_e32 v26, 0xffff0000, v32
	v_mul_f32_e32 v30, 0x3d372713, v26
	v_mul_f32_e32 v30, v30, v26
	v_fma_f32 v30, v30, v26, v26
	v_mul_f32_e32 v30, 0x3f4c422a, v30
	v_add_f32_e32 v30, v30, v30
	v_mul_f32_e32 v30, 0x3fb8aa3b, v30
	v_exp_f32_e32 v30, v30
	v_mul_f32_e32 v26, 0.5, v26
	v_add_f32_e32 v30, 1.0, v30
	v_div_scale_f32 v31, s[14:15], v30, v30, 2.0
	v_rcp_f32_e32 v32, v31
	s_nop 0
	v_fma_f32 v41, -v31, v32, 1.0
	v_fmac_f32_e32 v32, v41, v32
	v_div_scale_f32 v41, vcc, 2.0, v30, 2.0
	v_mul_f32_e32 v42, v41, v32
	v_fma_f32 v43, -v31, v42, v41
	v_fmac_f32_e32 v42, v43, v32
	v_fma_f32 v31, -v31, v42, v41
	v_div_fmas_f32 v31, v31, v32, v42
	v_div_fixup_f32 v30, v31, v30, 2.0
	v_sub_f32_e32 v30, 1.0, v30
	v_add_f32_e32 v30, 1.0, v30
	v_mul_f32_e32 v32, v26, v30
	v_lshlrev_b32_e32 v26, 16, v33
	v_mul_f32_e32 v30, 0x3d372713, v26
	v_mul_f32_e32 v30, v30, v26
	v_fma_f32 v30, v30, v26, v26
	v_mul_f32_e32 v30, 0x3f4c422a, v30
	v_add_f32_e32 v30, v30, v30
	v_mul_f32_e32 v30, 0x3fb8aa3b, v30
	v_exp_f32_e32 v30, v30
	v_mul_f32_e32 v26, 0.5, v26
	v_add_f32_e32 v30, 1.0, v30
	v_div_scale_f32 v31, s[14:15], v30, v30, 2.0
	v_rcp_f32_e32 v41, v31
	s_nop 0
	v_fma_f32 v42, -v31, v41, 1.0
	v_fmac_f32_e32 v41, v42, v41
	v_div_scale_f32 v42, vcc, 2.0, v30, 2.0
	v_mul_f32_e32 v43, v42, v41
	v_fma_f32 v44, -v31, v43, v42
	v_fmac_f32_e32 v43, v44, v41
	v_fma_f32 v31, -v31, v43, v42
	v_div_fmas_f32 v31, v31, v41, v43
	v_div_fixup_f32 v30, v31, v30, 2.0
	v_sub_f32_e32 v30, 1.0, v30
	v_add_f32_e32 v30, 1.0, v30
	v_mul_f32_e32 v41, v26, v30
	v_and_b32_e32 v26, 0xffff0000, v33
	v_mul_f32_e32 v30, 0x3d372713, v26
	v_mul_f32_e32 v30, v30, v26
	v_fma_f32 v30, v30, v26, v26
	v_mul_f32_e32 v30, 0x3f4c422a, v30
	v_add_f32_e32 v30, v30, v30
	v_mul_f32_e32 v30, 0x3fb8aa3b, v30
	v_exp_f32_e32 v30, v30
	v_mul_f32_e32 v26, 0.5, v26
	v_add_f32_e32 v30, 1.0, v30
	v_div_scale_f32 v31, s[14:15], v30, v30, 2.0
	v_rcp_f32_e32 v33, v31
	s_nop 0
	v_fma_f32 v42, -v31, v33, 1.0
	v_fmac_f32_e32 v33, v42, v33
	v_div_scale_f32 v42, vcc, 2.0, v30, 2.0
	v_mul_f32_e32 v43, v42, v33
	v_fma_f32 v44, -v31, v43, v42
	v_fmac_f32_e32 v43, v44, v33
	v_fma_f32 v31, -v31, v43, v42
	v_div_fmas_f32 v31, v31, v33, v43
	v_div_fixup_f32 v30, v31, v30, 2.0
	v_sub_f32_e32 v30, 1.0, v30
	v_add_f32_e32 v30, 1.0, v30
	v_mul_f32_e32 v33, v26, v30
	v_and_b32_e32 v26, 0xffff0000, v27
	v_lshlrev_b32_e32 v27, 16, v27
	v_mul_f32_e32 v30, 0x3d372713, v27
	v_mul_f32_e32 v30, v30, v27
	v_mov_b32_e32 v31, v27
	v_fmac_f32_e32 v31, v30, v31
	v_mul_f32_e32 v30, 0x3f4c422a, v31
	v_add_f32_e32 v30, v30, v30
	v_mul_f32_e32 v30, 0x3fb8aa3b, v30
	v_exp_f32_e32 v31, v30
	v_mul_f32_e32 v30, 0x3d372713, v26
	v_mul_f32_e32 v30, v30, v26
	v_mov_b32_e32 v43, v26
	v_fmac_f32_e32 v43, v30, v43
	v_mul_f32_e32 v30, 0x3f4c422a, v43
	v_add_f32_e32 v30, v30, v30
	v_mul_f32_e32 v30, 0x3fb8aa3b, v30
	v_exp_f32_e32 v30, v30
	v_pk_mul_f32 v[26:27], v[26:27], 0.5 op_sel_hi:[1,0]
	v_mul_f32_e32 v42, v37, v37
	v_fmac_f32_e32 v42, v36, v36
	v_pk_add_f32 v[30:31], v[30:31], 1.0 op_sel_hi:[1,0]
	s_nop 0
	v_div_scale_f32 v43, s[14:15], v31, v31, 2.0
	v_rcp_f32_e32 v44, v43
	s_nop 0
	v_fma_f32 v45, -v43, v44, 1.0
	v_fmac_f32_e32 v44, v45, v44
	v_div_scale_f32 v45, vcc, 2.0, v31, 2.0
	v_mul_f32_e32 v46, v45, v44
	v_fma_f32 v47, -v43, v46, v45
	v_fmac_f32_e32 v46, v47, v44
	v_fma_f32 v43, -v43, v46, v45
	v_div_fmas_f32 v43, v43, v44, v46
	v_div_fixup_f32 v31, v43, v31, 2.0
	v_div_scale_f32 v43, s[14:15], v30, v30, 2.0
	v_rcp_f32_e32 v44, v43
	s_nop 0
	v_fma_f32 v45, -v43, v44, 1.0
	v_fmac_f32_e32 v44, v45, v44
	v_div_scale_f32 v45, vcc, 2.0, v30, 2.0
	v_mul_f32_e32 v46, v45, v44
	v_fma_f32 v47, -v43, v46, v45
	v_fmac_f32_e32 v46, v47, v44
	v_fma_f32 v43, -v43, v46, v45
	v_div_fmas_f32 v43, v43, v44, v46
	v_div_fixup_f32 v30, v43, v30, 2.0
	v_pk_add_f32 v[30:31], v[30:31], 1.0 op_sel_hi:[1,0] neg_lo:[1,0] neg_hi:[1,0]
	s_nop 0
	v_pk_add_f32 v[30:31], v[30:31], 1.0 op_sel_hi:[1,0]
	s_nop 0
	v_pk_mul_f32 v[26:27], v[26:27], v[30:31]
	s_nop 0
	v_pk_mul_f32 v[30:31], v[26:27], v[26:27]
	s_nop 0
	v_add_f32_e32 v31, v31, v42
	v_add_f32_e32 v44, v30, v31
	v_lshlrev_b32_e32 v31, 16, v28
	v_and_b32_e32 v30, 0xffff0000, v28
	v_mul_f32_e32 v28, 0x3d372713, v31
	v_mul_f32_e32 v28, v28, v31
	v_mov_b32_e32 v42, v31
	v_fmac_f32_e32 v42, v28, v42
	v_mul_f32_e32 v28, 0x3f4c422a, v42
	v_add_f32_e32 v28, v28, v28
	v_mul_f32_e32 v28, 0x3fb8aa3b, v28
	v_exp_f32_e32 v43, v28
	v_mul_f32_e32 v28, 0x3d372713, v30
	v_mul_f32_e32 v28, v28, v30
	v_mov_b32_e32 v42, v30
	v_fmac_f32_e32 v42, v28, v42
	v_mul_f32_e32 v28, 0x3f4c422a, v42
	v_add_f32_e32 v28, v28, v28
	v_mul_f32_e32 v28, 0x3fb8aa3b, v28
	v_exp_f32_e32 v42, v28
	v_pk_mul_f32 v[30:31], v[30:31], 0.5 op_sel_hi:[1,0]
	v_pk_add_f32 v[42:43], v[42:43], 1.0 op_sel_hi:[1,0]
	s_nop 0
	v_div_scale_f32 v28, s[14:15], v43, v43, 2.0
	v_rcp_f32_e32 v45, v28
	s_nop 0
	v_fma_f32 v46, -v28, v45, 1.0
	v_fmac_f32_e32 v45, v46, v45
	v_div_scale_f32 v46, vcc, 2.0, v43, 2.0
	v_mul_f32_e32 v47, v46, v45
	v_fma_f32 v48, -v28, v47, v46
	v_fmac_f32_e32 v47, v48, v45
	v_fma_f32 v28, -v28, v47, v46
	v_div_fmas_f32 v28, v28, v45, v47
	v_div_fixup_f32 v43, v28, v43, 2.0
	v_div_scale_f32 v28, s[14:15], v42, v42, 2.0
	v_rcp_f32_e32 v45, v28
	s_nop 0
	v_fma_f32 v46, -v28, v45, 1.0
	v_fmac_f32_e32 v45, v46, v45
	v_div_scale_f32 v46, vcc, 2.0, v42, 2.0
	v_mul_f32_e32 v47, v46, v45
	v_fma_f32 v48, -v28, v47, v46
	v_fmac_f32_e32 v47, v48, v45
	v_fma_f32 v28, -v28, v47, v46
	v_div_fmas_f32 v28, v28, v45, v47
	v_div_fixup_f32 v42, v28, v42, 2.0
	v_pk_add_f32 v[42:43], v[42:43], 1.0 op_sel_hi:[1,0] neg_lo:[1,0] neg_hi:[1,0]
	s_nop 0
	v_pk_add_f32 v[42:43], v[42:43], 1.0 op_sel_hi:[1,0]
	s_nop 0
	v_pk_mul_f32 v[30:31], v[30:31], v[42:43]
	s_nop 0
	v_pk_mul_f32 v[42:43], v[30:31], v[30:31]
	s_nop 0
	v_add_f32_e32 v28, v43, v44
	v_add_f32_e32 v44, v42, v28
	v_and_b32_e32 v28, 0xffff0000, v29
	v_lshlrev_b32_e32 v29, 16, v29
	v_mul_f32_e32 v42, 0x3d372713, v29
	v_mul_f32_e32 v42, v42, v29
	v_mov_b32_e32 v43, v29
	v_fmac_f32_e32 v43, v42, v43
	v_mul_f32_e32 v42, 0x3f4c422a, v43
	v_add_f32_e32 v42, v42, v42
	v_mul_f32_e32 v42, 0x3fb8aa3b, v42
	v_exp_f32_e32 v43, v42
	v_mul_f32_e32 v42, 0x3d372713, v28
	v_mul_f32_e32 v42, v42, v28
	v_mov_b32_e32 v45, v28
	v_fmac_f32_e32 v45, v42, v45
	v_mul_f32_e32 v42, 0x3f4c422a, v45
	v_add_f32_e32 v42, v42, v42
	v_mul_f32_e32 v42, 0x3fb8aa3b, v42
	v_exp_f32_e32 v42, v42
	v_pk_mul_f32 v[28:29], v[28:29], 0.5 op_sel_hi:[1,0]
	v_pk_add_f32 v[42:43], v[42:43], 1.0 op_sel_hi:[1,0]
	s_nop 0
	v_div_scale_f32 v45, s[14:15], v43, v43, 2.0
	v_rcp_f32_e32 v46, v45
	s_nop 0
	v_fma_f32 v47, -v45, v46, 1.0
	v_fmac_f32_e32 v46, v47, v46
	v_div_scale_f32 v47, vcc, 2.0, v43, 2.0
	v_mul_f32_e32 v48, v47, v46
	v_fma_f32 v49, -v45, v48, v47
	v_fmac_f32_e32 v48, v49, v46
	v_fma_f32 v45, -v45, v48, v47
	v_div_fmas_f32 v45, v45, v46, v48
	v_div_fixup_f32 v43, v45, v43, 2.0
	v_div_scale_f32 v45, s[14:15], v42, v42, 2.0
	v_rcp_f32_e32 v46, v45
	s_nop 0
	v_fma_f32 v47, -v45, v46, 1.0
	v_fmac_f32_e32 v46, v47, v46
	v_div_scale_f32 v47, vcc, 2.0, v42, 2.0
	v_mul_f32_e32 v48, v47, v46
	v_fma_f32 v49, -v45, v48, v47
	v_fmac_f32_e32 v48, v49, v46
	v_fma_f32 v45, -v45, v48, v47
	v_div_fmas_f32 v45, v45, v46, v48
	v_div_fixup_f32 v42, v45, v42, 2.0
	v_pk_add_f32 v[42:43], v[42:43], 1.0 op_sel_hi:[1,0] neg_lo:[1,0] neg_hi:[1,0]
	s_nop 0
	v_pk_add_f32 v[42:43], v[42:43], 1.0 op_sel_hi:[1,0]
	s_nop 0
	v_pk_mul_f32 v[42:43], v[28:29], v[42:43]
	s_nop 0
	v_pk_mul_f32 v[28:29], v[42:43], v[42:43]
	s_nop 0
	v_add_f32_e32 v29, v29, v44
	v_add_f32_e32 v28, v28, v29
	s_nop 1
	v_mov_b32_dpp v29, v28 quad_perm:[1,0,3,2] row_mask:0xf bank_mask:0xf
	s_waitcnt lgkmcnt(0)
	v_add_f32_e32 v28, v28, v29
	s_nop 1
	v_mov_b32_dpp v29, v28 quad_perm:[2,3,0,1] row_mask:0xf bank_mask:0xf
	s_waitcnt lgkmcnt(0)
	v_add_f32_e32 v28, v28, v29
	s_nop 1
	v_mov_b32_dpp v29, v28 row_half_mirror row_mask:0xf bank_mask:0xf
	s_waitcnt lgkmcnt(0)
	v_add_f32_e32 v28, v28, v29
	s_nop 1
	v_mov_b32_dpp v29, v28 row_mirror row_mask:0xf bank_mask:0xf
	s_waitcnt lgkmcnt(0)
	v_add_f32_e32 v28, v28, v29
	ds_bpermute_b32 v29, v110, v28
	s_waitcnt lgkmcnt(0)
	v_add_f32_e32 v28, v28, v29
	v_fmamk_f32 v28, v28, 0x3b800000, v243
	v_cmp_gt_f32_e32 vcc, s3, v28
	v_mul_f32_e32 v29, 0x4b800000, v28
	s_nop 0
	v_cndmask_b32_e32 v28, v28, v29, vcc
	v_rsq_f32_e32 v28, v28
	s_nop 0
	v_mul_f32_e32 v29, 0x45800000, v28
	v_cndmask_b32_e32 v44, v28, v29, vcc
	v_mul_f32_e32 v28, v36, v44
	v_mul_f32_e32 v29, v37, v44
	v_mul_f32_e32 v26, v26, v44
	v_mul_f32_e32 v28, v70, v28
	v_mul_f32_e32 v29, v71, v29
	v_mul_f32_e32 v27, v27, v44
	v_mul_f32_e32 v26, v73, v26
	v_cvt_pk_bf16_f32 v28, v28, v29
	v_cvt_pk_bf16_f32 v35, v38, v39
	v_mul_f32_e32 v27, v72, v27
	v_cvt_pk_bf16_f32 v29, v27, v26
	v_mul_f32_e32 v26, v31, v44
	v_mul_f32_e32 v26, v66, v26
	v_mul_f32_e32 v27, v30, v44
	v_cvt_pk_bf16_f32 v36, v40, v32
	v_mul_f32_e32 v27, v67, v27
	v_cvt_pk_bf16_f32 v30, v26, v27
	v_mul_f32_e32 v26, v43, v44
	v_mul_f32_e32 v26, v68, v26
	v_mul_f32_e32 v27, v42, v44
	v_cvt_pk_bf16_f32 v37, v41, v33
	v_mul_f32_e32 v27, v69, v27
	v_cvt_pk_bf16_f32 v31, v26, v27
	v_lshlrev_b32_e32 v26, 16, v22
	v_mul_f32_e32 v27, 0x3d372713, v26
	v_mul_f32_e32 v27, v27, v26
	v_fma_f32 v27, v27, v26, v26
	v_mul_f32_e32 v27, 0x3f4c422a, v27
	v_add_f32_e32 v27, v27, v27
	v_mul_f32_e32 v27, 0x3fb8aa3b, v27
	v_exp_f32_e32 v27, v27
	ds_write_b128 v111, v[34:37] offset:34816
	ds_write_b128 v112, v[28:31] offset:34816
	v_mul_f32_e32 v26, 0.5, v26
	v_and_b32_e32 v22, 0xffff0000, v22
	v_add_f32_e32 v27, 1.0, v27
	v_div_scale_f32 v28, s[14:15], v27, v27, 2.0
	v_rcp_f32_e32 v29, v28
	s_nop 0
	v_fma_f32 v30, -v28, v29, 1.0
	v_fmac_f32_e32 v29, v30, v29
	v_div_scale_f32 v30, vcc, 2.0, v27, 2.0
	v_mul_f32_e32 v31, v30, v29
	v_fma_f32 v32, -v28, v31, v30
	v_fmac_f32_e32 v31, v32, v29
	v_fma_f32 v28, -v28, v31, v30
	v_div_fmas_f32 v28, v28, v29, v31
	v_div_fixup_f32 v27, v28, v27, 2.0
	v_sub_f32_e32 v27, 1.0, v27
	v_add_f32_e32 v27, 1.0, v27
	v_mul_f32_e32 v26, v26, v27
	v_mul_f32_e32 v27, 0x3d372713, v22
	v_mul_f32_e32 v27, v27, v22
	v_fma_f32 v27, v27, v22, v22
	v_mul_f32_e32 v27, 0x3f4c422a, v27
	v_add_f32_e32 v27, v27, v27
	v_mul_f32_e32 v27, 0x3fb8aa3b, v27
	v_exp_f32_e32 v27, v27
	v_mul_f32_e32 v22, 0.5, v22
	v_add_f32_e32 v27, 1.0, v27
	v_div_scale_f32 v28, s[14:15], v27, v27, 2.0
	v_rcp_f32_e32 v29, v28
	s_nop 0
	v_fma_f32 v30, -v28, v29, 1.0
	v_fmac_f32_e32 v29, v30, v29
	v_div_scale_f32 v30, vcc, 2.0, v27, 2.0
	v_mul_f32_e32 v31, v30, v29
	v_fma_f32 v32, -v28, v31, v30
	v_fmac_f32_e32 v31, v32, v29
	v_fma_f32 v28, -v28, v31, v30
	v_div_fmas_f32 v28, v28, v29, v31
	v_div_fixup_f32 v27, v28, v27, 2.0
	v_sub_f32_e32 v27, 1.0, v27
	v_add_f32_e32 v27, 1.0, v27
	v_mul_f32_e32 v27, v22, v27
	v_lshlrev_b32_e32 v22, 16, v18
	v_mul_f32_e32 v28, 0x3d372713, v22
	v_mul_f32_e32 v28, v28, v22
	v_fma_f32 v28, v28, v22, v22
	v_mul_f32_e32 v28, 0x3f4c422a, v28
	v_add_f32_e32 v28, v28, v28
	v_mul_f32_e32 v28, 0x3fb8aa3b, v28
	v_exp_f32_e32 v28, v28
	v_mul_f32_e32 v22, 0.5, v22
	v_and_b32_e32 v18, 0xffff0000, v18
	v_cvt_pk_bf16_f32 v26, v26, v27
	v_add_f32_e32 v28, 1.0, v28
	v_div_scale_f32 v29, s[14:15], v28, v28, 2.0
	v_rcp_f32_e32 v30, v29
	s_nop 0
	v_fma_f32 v31, -v29, v30, 1.0
	v_fmac_f32_e32 v30, v31, v30
	v_div_scale_f32 v31, vcc, 2.0, v28, 2.0
	v_mul_f32_e32 v32, v31, v30
	v_fma_f32 v33, -v29, v32, v31
	v_fmac_f32_e32 v32, v33, v30
	v_fma_f32 v29, -v29, v32, v31
	v_div_fmas_f32 v29, v29, v30, v32
	v_div_fixup_f32 v28, v29, v28, 2.0
	v_sub_f32_e32 v28, 1.0, v28
	v_add_f32_e32 v28, 1.0, v28
	v_mul_f32_e32 v28, v22, v28
	v_mul_f32_e32 v22, 0x3d372713, v18
	v_mul_f32_e32 v22, v22, v18
	v_fma_f32 v22, v22, v18, v18
	v_mul_f32_e32 v22, 0x3f4c422a, v22
	v_add_f32_e32 v22, v22, v22
	v_mul_f32_e32 v22, 0x3fb8aa3b, v22
	v_exp_f32_e32 v22, v22
	v_mul_f32_e32 v18, 0.5, v18
	v_add_f32_e32 v22, 1.0, v22
	v_div_scale_f32 v29, s[14:15], v22, v22, 2.0
	v_rcp_f32_e32 v30, v29
	s_nop 0
	v_fma_f32 v31, -v29, v30, 1.0
	v_fmac_f32_e32 v30, v31, v30
	v_div_scale_f32 v31, vcc, 2.0, v22, 2.0
	v_mul_f32_e32 v32, v31, v30
	v_fma_f32 v33, -v29, v32, v31
	v_fmac_f32_e32 v32, v33, v30
	v_fma_f32 v29, -v29, v32, v31
	v_div_fmas_f32 v29, v29, v30, v32
	v_div_fixup_f32 v22, v29, v22, 2.0
	v_sub_f32_e32 v22, 1.0, v22
	v_add_f32_e32 v22, 1.0, v22
	v_mul_f32_e32 v29, v18, v22
	v_lshlrev_b32_e32 v18, 16, v23
	v_mul_f32_e32 v22, 0x3d372713, v18
	v_mul_f32_e32 v22, v22, v18
	v_fma_f32 v22, v22, v18, v18
	v_mul_f32_e32 v22, 0x3f4c422a, v22
	v_add_f32_e32 v22, v22, v22
	v_mul_f32_e32 v22, 0x3fb8aa3b, v22
	v_exp_f32_e32 v22, v22
	v_mul_f32_e32 v18, 0.5, v18
	v_add_f32_e32 v22, 1.0, v22
	v_div_scale_f32 v30, s[14:15], v22, v22, 2.0
	v_rcp_f32_e32 v31, v30
	s_nop 0
	v_fma_f32 v32, -v30, v31, 1.0
	v_fmac_f32_e32 v31, v32, v31
	v_div_scale_f32 v32, vcc, 2.0, v22, 2.0
	v_mul_f32_e32 v33, v32, v31
	v_fma_f32 v34, -v30, v33, v32
	v_fmac_f32_e32 v33, v34, v31
	v_fma_f32 v30, -v30, v33, v32
	v_div_fmas_f32 v30, v30, v31, v33
	v_div_fixup_f32 v22, v30, v22, 2.0
	v_sub_f32_e32 v22, 1.0, v22
	v_add_f32_e32 v22, 1.0, v22
	v_mul_f32_e32 v30, v18, v22
	v_and_b32_e32 v18, 0xffff0000, v23
	v_mul_f32_e32 v22, 0x3d372713, v18
	v_mul_f32_e32 v22, v22, v18
	v_fma_f32 v22, v22, v18, v18
	v_mul_f32_e32 v22, 0x3f4c422a, v22
	v_add_f32_e32 v22, v22, v22
	v_mul_f32_e32 v22, 0x3fb8aa3b, v22
	v_exp_f32_e32 v22, v22
	v_mul_f32_e32 v18, 0.5, v18
	v_add_f32_e32 v22, 1.0, v22
	v_div_scale_f32 v23, s[14:15], v22, v22, 2.0
	v_rcp_f32_e32 v31, v23
	s_nop 0
	v_fma_f32 v32, -v23, v31, 1.0
	v_fmac_f32_e32 v31, v32, v31
	v_div_scale_f32 v32, vcc, 2.0, v22, 2.0
	v_mul_f32_e32 v33, v32, v31
	v_fma_f32 v34, -v23, v33, v32
	v_fmac_f32_e32 v33, v34, v31
	v_fma_f32 v23, -v23, v33, v32
	v_div_fmas_f32 v23, v23, v31, v33
	v_div_fixup_f32 v22, v23, v22, 2.0
	v_sub_f32_e32 v22, 1.0, v22
	v_add_f32_e32 v22, 1.0, v22
	v_mul_f32_e32 v31, v18, v22
	v_lshlrev_b32_e32 v18, 16, v24
	v_mul_f32_e32 v22, 0x3d372713, v18
	v_mul_f32_e32 v22, v22, v18
	v_fma_f32 v22, v22, v18, v18
	v_mul_f32_e32 v22, 0x3f4c422a, v22
	v_add_f32_e32 v22, v22, v22
	v_mul_f32_e32 v22, 0x3fb8aa3b, v22
	v_exp_f32_e32 v22, v22
	v_mul_f32_e32 v18, 0.5, v18
	v_add_f32_e32 v22, 1.0, v22
	v_div_scale_f32 v23, s[14:15], v22, v22, 2.0
	v_rcp_f32_e32 v32, v23
	s_nop 0
	v_fma_f32 v33, -v23, v32, 1.0
	v_fmac_f32_e32 v32, v33, v32
	v_div_scale_f32 v33, vcc, 2.0, v22, 2.0
	v_mul_f32_e32 v34, v33, v32
	v_fma_f32 v35, -v23, v34, v33
	v_fmac_f32_e32 v34, v35, v32
	v_fma_f32 v23, -v23, v34, v33
	v_div_fmas_f32 v23, v23, v32, v34
	v_div_fixup_f32 v22, v23, v22, 2.0
	v_sub_f32_e32 v22, 1.0, v22
	v_add_f32_e32 v22, 1.0, v22
	v_mul_f32_e32 v32, v18, v22
	v_and_b32_e32 v18, 0xffff0000, v24
	v_mul_f32_e32 v22, 0x3d372713, v18
	v_mul_f32_e32 v22, v22, v18
	v_fma_f32 v22, v22, v18, v18
	v_mul_f32_e32 v22, 0x3f4c422a, v22
	v_add_f32_e32 v22, v22, v22
	v_mul_f32_e32 v22, 0x3fb8aa3b, v22
	v_exp_f32_e32 v22, v22
	v_mul_f32_e32 v18, 0.5, v18
	v_add_f32_e32 v22, 1.0, v22
	v_div_scale_f32 v23, s[14:15], v22, v22, 2.0
	v_rcp_f32_e32 v24, v23
	s_nop 0
	v_fma_f32 v33, -v23, v24, 1.0
	v_fmac_f32_e32 v24, v33, v24
	v_div_scale_f32 v33, vcc, 2.0, v22, 2.0
	v_mul_f32_e32 v34, v33, v24
	v_fma_f32 v35, -v23, v34, v33
	v_fmac_f32_e32 v34, v35, v24
	v_fma_f32 v23, -v23, v34, v33
	v_div_fmas_f32 v23, v23, v24, v34
	v_div_fixup_f32 v22, v23, v22, 2.0
	v_sub_f32_e32 v22, 1.0, v22
	v_add_f32_e32 v22, 1.0, v22
	v_mul_f32_e32 v24, v18, v22
	v_lshlrev_b32_e32 v18, 16, v25
	v_mul_f32_e32 v22, 0x3d372713, v18
	v_mul_f32_e32 v22, v22, v18
	v_fma_f32 v22, v22, v18, v18
	v_mul_f32_e32 v22, 0x3f4c422a, v22
	v_add_f32_e32 v22, v22, v22
	v_mul_f32_e32 v22, 0x3fb8aa3b, v22
	v_exp_f32_e32 v22, v22
	v_mul_f32_e32 v18, 0.5, v18
	v_add_f32_e32 v22, 1.0, v22
	v_div_scale_f32 v23, s[14:15], v22, v22, 2.0
	v_rcp_f32_e32 v33, v23
	s_nop 0
	v_fma_f32 v34, -v23, v33, 1.0
	v_fmac_f32_e32 v33, v34, v33
	v_div_scale_f32 v34, vcc, 2.0, v22, 2.0
	v_mul_f32_e32 v35, v34, v33
	v_fma_f32 v36, -v23, v35, v34
	v_fmac_f32_e32 v35, v36, v33
	v_fma_f32 v23, -v23, v35, v34
	v_div_fmas_f32 v23, v23, v33, v35
	v_div_fixup_f32 v22, v23, v22, 2.0
	v_sub_f32_e32 v22, 1.0, v22
	v_add_f32_e32 v22, 1.0, v22
	v_mul_f32_e32 v33, v18, v22
	v_and_b32_e32 v18, 0xffff0000, v25
	v_mul_f32_e32 v22, 0x3d372713, v18
	v_mul_f32_e32 v22, v22, v18
	v_fma_f32 v22, v22, v18, v18
	v_mul_f32_e32 v22, 0x3f4c422a, v22
	v_add_f32_e32 v22, v22, v22
	v_mul_f32_e32 v22, 0x3fb8aa3b, v22
	v_exp_f32_e32 v22, v22
	v_mul_f32_e32 v18, 0.5, v18
	v_add_f32_e32 v22, 1.0, v22
	v_div_scale_f32 v23, s[14:15], v22, v22, 2.0
	v_rcp_f32_e32 v25, v23
	s_nop 0
	v_fma_f32 v34, -v23, v25, 1.0
	v_fmac_f32_e32 v25, v34, v25
	v_div_scale_f32 v34, vcc, 2.0, v22, 2.0
	v_mul_f32_e32 v35, v34, v25
	v_fma_f32 v36, -v23, v35, v34
	v_fmac_f32_e32 v35, v36, v25
	v_fma_f32 v23, -v23, v35, v34
	v_div_fmas_f32 v23, v23, v25, v35
	v_div_fixup_f32 v22, v23, v22, 2.0
	v_sub_f32_e32 v22, 1.0, v22
	v_add_f32_e32 v22, 1.0, v22
	v_mul_f32_e32 v25, v18, v22
	v_and_b32_e32 v18, 0xffff0000, v19
	v_lshlrev_b32_e32 v19, 16, v19
	v_mul_f32_e32 v22, 0x3d372713, v19
	v_mul_f32_e32 v22, v22, v19
	v_mov_b32_e32 v23, v19
	v_fmac_f32_e32 v23, v22, v23
	v_mul_f32_e32 v22, 0x3f4c422a, v23
	v_add_f32_e32 v22, v22, v22
	v_mul_f32_e32 v22, 0x3fb8aa3b, v22
	v_exp_f32_e32 v23, v22
	v_mul_f32_e32 v22, 0x3d372713, v18
	v_mul_f32_e32 v22, v22, v18
	v_mov_b32_e32 v35, v18
	v_fmac_f32_e32 v35, v22, v35
	v_mul_f32_e32 v22, 0x3f4c422a, v35
	v_add_f32_e32 v22, v22, v22
	v_mul_f32_e32 v22, 0x3fb8aa3b, v22
	v_exp_f32_e32 v22, v22
	v_pk_mul_f32 v[18:19], v[18:19], 0.5 op_sel_hi:[1,0]
	v_mul_f32_e32 v34, v29, v29
	v_fmac_f32_e32 v34, v28, v28
	v_pk_add_f32 v[22:23], v[22:23], 1.0 op_sel_hi:[1,0]
	s_nop 0
	v_div_scale_f32 v35, s[14:15], v23, v23, 2.0
	v_rcp_f32_e32 v36, v35
	s_nop 0
	v_fma_f32 v37, -v35, v36, 1.0
	v_fmac_f32_e32 v36, v37, v36
	v_div_scale_f32 v37, vcc, 2.0, v23, 2.0
	v_mul_f32_e32 v38, v37, v36
	v_fma_f32 v39, -v35, v38, v37
	v_fmac_f32_e32 v38, v39, v36
	v_fma_f32 v35, -v35, v38, v37
	v_div_fmas_f32 v35, v35, v36, v38
	v_div_fixup_f32 v23, v35, v23, 2.0
	v_div_scale_f32 v35, s[14:15], v22, v22, 2.0
	v_rcp_f32_e32 v36, v35
	s_nop 0
	v_fma_f32 v37, -v35, v36, 1.0
	v_fmac_f32_e32 v36, v37, v36
	v_div_scale_f32 v37, vcc, 2.0, v22, 2.0
	v_mul_f32_e32 v38, v37, v36
	v_fma_f32 v39, -v35, v38, v37
	v_fmac_f32_e32 v38, v39, v36
	v_fma_f32 v35, -v35, v38, v37
	v_div_fmas_f32 v35, v35, v36, v38
	v_div_fixup_f32 v22, v35, v22, 2.0
	v_pk_add_f32 v[22:23], v[22:23], 1.0 op_sel_hi:[1,0] neg_lo:[1,0] neg_hi:[1,0]
	s_nop 0
	v_pk_add_f32 v[22:23], v[22:23], 1.0 op_sel_hi:[1,0]
	s_nop 0
	v_pk_mul_f32 v[18:19], v[18:19], v[22:23]
	s_nop 0
	v_pk_mul_f32 v[22:23], v[18:19], v[18:19]
	s_nop 0
	v_add_f32_e32 v23, v23, v34
	v_add_f32_e32 v36, v22, v23
	v_lshlrev_b32_e32 v23, 16, v20
	v_and_b32_e32 v22, 0xffff0000, v20
	v_mul_f32_e32 v20, 0x3d372713, v23
	v_mul_f32_e32 v20, v20, v23
	v_mov_b32_e32 v34, v23
	v_fmac_f32_e32 v34, v20, v34
	v_mul_f32_e32 v20, 0x3f4c422a, v34
	v_add_f32_e32 v20, v20, v20
	v_mul_f32_e32 v20, 0x3fb8aa3b, v20
	v_exp_f32_e32 v35, v20
	v_mul_f32_e32 v20, 0x3d372713, v22
	v_mul_f32_e32 v20, v20, v22
	v_mov_b32_e32 v34, v22
	v_fmac_f32_e32 v34, v20, v34
	v_mul_f32_e32 v20, 0x3f4c422a, v34
	v_add_f32_e32 v20, v20, v20
	v_mul_f32_e32 v20, 0x3fb8aa3b, v20
	v_exp_f32_e32 v34, v20
	v_pk_mul_f32 v[22:23], v[22:23], 0.5 op_sel_hi:[1,0]
	v_pk_add_f32 v[34:35], v[34:35], 1.0 op_sel_hi:[1,0]
	s_nop 0
	v_div_scale_f32 v20, s[14:15], v35, v35, 2.0
	v_rcp_f32_e32 v37, v20
	s_nop 0
	v_fma_f32 v38, -v20, v37, 1.0
	v_fmac_f32_e32 v37, v38, v37
	v_div_scale_f32 v38, vcc, 2.0, v35, 2.0
	v_mul_f32_e32 v39, v38, v37
	v_fma_f32 v40, -v20, v39, v38
	v_fmac_f32_e32 v39, v40, v37
	v_fma_f32 v20, -v20, v39, v38
	v_div_fmas_f32 v20, v20, v37, v39
	v_div_fixup_f32 v35, v20, v35, 2.0
	v_div_scale_f32 v20, s[14:15], v34, v34, 2.0
	v_rcp_f32_e32 v37, v20
	s_nop 0
	v_fma_f32 v38, -v20, v37, 1.0
	v_fmac_f32_e32 v37, v38, v37
	v_div_scale_f32 v38, vcc, 2.0, v34, 2.0
	v_mul_f32_e32 v39, v38, v37
	v_fma_f32 v40, -v20, v39, v38
	v_fmac_f32_e32 v39, v40, v37
	v_fma_f32 v20, -v20, v39, v38
	v_div_fmas_f32 v20, v20, v37, v39
	v_div_fixup_f32 v34, v20, v34, 2.0
	v_pk_add_f32 v[34:35], v[34:35], 1.0 op_sel_hi:[1,0] neg_lo:[1,0] neg_hi:[1,0]
	s_nop 0
	v_pk_add_f32 v[34:35], v[34:35], 1.0 op_sel_hi:[1,0]
	s_nop 0
	v_pk_mul_f32 v[22:23], v[22:23], v[34:35]
	s_nop 0
	v_pk_mul_f32 v[34:35], v[22:23], v[22:23]
	s_nop 0
	v_add_f32_e32 v20, v35, v36
	v_add_f32_e32 v36, v34, v20
	v_and_b32_e32 v20, 0xffff0000, v21
	v_lshlrev_b32_e32 v21, 16, v21
	v_mul_f32_e32 v34, 0x3d372713, v21
	v_mul_f32_e32 v34, v34, v21
	v_mov_b32_e32 v35, v21
	v_fmac_f32_e32 v35, v34, v35
	v_mul_f32_e32 v34, 0x3f4c422a, v35
	v_add_f32_e32 v34, v34, v34
	v_mul_f32_e32 v34, 0x3fb8aa3b, v34
	v_exp_f32_e32 v35, v34
	v_mul_f32_e32 v34, 0x3d372713, v20
	v_mul_f32_e32 v34, v34, v20
	v_mov_b32_e32 v37, v20
	v_fmac_f32_e32 v37, v34, v37
	v_mul_f32_e32 v34, 0x3f4c422a, v37
	v_add_f32_e32 v34, v34, v34
	v_mul_f32_e32 v34, 0x3fb8aa3b, v34
	v_exp_f32_e32 v34, v34
	v_pk_mul_f32 v[20:21], v[20:21], 0.5 op_sel_hi:[1,0]
	v_pk_add_f32 v[34:35], v[34:35], 1.0 op_sel_hi:[1,0]
	s_nop 0
	v_div_scale_f32 v37, s[14:15], v35, v35, 2.0
	v_rcp_f32_e32 v38, v37
	s_nop 0
	v_fma_f32 v39, -v37, v38, 1.0
	v_fmac_f32_e32 v38, v39, v38
	v_div_scale_f32 v39, vcc, 2.0, v35, 2.0
	v_mul_f32_e32 v40, v39, v38
	v_fma_f32 v41, -v37, v40, v39
	v_fmac_f32_e32 v40, v41, v38
	v_fma_f32 v37, -v37, v40, v39
	v_div_fmas_f32 v37, v37, v38, v40
	v_div_fixup_f32 v35, v37, v35, 2.0
	v_div_scale_f32 v37, s[14:15], v34, v34, 2.0
	v_rcp_f32_e32 v38, v37
	s_nop 0
	v_fma_f32 v39, -v37, v38, 1.0
	v_fmac_f32_e32 v38, v39, v38
	v_div_scale_f32 v39, vcc, 2.0, v34, 2.0
	v_mul_f32_e32 v40, v39, v38
	v_fma_f32 v41, -v37, v40, v39
	v_fmac_f32_e32 v40, v41, v38
	v_fma_f32 v37, -v37, v40, v39
	v_div_fmas_f32 v37, v37, v38, v40
	v_div_fixup_f32 v34, v37, v34, 2.0
	v_pk_add_f32 v[34:35], v[34:35], 1.0 op_sel_hi:[1,0] neg_lo:[1,0] neg_hi:[1,0]
	s_nop 0
	v_pk_add_f32 v[34:35], v[34:35], 1.0 op_sel_hi:[1,0]
	s_nop 0
	v_pk_mul_f32 v[34:35], v[20:21], v[34:35]
	s_nop 0
	v_pk_mul_f32 v[20:21], v[34:35], v[34:35]
	s_nop 0
	v_add_f32_e32 v21, v21, v36
	v_add_f32_e32 v20, v20, v21
	s_nop 1
	v_mov_b32_dpp v21, v20 quad_perm:[1,0,3,2] row_mask:0xf bank_mask:0xf
	s_waitcnt lgkmcnt(0)
	v_add_f32_e32 v20, v20, v21
	s_nop 1
	v_mov_b32_dpp v21, v20 quad_perm:[2,3,0,1] row_mask:0xf bank_mask:0xf
	s_waitcnt lgkmcnt(0)
	v_add_f32_e32 v20, v20, v21
	s_nop 1
	v_mov_b32_dpp v21, v20 row_half_mirror row_mask:0xf bank_mask:0xf
	s_waitcnt lgkmcnt(0)
	v_add_f32_e32 v20, v20, v21
	s_nop 1
	v_mov_b32_dpp v21, v20 row_mirror row_mask:0xf bank_mask:0xf
	s_waitcnt lgkmcnt(0)
	v_add_f32_e32 v20, v20, v21
	ds_bpermute_b32 v21, v110, v20
	s_waitcnt lgkmcnt(0)
	v_add_f32_e32 v20, v20, v21
	v_fmamk_f32 v20, v20, 0x3b800000, v243
	v_cmp_gt_f32_e32 vcc, s3, v20
	v_mul_f32_e32 v21, 0x4b800000, v20
	s_nop 0
	v_cndmask_b32_e32 v20, v20, v21, vcc
	v_rsq_f32_e32 v20, v20
	s_nop 0
	v_mul_f32_e32 v21, 0x45800000, v20
	v_cndmask_b32_e32 v36, v20, v21, vcc
	v_mul_f32_e32 v20, v28, v36
	v_mul_f32_e32 v21, v29, v36
	v_mul_f32_e32 v18, v18, v36
	v_mul_f32_e32 v20, v70, v20
	v_mul_f32_e32 v21, v71, v21
	v_mul_f32_e32 v19, v19, v36
	v_mul_f32_e32 v18, v73, v18
	v_cvt_pk_bf16_f32 v20, v20, v21
	v_cvt_pk_bf16_f32 v27, v30, v31
	v_mul_f32_e32 v19, v72, v19
	v_cvt_pk_bf16_f32 v21, v19, v18
	v_mul_f32_e32 v18, v23, v36
	v_mul_f32_e32 v18, v66, v18
	v_mul_f32_e32 v19, v22, v36
	v_cvt_pk_bf16_f32 v28, v32, v24
	v_mul_f32_e32 v19, v67, v19
	v_cvt_pk_bf16_f32 v22, v18, v19
	v_mul_f32_e32 v18, v35, v36
	v_mul_f32_e32 v18, v68, v18
	v_mul_f32_e32 v19, v34, v36
	v_cvt_pk_bf16_f32 v29, v33, v25
	v_mul_f32_e32 v19, v69, v19
	v_cvt_pk_bf16_f32 v23, v18, v19
	v_lshlrev_b32_e32 v18, 16, v14
	v_mul_f32_e32 v19, 0x3d372713, v18
	v_mul_f32_e32 v19, v19, v18
	v_fma_f32 v19, v19, v18, v18
	v_mul_f32_e32 v19, 0x3f4c422a, v19
	v_add_f32_e32 v19, v19, v19
	v_mul_f32_e32 v19, 0x3fb8aa3b, v19
	v_exp_f32_e32 v19, v19
	ds_write_b128 v111, v[26:29] offset:43520
	ds_write_b128 v112, v[20:23] offset:43520
	v_mul_f32_e32 v18, 0.5, v18
	v_and_b32_e32 v14, 0xffff0000, v14
	v_add_f32_e32 v19, 1.0, v19
	v_div_scale_f32 v20, s[14:15], v19, v19, 2.0
	v_rcp_f32_e32 v21, v20
	s_nop 0
	v_fma_f32 v22, -v20, v21, 1.0
	v_fmac_f32_e32 v21, v22, v21
	v_div_scale_f32 v22, vcc, 2.0, v19, 2.0
	v_mul_f32_e32 v23, v22, v21
	v_fma_f32 v24, -v20, v23, v22
	v_fmac_f32_e32 v23, v24, v21
	v_fma_f32 v20, -v20, v23, v22
	v_div_fmas_f32 v20, v20, v21, v23
	v_div_fixup_f32 v19, v20, v19, 2.0
	v_sub_f32_e32 v19, 1.0, v19
	v_add_f32_e32 v19, 1.0, v19
	v_mul_f32_e32 v18, v18, v19
	v_mul_f32_e32 v19, 0x3d372713, v14
	v_mul_f32_e32 v19, v19, v14
	v_fma_f32 v19, v19, v14, v14
	v_mul_f32_e32 v19, 0x3f4c422a, v19
	v_add_f32_e32 v19, v19, v19
	v_mul_f32_e32 v19, 0x3fb8aa3b, v19
	v_exp_f32_e32 v19, v19
	v_mul_f32_e32 v14, 0.5, v14
	v_add_f32_e32 v19, 1.0, v19
	v_div_scale_f32 v20, s[14:15], v19, v19, 2.0
	v_rcp_f32_e32 v21, v20
	s_nop 0
	v_fma_f32 v22, -v20, v21, 1.0
	v_fmac_f32_e32 v21, v22, v21
	v_div_scale_f32 v22, vcc, 2.0, v19, 2.0
	v_mul_f32_e32 v23, v22, v21
	v_fma_f32 v24, -v20, v23, v22
	v_fmac_f32_e32 v23, v24, v21
	v_fma_f32 v20, -v20, v23, v22
	v_div_fmas_f32 v20, v20, v21, v23
	v_div_fixup_f32 v19, v20, v19, 2.0
	v_sub_f32_e32 v19, 1.0, v19
	v_add_f32_e32 v19, 1.0, v19
	v_mul_f32_e32 v19, v14, v19
	v_lshlrev_b32_e32 v14, 16, v10
	v_mul_f32_e32 v20, 0x3d372713, v14
	v_mul_f32_e32 v20, v20, v14
	v_fma_f32 v20, v20, v14, v14
	v_mul_f32_e32 v20, 0x3f4c422a, v20
	v_add_f32_e32 v20, v20, v20
	v_mul_f32_e32 v20, 0x3fb8aa3b, v20
	v_exp_f32_e32 v20, v20
	v_mul_f32_e32 v14, 0.5, v14
	v_and_b32_e32 v10, 0xffff0000, v10
	v_cvt_pk_bf16_f32 v18, v18, v19
	v_add_f32_e32 v20, 1.0, v20
	v_div_scale_f32 v21, s[14:15], v20, v20, 2.0
	v_rcp_f32_e32 v22, v21
	s_nop 0
	v_fma_f32 v23, -v21, v22, 1.0
	v_fmac_f32_e32 v22, v23, v22
	v_div_scale_f32 v23, vcc, 2.0, v20, 2.0
	v_mul_f32_e32 v24, v23, v22
	v_fma_f32 v25, -v21, v24, v23
	v_fmac_f32_e32 v24, v25, v22
	v_fma_f32 v21, -v21, v24, v23
	v_div_fmas_f32 v21, v21, v22, v24
	v_div_fixup_f32 v20, v21, v20, 2.0
	v_sub_f32_e32 v20, 1.0, v20
	v_add_f32_e32 v20, 1.0, v20
	v_mul_f32_e32 v20, v14, v20
	v_mul_f32_e32 v14, 0x3d372713, v10
	v_mul_f32_e32 v14, v14, v10
	v_fma_f32 v14, v14, v10, v10
	v_mul_f32_e32 v14, 0x3f4c422a, v14
	v_add_f32_e32 v14, v14, v14
	v_mul_f32_e32 v14, 0x3fb8aa3b, v14
	v_exp_f32_e32 v14, v14
	v_mul_f32_e32 v10, 0.5, v10
	v_add_f32_e32 v14, 1.0, v14
	v_div_scale_f32 v21, s[14:15], v14, v14, 2.0
	v_rcp_f32_e32 v22, v21
	s_nop 0
	v_fma_f32 v23, -v21, v22, 1.0
	v_fmac_f32_e32 v22, v23, v22
	v_div_scale_f32 v23, vcc, 2.0, v14, 2.0
	v_mul_f32_e32 v24, v23, v22
	v_fma_f32 v25, -v21, v24, v23
	v_fmac_f32_e32 v24, v25, v22
	v_fma_f32 v21, -v21, v24, v23
	v_div_fmas_f32 v21, v21, v22, v24
	v_div_fixup_f32 v14, v21, v14, 2.0
	v_sub_f32_e32 v14, 1.0, v14
	v_add_f32_e32 v14, 1.0, v14
	v_mul_f32_e32 v21, v10, v14
	v_lshlrev_b32_e32 v10, 16, v15
	v_mul_f32_e32 v14, 0x3d372713, v10
	v_mul_f32_e32 v14, v14, v10
	v_fma_f32 v14, v14, v10, v10
	v_mul_f32_e32 v14, 0x3f4c422a, v14
	v_add_f32_e32 v14, v14, v14
	v_mul_f32_e32 v14, 0x3fb8aa3b, v14
	v_exp_f32_e32 v14, v14
	v_mul_f32_e32 v10, 0.5, v10
	v_add_f32_e32 v14, 1.0, v14
	v_div_scale_f32 v22, s[14:15], v14, v14, 2.0
	v_rcp_f32_e32 v23, v22
	s_nop 0
	v_fma_f32 v24, -v22, v23, 1.0
	v_fmac_f32_e32 v23, v24, v23
	v_div_scale_f32 v24, vcc, 2.0, v14, 2.0
	v_mul_f32_e32 v25, v24, v23
	v_fma_f32 v26, -v22, v25, v24
	v_fmac_f32_e32 v25, v26, v23
	v_fma_f32 v22, -v22, v25, v24
	v_div_fmas_f32 v22, v22, v23, v25
	v_div_fixup_f32 v14, v22, v14, 2.0
	v_sub_f32_e32 v14, 1.0, v14
	v_add_f32_e32 v14, 1.0, v14
	v_mul_f32_e32 v22, v10, v14
	v_and_b32_e32 v10, 0xffff0000, v15
	v_mul_f32_e32 v14, 0x3d372713, v10
	v_mul_f32_e32 v14, v14, v10
	v_fma_f32 v14, v14, v10, v10
	v_mul_f32_e32 v14, 0x3f4c422a, v14
	v_add_f32_e32 v14, v14, v14
	v_mul_f32_e32 v14, 0x3fb8aa3b, v14
	v_exp_f32_e32 v14, v14
	v_mul_f32_e32 v10, 0.5, v10
	v_add_f32_e32 v14, 1.0, v14
	v_div_scale_f32 v15, s[14:15], v14, v14, 2.0
	v_rcp_f32_e32 v23, v15
	s_nop 0
	v_fma_f32 v24, -v15, v23, 1.0
	v_fmac_f32_e32 v23, v24, v23
	v_div_scale_f32 v24, vcc, 2.0, v14, 2.0
	v_mul_f32_e32 v25, v24, v23
	v_fma_f32 v26, -v15, v25, v24
	v_fmac_f32_e32 v25, v26, v23
	v_fma_f32 v15, -v15, v25, v24
	v_div_fmas_f32 v15, v15, v23, v25
	v_div_fixup_f32 v14, v15, v14, 2.0
	v_sub_f32_e32 v14, 1.0, v14
	v_add_f32_e32 v14, 1.0, v14
	v_mul_f32_e32 v23, v10, v14
	v_lshlrev_b32_e32 v10, 16, v16
	v_mul_f32_e32 v14, 0x3d372713, v10
	v_mul_f32_e32 v14, v14, v10
	v_fma_f32 v14, v14, v10, v10
	v_mul_f32_e32 v14, 0x3f4c422a, v14
	v_add_f32_e32 v14, v14, v14
	v_mul_f32_e32 v14, 0x3fb8aa3b, v14
	v_exp_f32_e32 v14, v14
	v_mul_f32_e32 v10, 0.5, v10
	v_add_f32_e32 v14, 1.0, v14
	v_div_scale_f32 v15, s[14:15], v14, v14, 2.0
	v_rcp_f32_e32 v24, v15
	s_nop 0
	v_fma_f32 v25, -v15, v24, 1.0
	v_fmac_f32_e32 v24, v25, v24
	v_div_scale_f32 v25, vcc, 2.0, v14, 2.0
	v_mul_f32_e32 v26, v25, v24
	v_fma_f32 v27, -v15, v26, v25
	v_fmac_f32_e32 v26, v27, v24
	v_fma_f32 v15, -v15, v26, v25
	v_div_fmas_f32 v15, v15, v24, v26
	v_div_fixup_f32 v14, v15, v14, 2.0
	v_sub_f32_e32 v14, 1.0, v14
	v_add_f32_e32 v14, 1.0, v14
	v_mul_f32_e32 v24, v10, v14
	v_and_b32_e32 v10, 0xffff0000, v16
	v_mul_f32_e32 v14, 0x3d372713, v10
	v_mul_f32_e32 v14, v14, v10
	v_fma_f32 v14, v14, v10, v10
	v_mul_f32_e32 v14, 0x3f4c422a, v14
	v_add_f32_e32 v14, v14, v14
	v_mul_f32_e32 v14, 0x3fb8aa3b, v14
	v_exp_f32_e32 v14, v14
	v_mul_f32_e32 v10, 0.5, v10
	v_add_f32_e32 v14, 1.0, v14
	v_div_scale_f32 v15, s[14:15], v14, v14, 2.0
	v_rcp_f32_e32 v16, v15
	s_nop 0
	v_fma_f32 v25, -v15, v16, 1.0
	v_fmac_f32_e32 v16, v25, v16
	v_div_scale_f32 v25, vcc, 2.0, v14, 2.0
	v_mul_f32_e32 v26, v25, v16
	v_fma_f32 v27, -v15, v26, v25
	v_fmac_f32_e32 v26, v27, v16
	v_fma_f32 v15, -v15, v26, v25
	v_div_fmas_f32 v15, v15, v16, v26
	v_div_fixup_f32 v14, v15, v14, 2.0
	v_sub_f32_e32 v14, 1.0, v14
	v_add_f32_e32 v14, 1.0, v14
	v_mul_f32_e32 v16, v10, v14
	v_lshlrev_b32_e32 v10, 16, v17
	v_mul_f32_e32 v14, 0x3d372713, v10
	v_mul_f32_e32 v14, v14, v10
	v_fma_f32 v14, v14, v10, v10
	v_mul_f32_e32 v14, 0x3f4c422a, v14
	v_add_f32_e32 v14, v14, v14
	v_mul_f32_e32 v14, 0x3fb8aa3b, v14
	v_exp_f32_e32 v14, v14
	v_mul_f32_e32 v10, 0.5, v10
	v_add_f32_e32 v14, 1.0, v14
	v_div_scale_f32 v15, s[14:15], v14, v14, 2.0
	v_rcp_f32_e32 v25, v15
	s_nop 0
	v_fma_f32 v26, -v15, v25, 1.0
	v_fmac_f32_e32 v25, v26, v25
	v_div_scale_f32 v26, vcc, 2.0, v14, 2.0
	v_mul_f32_e32 v27, v26, v25
	v_fma_f32 v28, -v15, v27, v26
	v_fmac_f32_e32 v27, v28, v25
	v_fma_f32 v15, -v15, v27, v26
	v_div_fmas_f32 v15, v15, v25, v27
	v_div_fixup_f32 v14, v15, v14, 2.0
	v_sub_f32_e32 v14, 1.0, v14
	v_add_f32_e32 v14, 1.0, v14
	v_mul_f32_e32 v25, v10, v14
	v_and_b32_e32 v10, 0xffff0000, v17
	v_mul_f32_e32 v14, 0x3d372713, v10
	v_mul_f32_e32 v14, v14, v10
	v_fma_f32 v14, v14, v10, v10
	v_mul_f32_e32 v14, 0x3f4c422a, v14
	v_add_f32_e32 v14, v14, v14
	v_mul_f32_e32 v14, 0x3fb8aa3b, v14
	v_exp_f32_e32 v14, v14
	v_mul_f32_e32 v10, 0.5, v10
	v_add_f32_e32 v14, 1.0, v14
	v_div_scale_f32 v15, s[14:15], v14, v14, 2.0
	v_rcp_f32_e32 v17, v15
	s_nop 0
	v_fma_f32 v26, -v15, v17, 1.0
	v_fmac_f32_e32 v17, v26, v17
	v_div_scale_f32 v26, vcc, 2.0, v14, 2.0
	v_mul_f32_e32 v27, v26, v17
	v_fma_f32 v28, -v15, v27, v26
	v_fmac_f32_e32 v27, v28, v17
	v_fma_f32 v15, -v15, v27, v26
	v_div_fmas_f32 v15, v15, v17, v27
	v_div_fixup_f32 v14, v15, v14, 2.0
	v_sub_f32_e32 v14, 1.0, v14
	v_add_f32_e32 v14, 1.0, v14
	v_mul_f32_e32 v17, v10, v14
	v_and_b32_e32 v10, 0xffff0000, v11
	v_lshlrev_b32_e32 v11, 16, v11
	v_mul_f32_e32 v14, 0x3d372713, v11
	v_mul_f32_e32 v14, v14, v11
	v_mov_b32_e32 v15, v11
	v_fmac_f32_e32 v15, v14, v15
	v_mul_f32_e32 v14, 0x3f4c422a, v15
	v_add_f32_e32 v14, v14, v14
	v_mul_f32_e32 v14, 0x3fb8aa3b, v14
	v_exp_f32_e32 v15, v14
	v_mul_f32_e32 v14, 0x3d372713, v10
	v_mul_f32_e32 v14, v14, v10
	v_mov_b32_e32 v27, v10
	v_fmac_f32_e32 v27, v14, v27
	v_mul_f32_e32 v14, 0x3f4c422a, v27
	v_add_f32_e32 v14, v14, v14
	v_mul_f32_e32 v14, 0x3fb8aa3b, v14
	v_exp_f32_e32 v14, v14
	v_pk_mul_f32 v[10:11], v[10:11], 0.5 op_sel_hi:[1,0]
	v_mul_f32_e32 v26, v21, v21
	v_fmac_f32_e32 v26, v20, v20
	v_pk_add_f32 v[14:15], v[14:15], 1.0 op_sel_hi:[1,0]
	s_nop 0
	v_div_scale_f32 v27, s[14:15], v15, v15, 2.0
	v_rcp_f32_e32 v28, v27
	s_nop 0
	v_fma_f32 v29, -v27, v28, 1.0
	v_fmac_f32_e32 v28, v29, v28
	v_div_scale_f32 v29, vcc, 2.0, v15, 2.0
	v_mul_f32_e32 v30, v29, v28
	v_fma_f32 v31, -v27, v30, v29
	v_fmac_f32_e32 v30, v31, v28
	v_fma_f32 v27, -v27, v30, v29
	v_div_fmas_f32 v27, v27, v28, v30
	v_div_fixup_f32 v15, v27, v15, 2.0
	v_div_scale_f32 v27, s[14:15], v14, v14, 2.0
	v_rcp_f32_e32 v28, v27
	s_nop 0
	v_fma_f32 v29, -v27, v28, 1.0
	v_fmac_f32_e32 v28, v29, v28
	v_div_scale_f32 v29, vcc, 2.0, v14, 2.0
	v_mul_f32_e32 v30, v29, v28
	v_fma_f32 v31, -v27, v30, v29
	v_fmac_f32_e32 v30, v31, v28
	v_fma_f32 v27, -v27, v30, v29
	v_div_fmas_f32 v27, v27, v28, v30
	v_div_fixup_f32 v14, v27, v14, 2.0
	v_pk_add_f32 v[14:15], v[14:15], 1.0 op_sel_hi:[1,0] neg_lo:[1,0] neg_hi:[1,0]
	s_nop 0
	v_pk_add_f32 v[14:15], v[14:15], 1.0 op_sel_hi:[1,0]
	s_nop 0
	v_pk_mul_f32 v[10:11], v[10:11], v[14:15]
	s_nop 0
	v_pk_mul_f32 v[14:15], v[10:11], v[10:11]
	s_nop 0
	v_add_f32_e32 v15, v15, v26
	v_add_f32_e32 v28, v14, v15
	v_lshlrev_b32_e32 v15, 16, v12
	v_and_b32_e32 v14, 0xffff0000, v12
	v_mul_f32_e32 v12, 0x3d372713, v15
	v_mul_f32_e32 v12, v12, v15
	v_mov_b32_e32 v26, v15
	v_fmac_f32_e32 v26, v12, v26
	v_mul_f32_e32 v12, 0x3f4c422a, v26
	v_add_f32_e32 v12, v12, v12
	v_mul_f32_e32 v12, 0x3fb8aa3b, v12
	v_exp_f32_e32 v27, v12
	v_mul_f32_e32 v12, 0x3d372713, v14
	v_mul_f32_e32 v12, v12, v14
	v_mov_b32_e32 v26, v14
	v_fmac_f32_e32 v26, v12, v26
	v_mul_f32_e32 v12, 0x3f4c422a, v26
	v_add_f32_e32 v12, v12, v12
	v_mul_f32_e32 v12, 0x3fb8aa3b, v12
	v_exp_f32_e32 v26, v12
	v_pk_mul_f32 v[14:15], v[14:15], 0.5 op_sel_hi:[1,0]
	v_pk_add_f32 v[26:27], v[26:27], 1.0 op_sel_hi:[1,0]
	s_nop 0
	v_div_scale_f32 v12, s[14:15], v27, v27, 2.0
	v_rcp_f32_e32 v29, v12
	s_nop 0
	v_fma_f32 v30, -v12, v29, 1.0
	v_fmac_f32_e32 v29, v30, v29
	v_div_scale_f32 v30, vcc, 2.0, v27, 2.0
	v_mul_f32_e32 v31, v30, v29
	v_fma_f32 v32, -v12, v31, v30
	v_fmac_f32_e32 v31, v32, v29
	v_fma_f32 v12, -v12, v31, v30
	v_div_fmas_f32 v12, v12, v29, v31
	v_div_fixup_f32 v27, v12, v27, 2.0
	v_div_scale_f32 v12, s[14:15], v26, v26, 2.0
	v_rcp_f32_e32 v29, v12
	s_nop 0
	v_fma_f32 v30, -v12, v29, 1.0
	v_fmac_f32_e32 v29, v30, v29
	v_div_scale_f32 v30, vcc, 2.0, v26, 2.0
	v_mul_f32_e32 v31, v30, v29
	v_fma_f32 v32, -v12, v31, v30
	v_fmac_f32_e32 v31, v32, v29
	v_fma_f32 v12, -v12, v31, v30
	v_div_fmas_f32 v12, v12, v29, v31
	v_div_fixup_f32 v26, v12, v26, 2.0
	v_pk_add_f32 v[26:27], v[26:27], 1.0 op_sel_hi:[1,0] neg_lo:[1,0] neg_hi:[1,0]
	s_nop 0
	v_pk_add_f32 v[26:27], v[26:27], 1.0 op_sel_hi:[1,0]
	s_nop 0
	v_pk_mul_f32 v[14:15], v[14:15], v[26:27]
	s_nop 0
	v_pk_mul_f32 v[26:27], v[14:15], v[14:15]
	s_nop 0
	v_add_f32_e32 v12, v27, v28
	v_add_f32_e32 v28, v26, v12
	v_and_b32_e32 v12, 0xffff0000, v13
	v_lshlrev_b32_e32 v13, 16, v13
	v_mul_f32_e32 v26, 0x3d372713, v13
	v_mul_f32_e32 v26, v26, v13
	v_mov_b32_e32 v27, v13
	v_fmac_f32_e32 v27, v26, v27
	v_mul_f32_e32 v26, 0x3f4c422a, v27
	v_add_f32_e32 v26, v26, v26
	v_mul_f32_e32 v26, 0x3fb8aa3b, v26
	v_exp_f32_e32 v27, v26
	v_mul_f32_e32 v26, 0x3d372713, v12
	v_mul_f32_e32 v26, v26, v12
	v_mov_b32_e32 v29, v12
	v_fmac_f32_e32 v29, v26, v29
	v_mul_f32_e32 v26, 0x3f4c422a, v29
	v_add_f32_e32 v26, v26, v26
	v_mul_f32_e32 v26, 0x3fb8aa3b, v26
	v_exp_f32_e32 v26, v26
	v_pk_mul_f32 v[12:13], v[12:13], 0.5 op_sel_hi:[1,0]
	v_pk_add_f32 v[26:27], v[26:27], 1.0 op_sel_hi:[1,0]
	s_nop 0
	v_div_scale_f32 v29, s[14:15], v27, v27, 2.0
	v_rcp_f32_e32 v30, v29
	s_nop 0
	v_fma_f32 v31, -v29, v30, 1.0
	v_fmac_f32_e32 v30, v31, v30
	v_div_scale_f32 v31, vcc, 2.0, v27, 2.0
	v_mul_f32_e32 v32, v31, v30
	v_fma_f32 v33, -v29, v32, v31
	v_fmac_f32_e32 v32, v33, v30
	v_fma_f32 v29, -v29, v32, v31
	v_div_fmas_f32 v29, v29, v30, v32
	v_div_fixup_f32 v27, v29, v27, 2.0
	v_div_scale_f32 v29, s[14:15], v26, v26, 2.0
	v_rcp_f32_e32 v30, v29
	s_nop 0
	v_fma_f32 v31, -v29, v30, 1.0
	v_fmac_f32_e32 v30, v31, v30
	v_div_scale_f32 v31, vcc, 2.0, v26, 2.0
	v_mul_f32_e32 v32, v31, v30
	v_fma_f32 v33, -v29, v32, v31
	v_fmac_f32_e32 v32, v33, v30
	v_fma_f32 v29, -v29, v32, v31
	v_div_fmas_f32 v29, v29, v30, v32
	v_div_fixup_f32 v26, v29, v26, 2.0
	v_pk_add_f32 v[26:27], v[26:27], 1.0 op_sel_hi:[1,0] neg_lo:[1,0] neg_hi:[1,0]
	s_nop 0
	v_pk_add_f32 v[26:27], v[26:27], 1.0 op_sel_hi:[1,0]
	s_nop 0
	v_pk_mul_f32 v[26:27], v[12:13], v[26:27]
	s_nop 0
	v_pk_mul_f32 v[12:13], v[26:27], v[26:27]
	s_nop 0
	v_add_f32_e32 v13, v13, v28
	v_add_f32_e32 v12, v12, v13
	s_nop 1
	v_mov_b32_dpp v13, v12 quad_perm:[1,0,3,2] row_mask:0xf bank_mask:0xf
	s_waitcnt lgkmcnt(0)
	v_add_f32_e32 v12, v12, v13
	s_nop 1
	v_mov_b32_dpp v13, v12 quad_perm:[2,3,0,1] row_mask:0xf bank_mask:0xf
	s_waitcnt lgkmcnt(0)
	v_add_f32_e32 v12, v12, v13
	s_nop 1
	v_mov_b32_dpp v13, v12 row_half_mirror row_mask:0xf bank_mask:0xf
	s_waitcnt lgkmcnt(0)
	v_add_f32_e32 v12, v12, v13
	s_nop 1
	v_mov_b32_dpp v13, v12 row_mirror row_mask:0xf bank_mask:0xf
	s_waitcnt lgkmcnt(0)
	v_add_f32_e32 v12, v12, v13
	ds_bpermute_b32 v13, v110, v12
	s_waitcnt lgkmcnt(0)
	v_add_f32_e32 v12, v12, v13
	v_fmamk_f32 v12, v12, 0x3b800000, v243
	v_cmp_gt_f32_e32 vcc, s3, v12
	v_mul_f32_e32 v13, 0x4b800000, v12
	s_nop 0
	v_cndmask_b32_e32 v12, v12, v13, vcc
	v_rsq_f32_e32 v12, v12
	s_nop 0
	v_mul_f32_e32 v13, 0x45800000, v12
	v_cndmask_b32_e32 v28, v12, v13, vcc
	v_mul_f32_e32 v12, v20, v28
	v_mul_f32_e32 v13, v21, v28
	v_mul_f32_e32 v10, v10, v28
	v_mul_f32_e32 v12, v70, v12
	v_mul_f32_e32 v13, v71, v13
	v_mul_f32_e32 v11, v11, v28
	v_mul_f32_e32 v10, v73, v10
	v_cvt_pk_bf16_f32 v12, v12, v13
	v_cvt_pk_bf16_f32 v19, v22, v23
	v_mul_f32_e32 v11, v72, v11
	v_cvt_pk_bf16_f32 v13, v11, v10
	v_mul_f32_e32 v10, v15, v28
	v_mul_f32_e32 v10, v66, v10
	v_mul_f32_e32 v11, v14, v28
	v_cvt_pk_bf16_f32 v20, v24, v16
	v_mul_f32_e32 v11, v67, v11
	v_cvt_pk_bf16_f32 v14, v10, v11
	v_mul_f32_e32 v10, v27, v28
	v_mul_f32_e32 v10, v68, v10
	v_mul_f32_e32 v11, v26, v28
	v_cvt_pk_bf16_f32 v21, v25, v17
	v_mul_f32_e32 v11, v69, v11
	v_cvt_pk_bf16_f32 v15, v10, v11
	v_lshlrev_b32_e32 v10, 16, v6
	v_mul_f32_e32 v11, 0x3d372713, v10
	v_mul_f32_e32 v11, v11, v10
	v_fma_f32 v11, v11, v10, v10
	v_mul_f32_e32 v11, 0x3f4c422a, v11
	v_add_f32_e32 v11, v11, v11
	v_mul_f32_e32 v11, 0x3fb8aa3b, v11
	v_exp_f32_e32 v11, v11
	ds_write_b128 v111, v[18:21] offset:52224
	ds_write_b128 v112, v[12:15] offset:52224
	v_mul_f32_e32 v10, 0.5, v10
	v_and_b32_e32 v6, 0xffff0000, v6
	v_add_f32_e32 v11, 1.0, v11
	v_div_scale_f32 v12, s[14:15], v11, v11, 2.0
	v_rcp_f32_e32 v13, v12
	s_nop 0
	v_fma_f32 v14, -v12, v13, 1.0
	v_fmac_f32_e32 v13, v14, v13
	v_div_scale_f32 v14, vcc, 2.0, v11, 2.0
	v_mul_f32_e32 v15, v14, v13
	v_fma_f32 v16, -v12, v15, v14
	v_fmac_f32_e32 v15, v16, v13
	v_fma_f32 v12, -v12, v15, v14
	v_div_fmas_f32 v12, v12, v13, v15
	v_div_fixup_f32 v11, v12, v11, 2.0
	v_sub_f32_e32 v11, 1.0, v11
	v_add_f32_e32 v11, 1.0, v11
	v_mul_f32_e32 v10, v10, v11
	v_mul_f32_e32 v11, 0x3d372713, v6
	v_mul_f32_e32 v11, v11, v6
	v_fma_f32 v11, v11, v6, v6
	v_mul_f32_e32 v11, 0x3f4c422a, v11
	v_add_f32_e32 v11, v11, v11
	v_mul_f32_e32 v11, 0x3fb8aa3b, v11
	v_exp_f32_e32 v11, v11
	v_mul_f32_e32 v6, 0.5, v6
	v_add_f32_e32 v11, 1.0, v11
	v_div_scale_f32 v12, s[14:15], v11, v11, 2.0
	v_rcp_f32_e32 v13, v12
	s_nop 0
	v_fma_f32 v14, -v12, v13, 1.0
	v_fmac_f32_e32 v13, v14, v13
	v_div_scale_f32 v14, vcc, 2.0, v11, 2.0
	v_mul_f32_e32 v15, v14, v13
	v_fma_f32 v16, -v12, v15, v14
	v_fmac_f32_e32 v15, v16, v13
	v_fma_f32 v12, -v12, v15, v14
	v_div_fmas_f32 v12, v12, v13, v15
	v_div_fixup_f32 v11, v12, v11, 2.0
	v_sub_f32_e32 v11, 1.0, v11
	v_add_f32_e32 v11, 1.0, v11
	v_mul_f32_e32 v11, v6, v11
	v_lshlrev_b32_e32 v6, 16, v2
	v_mul_f32_e32 v12, 0x3d372713, v6
	v_mul_f32_e32 v12, v12, v6
	v_fma_f32 v12, v12, v6, v6
	v_mul_f32_e32 v12, 0x3f4c422a, v12
	v_add_f32_e32 v12, v12, v12
	v_mul_f32_e32 v12, 0x3fb8aa3b, v12
	v_exp_f32_e32 v12, v12
	v_mul_f32_e32 v6, 0.5, v6
	v_and_b32_e32 v2, 0xffff0000, v2
	v_cvt_pk_bf16_f32 v10, v10, v11
	v_add_f32_e32 v12, 1.0, v12
	v_div_scale_f32 v13, s[14:15], v12, v12, 2.0
	v_rcp_f32_e32 v14, v13
	s_nop 0
	v_fma_f32 v15, -v13, v14, 1.0
	v_fmac_f32_e32 v14, v15, v14
	v_div_scale_f32 v15, vcc, 2.0, v12, 2.0
	v_mul_f32_e32 v16, v15, v14
	v_fma_f32 v17, -v13, v16, v15
	v_fmac_f32_e32 v16, v17, v14
	v_fma_f32 v13, -v13, v16, v15
	v_div_fmas_f32 v13, v13, v14, v16
	v_div_fixup_f32 v12, v13, v12, 2.0
	v_sub_f32_e32 v12, 1.0, v12
	v_add_f32_e32 v12, 1.0, v12
	v_mul_f32_e32 v12, v6, v12
	v_mul_f32_e32 v6, 0x3d372713, v2
	v_mul_f32_e32 v6, v6, v2
	v_fma_f32 v6, v6, v2, v2
	v_mul_f32_e32 v6, 0x3f4c422a, v6
	v_add_f32_e32 v6, v6, v6
	v_mul_f32_e32 v6, 0x3fb8aa3b, v6
	v_exp_f32_e32 v6, v6
	v_mul_f32_e32 v2, 0.5, v2
	v_add_f32_e32 v6, 1.0, v6
	v_div_scale_f32 v13, s[14:15], v6, v6, 2.0
	v_rcp_f32_e32 v14, v13
	s_nop 0
	v_fma_f32 v15, -v13, v14, 1.0
	v_fmac_f32_e32 v14, v15, v14
	v_div_scale_f32 v15, vcc, 2.0, v6, 2.0
	v_mul_f32_e32 v16, v15, v14
	v_fma_f32 v17, -v13, v16, v15
	v_fmac_f32_e32 v16, v17, v14
	v_fma_f32 v13, -v13, v16, v15
	v_div_fmas_f32 v13, v13, v14, v16
	v_div_fixup_f32 v6, v13, v6, 2.0
	v_sub_f32_e32 v6, 1.0, v6
	v_add_f32_e32 v6, 1.0, v6
	v_mul_f32_e32 v13, v2, v6
	v_lshlrev_b32_e32 v2, 16, v7
	v_mul_f32_e32 v6, 0x3d372713, v2
	v_mul_f32_e32 v6, v6, v2
	v_fma_f32 v6, v6, v2, v2
	v_mul_f32_e32 v6, 0x3f4c422a, v6
	v_add_f32_e32 v6, v6, v6
	v_mul_f32_e32 v6, 0x3fb8aa3b, v6
	v_exp_f32_e32 v6, v6
	v_mul_f32_e32 v2, 0.5, v2
	v_add_f32_e32 v6, 1.0, v6
	v_div_scale_f32 v14, s[14:15], v6, v6, 2.0
	v_rcp_f32_e32 v15, v14
	s_nop 0
	v_fma_f32 v16, -v14, v15, 1.0
	v_fmac_f32_e32 v15, v16, v15
	v_div_scale_f32 v16, vcc, 2.0, v6, 2.0
	v_mul_f32_e32 v17, v16, v15
	v_fma_f32 v18, -v14, v17, v16
	v_fmac_f32_e32 v17, v18, v15
	v_fma_f32 v14, -v14, v17, v16
	v_div_fmas_f32 v14, v14, v15, v17
	v_div_fixup_f32 v6, v14, v6, 2.0
	v_sub_f32_e32 v6, 1.0, v6
	v_add_f32_e32 v6, 1.0, v6
	v_mul_f32_e32 v14, v2, v6
	v_and_b32_e32 v2, 0xffff0000, v7
	v_mul_f32_e32 v6, 0x3d372713, v2
	v_mul_f32_e32 v6, v6, v2
	v_fma_f32 v6, v6, v2, v2
	v_mul_f32_e32 v6, 0x3f4c422a, v6
	v_add_f32_e32 v6, v6, v6
	v_mul_f32_e32 v6, 0x3fb8aa3b, v6
	v_exp_f32_e32 v6, v6
	v_mul_f32_e32 v2, 0.5, v2
	v_add_f32_e32 v6, 1.0, v6
	v_div_scale_f32 v7, s[14:15], v6, v6, 2.0
	v_rcp_f32_e32 v15, v7
	s_nop 0
	v_fma_f32 v16, -v7, v15, 1.0
	v_fmac_f32_e32 v15, v16, v15
	v_div_scale_f32 v16, vcc, 2.0, v6, 2.0
	v_mul_f32_e32 v17, v16, v15
	v_fma_f32 v18, -v7, v17, v16
	v_fmac_f32_e32 v17, v18, v15
	v_fma_f32 v7, -v7, v17, v16
	v_div_fmas_f32 v7, v7, v15, v17
	v_div_fixup_f32 v6, v7, v6, 2.0
	v_sub_f32_e32 v6, 1.0, v6
	v_add_f32_e32 v6, 1.0, v6
	v_mul_f32_e32 v15, v2, v6
	v_lshlrev_b32_e32 v2, 16, v8
	v_mul_f32_e32 v6, 0x3d372713, v2
	v_mul_f32_e32 v6, v6, v2
	v_fma_f32 v6, v6, v2, v2
	v_mul_f32_e32 v6, 0x3f4c422a, v6
	v_add_f32_e32 v6, v6, v6
	v_mul_f32_e32 v6, 0x3fb8aa3b, v6
	v_exp_f32_e32 v6, v6
	v_mul_f32_e32 v2, 0.5, v2
	v_add_f32_e32 v6, 1.0, v6
	v_div_scale_f32 v7, s[14:15], v6, v6, 2.0
	v_rcp_f32_e32 v16, v7
	s_nop 0
	v_fma_f32 v17, -v7, v16, 1.0
	v_fmac_f32_e32 v16, v17, v16
	v_div_scale_f32 v17, vcc, 2.0, v6, 2.0
	v_mul_f32_e32 v18, v17, v16
	v_fma_f32 v19, -v7, v18, v17
	v_fmac_f32_e32 v18, v19, v16
	v_fma_f32 v7, -v7, v18, v17
	v_div_fmas_f32 v7, v7, v16, v18
	v_div_fixup_f32 v6, v7, v6, 2.0
	v_sub_f32_e32 v6, 1.0, v6
	v_add_f32_e32 v6, 1.0, v6
	v_mul_f32_e32 v16, v2, v6
	v_and_b32_e32 v2, 0xffff0000, v8
	v_mul_f32_e32 v6, 0x3d372713, v2
	v_mul_f32_e32 v6, v6, v2
	v_fma_f32 v6, v6, v2, v2
	v_mul_f32_e32 v6, 0x3f4c422a, v6
	v_add_f32_e32 v6, v6, v6
	v_mul_f32_e32 v6, 0x3fb8aa3b, v6
	v_exp_f32_e32 v6, v6
	v_mul_f32_e32 v2, 0.5, v2
	v_add_f32_e32 v6, 1.0, v6
	v_div_scale_f32 v7, s[14:15], v6, v6, 2.0
	v_rcp_f32_e32 v8, v7
	s_nop 0
	v_fma_f32 v17, -v7, v8, 1.0
	v_fmac_f32_e32 v8, v17, v8
	v_div_scale_f32 v17, vcc, 2.0, v6, 2.0
	v_mul_f32_e32 v18, v17, v8
	v_fma_f32 v19, -v7, v18, v17
	v_fmac_f32_e32 v18, v19, v8
	v_fma_f32 v7, -v7, v18, v17
	v_div_fmas_f32 v7, v7, v8, v18
	v_div_fixup_f32 v6, v7, v6, 2.0
	v_sub_f32_e32 v6, 1.0, v6
	v_add_f32_e32 v6, 1.0, v6
	v_mul_f32_e32 v8, v2, v6
	v_lshlrev_b32_e32 v2, 16, v9
	v_mul_f32_e32 v6, 0x3d372713, v2
	v_mul_f32_e32 v6, v6, v2
	v_fma_f32 v6, v6, v2, v2
	v_mul_f32_e32 v6, 0x3f4c422a, v6
	v_add_f32_e32 v6, v6, v6
	v_mul_f32_e32 v6, 0x3fb8aa3b, v6
	v_exp_f32_e32 v6, v6
	v_mul_f32_e32 v2, 0.5, v2
	v_add_f32_e32 v6, 1.0, v6
	v_div_scale_f32 v7, s[14:15], v6, v6, 2.0
	v_rcp_f32_e32 v17, v7
	s_nop 0
	v_fma_f32 v18, -v7, v17, 1.0
	v_fmac_f32_e32 v17, v18, v17
	v_div_scale_f32 v18, vcc, 2.0, v6, 2.0
	v_mul_f32_e32 v19, v18, v17
	v_fma_f32 v20, -v7, v19, v18
	v_fmac_f32_e32 v19, v20, v17
	v_fma_f32 v7, -v7, v19, v18
	v_div_fmas_f32 v7, v7, v17, v19
	v_div_fixup_f32 v6, v7, v6, 2.0
	v_sub_f32_e32 v6, 1.0, v6
	v_add_f32_e32 v6, 1.0, v6
	v_mul_f32_e32 v17, v2, v6
	v_and_b32_e32 v2, 0xffff0000, v9
	v_mul_f32_e32 v6, 0x3d372713, v2
	v_mul_f32_e32 v6, v6, v2
	v_fma_f32 v6, v6, v2, v2
	v_mul_f32_e32 v6, 0x3f4c422a, v6
	v_add_f32_e32 v6, v6, v6
	v_mul_f32_e32 v6, 0x3fb8aa3b, v6
	v_exp_f32_e32 v6, v6
	v_mul_f32_e32 v2, 0.5, v2
	v_add_f32_e32 v6, 1.0, v6
	v_div_scale_f32 v7, s[14:15], v6, v6, 2.0
	v_rcp_f32_e32 v9, v7
	s_nop 0
	v_fma_f32 v18, -v7, v9, 1.0
	v_fmac_f32_e32 v9, v18, v9
	v_div_scale_f32 v18, vcc, 2.0, v6, 2.0
	v_mul_f32_e32 v19, v18, v9
	v_fma_f32 v20, -v7, v19, v18
	v_fmac_f32_e32 v19, v20, v9
	v_fma_f32 v7, -v7, v19, v18
	v_div_fmas_f32 v7, v7, v9, v19
	v_div_fixup_f32 v6, v7, v6, 2.0
	v_sub_f32_e32 v6, 1.0, v6
	v_add_f32_e32 v6, 1.0, v6
	v_mul_f32_e32 v9, v2, v6
	v_and_b32_e32 v2, 0xffff0000, v3
	v_lshlrev_b32_e32 v3, 16, v3
	v_mul_f32_e32 v6, 0x3d372713, v3
	v_mul_f32_e32 v6, v6, v3
	v_mov_b32_e32 v7, v3
	v_fmac_f32_e32 v7, v6, v7
	v_mul_f32_e32 v6, 0x3f4c422a, v7
	v_add_f32_e32 v6, v6, v6
	v_mul_f32_e32 v6, 0x3fb8aa3b, v6
	v_exp_f32_e32 v7, v6
	v_mul_f32_e32 v6, 0x3d372713, v2
	v_mul_f32_e32 v6, v6, v2
	v_mov_b32_e32 v19, v2
	v_fmac_f32_e32 v19, v6, v19
	v_mul_f32_e32 v6, 0x3f4c422a, v19
	v_add_f32_e32 v6, v6, v6
	v_mul_f32_e32 v6, 0x3fb8aa3b, v6
	v_exp_f32_e32 v6, v6
	v_pk_mul_f32 v[2:3], v[2:3], 0.5 op_sel_hi:[1,0]
	v_mul_f32_e32 v18, v13, v13
	v_fmac_f32_e32 v18, v12, v12
	v_pk_add_f32 v[6:7], v[6:7], 1.0 op_sel_hi:[1,0]
	s_nop 0
	v_div_scale_f32 v19, s[14:15], v7, v7, 2.0
	v_rcp_f32_e32 v20, v19
	s_nop 0
	v_fma_f32 v21, -v19, v20, 1.0
	v_fmac_f32_e32 v20, v21, v20
	v_div_scale_f32 v21, vcc, 2.0, v7, 2.0
	v_mul_f32_e32 v22, v21, v20
	v_fma_f32 v23, -v19, v22, v21
	v_fmac_f32_e32 v22, v23, v20
	v_fma_f32 v19, -v19, v22, v21
	v_div_fmas_f32 v19, v19, v20, v22
	v_div_fixup_f32 v7, v19, v7, 2.0
	v_div_scale_f32 v19, s[14:15], v6, v6, 2.0
	v_rcp_f32_e32 v20, v19
	s_nop 0
	v_fma_f32 v21, -v19, v20, 1.0
	v_fmac_f32_e32 v20, v21, v20
	v_div_scale_f32 v21, vcc, 2.0, v6, 2.0
	v_mul_f32_e32 v22, v21, v20
	v_fma_f32 v23, -v19, v22, v21
	v_fmac_f32_e32 v22, v23, v20
	v_fma_f32 v19, -v19, v22, v21
	v_div_fmas_f32 v19, v19, v20, v22
	v_div_fixup_f32 v6, v19, v6, 2.0
	v_pk_add_f32 v[6:7], v[6:7], 1.0 op_sel_hi:[1,0] neg_lo:[1,0] neg_hi:[1,0]
	s_nop 0
	v_pk_add_f32 v[6:7], v[6:7], 1.0 op_sel_hi:[1,0]
	s_nop 0
	v_pk_mul_f32 v[2:3], v[2:3], v[6:7]
	s_nop 0
	v_pk_mul_f32 v[6:7], v[2:3], v[2:3]
	s_nop 0
	v_add_f32_e32 v7, v7, v18
	v_add_f32_e32 v20, v6, v7
	v_lshlrev_b32_e32 v7, 16, v4
	v_and_b32_e32 v6, 0xffff0000, v4
	v_mul_f32_e32 v4, 0x3d372713, v7
	v_mul_f32_e32 v4, v4, v7
	v_mov_b32_e32 v18, v7
	v_fmac_f32_e32 v18, v4, v18
	v_mul_f32_e32 v4, 0x3f4c422a, v18
	v_add_f32_e32 v4, v4, v4
	v_mul_f32_e32 v4, 0x3fb8aa3b, v4
	v_exp_f32_e32 v19, v4
	v_mul_f32_e32 v4, 0x3d372713, v6
	v_mul_f32_e32 v4, v4, v6
	v_mov_b32_e32 v18, v6
	v_fmac_f32_e32 v18, v4, v18
	v_mul_f32_e32 v4, 0x3f4c422a, v18
	v_add_f32_e32 v4, v4, v4
	v_mul_f32_e32 v4, 0x3fb8aa3b, v4
	v_exp_f32_e32 v18, v4
	v_pk_mul_f32 v[6:7], v[6:7], 0.5 op_sel_hi:[1,0]
	v_pk_add_f32 v[18:19], v[18:19], 1.0 op_sel_hi:[1,0]
	s_nop 0
	v_div_scale_f32 v4, s[14:15], v19, v19, 2.0
	v_rcp_f32_e32 v21, v4
	s_nop 0
	v_fma_f32 v22, -v4, v21, 1.0
	v_fmac_f32_e32 v21, v22, v21
	v_div_scale_f32 v22, vcc, 2.0, v19, 2.0
	v_mul_f32_e32 v23, v22, v21
	v_fma_f32 v24, -v4, v23, v22
	v_fmac_f32_e32 v23, v24, v21
	v_fma_f32 v4, -v4, v23, v22
	v_div_fmas_f32 v4, v4, v21, v23
	v_div_fixup_f32 v19, v4, v19, 2.0
	v_div_scale_f32 v4, s[14:15], v18, v18, 2.0
	v_rcp_f32_e32 v21, v4
	s_nop 0
	v_fma_f32 v22, -v4, v21, 1.0
	v_fmac_f32_e32 v21, v22, v21
	v_div_scale_f32 v22, vcc, 2.0, v18, 2.0
	v_mul_f32_e32 v23, v22, v21
	v_fma_f32 v24, -v4, v23, v22
	v_fmac_f32_e32 v23, v24, v21
	v_fma_f32 v4, -v4, v23, v22
	v_div_fmas_f32 v4, v4, v21, v23
	v_div_fixup_f32 v18, v4, v18, 2.0
	v_pk_add_f32 v[18:19], v[18:19], 1.0 op_sel_hi:[1,0] neg_lo:[1,0] neg_hi:[1,0]
	s_nop 0
	v_pk_add_f32 v[18:19], v[18:19], 1.0 op_sel_hi:[1,0]
	s_nop 0
	v_pk_mul_f32 v[6:7], v[6:7], v[18:19]
	s_nop 0
	v_pk_mul_f32 v[18:19], v[6:7], v[6:7]
	s_nop 0
	v_add_f32_e32 v4, v19, v20
	v_add_f32_e32 v20, v18, v4
	v_and_b32_e32 v4, 0xffff0000, v5
	v_lshlrev_b32_e32 v5, 16, v5
	v_mul_f32_e32 v18, 0x3d372713, v5
	v_mul_f32_e32 v18, v18, v5
	v_mov_b32_e32 v19, v5
	v_fmac_f32_e32 v19, v18, v19
	v_mul_f32_e32 v18, 0x3f4c422a, v19
	v_add_f32_e32 v18, v18, v18
	v_mul_f32_e32 v18, 0x3fb8aa3b, v18
	v_exp_f32_e32 v19, v18
	v_mul_f32_e32 v18, 0x3d372713, v4
	v_mul_f32_e32 v18, v18, v4
	v_mov_b32_e32 v21, v4
	v_fmac_f32_e32 v21, v18, v21
	v_mul_f32_e32 v18, 0x3f4c422a, v21
	v_add_f32_e32 v18, v18, v18
	v_mul_f32_e32 v18, 0x3fb8aa3b, v18
	v_exp_f32_e32 v18, v18
	v_pk_mul_f32 v[4:5], v[4:5], 0.5 op_sel_hi:[1,0]
	v_pk_add_f32 v[18:19], v[18:19], 1.0 op_sel_hi:[1,0]
	s_nop 0
	v_div_scale_f32 v21, s[14:15], v19, v19, 2.0
	v_rcp_f32_e32 v22, v21
	s_nop 0
	v_fma_f32 v23, -v21, v22, 1.0
	v_fmac_f32_e32 v22, v23, v22
	v_div_scale_f32 v23, vcc, 2.0, v19, 2.0
	v_mul_f32_e32 v24, v23, v22
	v_fma_f32 v25, -v21, v24, v23
	v_fmac_f32_e32 v24, v25, v22
	v_fma_f32 v21, -v21, v24, v23
	v_div_fmas_f32 v21, v21, v22, v24
	v_div_fixup_f32 v19, v21, v19, 2.0
	v_div_scale_f32 v21, s[14:15], v18, v18, 2.0
	v_rcp_f32_e32 v22, v21
	s_nop 0
	v_fma_f32 v23, -v21, v22, 1.0
	v_fmac_f32_e32 v22, v23, v22
	v_div_scale_f32 v23, vcc, 2.0, v18, 2.0
	v_mul_f32_e32 v24, v23, v22
	v_fma_f32 v25, -v21, v24, v23
	v_fmac_f32_e32 v24, v25, v22
	v_fma_f32 v21, -v21, v24, v23
	v_div_fmas_f32 v21, v21, v22, v24
	v_div_fixup_f32 v18, v21, v18, 2.0
	v_pk_add_f32 v[18:19], v[18:19], 1.0 op_sel_hi:[1,0] neg_lo:[1,0] neg_hi:[1,0]
	s_nop 0
	v_pk_add_f32 v[18:19], v[18:19], 1.0 op_sel_hi:[1,0]
	s_nop 0
	v_pk_mul_f32 v[18:19], v[4:5], v[18:19]
	s_nop 0
	v_pk_mul_f32 v[4:5], v[18:19], v[18:19]
	s_nop 0
	v_add_f32_e32 v5, v5, v20
	v_add_f32_e32 v4, v4, v5
	s_nop 1
	v_mov_b32_dpp v5, v4 quad_perm:[1,0,3,2] row_mask:0xf bank_mask:0xf
	s_waitcnt lgkmcnt(0)
	v_add_f32_e32 v4, v4, v5
	s_nop 1
	v_mov_b32_dpp v5, v4 quad_perm:[2,3,0,1] row_mask:0xf bank_mask:0xf
	s_waitcnt lgkmcnt(0)
	v_add_f32_e32 v4, v4, v5
	s_nop 1
	v_mov_b32_dpp v5, v4 row_half_mirror row_mask:0xf bank_mask:0xf
	s_waitcnt lgkmcnt(0)
	v_add_f32_e32 v4, v4, v5
	s_nop 1
	v_mov_b32_dpp v5, v4 row_mirror row_mask:0xf bank_mask:0xf
	s_waitcnt lgkmcnt(0)
	v_add_f32_e32 v4, v4, v5
	ds_bpermute_b32 v5, v110, v4
	s_waitcnt lgkmcnt(0)
	v_add_f32_e32 v4, v4, v5
	v_fmamk_f32 v4, v4, 0x3b800000, v243
	v_cmp_gt_f32_e32 vcc, s3, v4
	v_mul_f32_e32 v5, 0x4b800000, v4
	s_nop 0
	v_cndmask_b32_e32 v4, v4, v5, vcc
	v_rsq_f32_e32 v4, v4
	s_nop 0
	v_mul_f32_e32 v5, 0x45800000, v4
	v_cndmask_b32_e32 v20, v4, v5, vcc
	v_mul_f32_e32 v4, v12, v20
	v_mul_f32_e32 v5, v13, v20
	v_mul_f32_e32 v2, v2, v20
	v_mul_f32_e32 v4, v70, v4
	v_mul_f32_e32 v5, v71, v5
	v_mul_f32_e32 v3, v3, v20
	v_mul_f32_e32 v2, v73, v2
	v_cvt_pk_bf16_f32 v4, v4, v5
	v_cvt_pk_bf16_f32 v11, v14, v15
	v_mul_f32_e32 v3, v72, v3
	v_cvt_pk_bf16_f32 v5, v3, v2
	v_mul_f32_e32 v2, v7, v20
	v_mul_f32_e32 v2, v66, v2
	v_mul_f32_e32 v3, v6, v20
	v_cvt_pk_bf16_f32 v12, v16, v8
	v_mul_f32_e32 v3, v67, v3
	v_cvt_pk_bf16_f32 v6, v2, v3
	v_mul_f32_e32 v2, v19, v20
	v_mul_f32_e32 v2, v68, v2
	v_mul_f32_e32 v3, v18, v20
	v_cvt_pk_bf16_f32 v13, v17, v9
	v_mul_f32_e32 v3, v69, v3
	v_cvt_pk_bf16_f32 v7, v2, v3
	global_load_dword v204, v[74:75], off
	global_load_dword v205, v[74:75], off offset:128
	v_lshl_add_u64 v[200:201], v[98:99], 0, v[0:1]
	v_lshl_add_u64 v[202:203], v[100:101], 0, v[0:1]
	v_lshl_add_u64 v[200:201], s[4:5], 0, v[200:201]
	v_lshl_add_u64 v[202:203], s[4:5], 0, v[202:203]
	global_load_dwordx4 v[136:139], v[200:201], off
	global_load_dwordx4 v[140:143], v[202:203], off
	global_load_dwordx4 v[144:147], v[200:201], off offset:32
	global_load_dwordx4 v[148:151], v[202:203], off offset:32
	global_load_dwordx4 v[152:155], v[200:201], off offset:64
	global_load_dwordx4 v[156:159], v[202:203], off offset:64
	global_load_dwordx4 v[160:163], v[200:201], off offset:96
	global_load_dwordx4 v[164:167], v[202:203], off offset:96
	global_load_dwordx4 v[168:171], v[200:201], off offset:128
	global_load_dwordx4 v[172:175], v[202:203], off offset:128
	global_load_dwordx4 v[176:179], v[200:201], off offset:160
	global_load_dwordx4 v[180:183], v[202:203], off offset:160
	global_load_dwordx4 v[184:187], v[200:201], off offset:192
	global_load_dwordx4 v[188:191], v[202:203], off offset:192
	global_load_dwordx4 v[192:195], v[200:201], off offset:224
	global_load_dwordx4 v[196:199], v[202:203], off offset:224
	v_mov_b32_e32 v2, 0
	ds_write_b128 v111, v[10:13] offset:60928
	ds_write_b128 v112, v[4:7] offset:60928
	v_mov_b32_e32 v3, v2
	v_mov_b32_e32 v4, v2
	v_mov_b32_e32 v5, v2
	v_mov_b32_e32 v6, v2
	v_mov_b32_e32 v7, v2
	v_mov_b32_e32 v8, v2
	v_mov_b32_e32 v9, v2
	v_mov_b32_e32 v10, v2
	v_mov_b32_e32 v11, v2
	v_mov_b32_e32 v12, v2
	v_mov_b32_e32 v13, v2
	v_mov_b32_e32 v14, v2
	v_mov_b32_e32 v15, v2
	v_mov_b32_e32 v16, v2
	v_mov_b32_e32 v17, v2
	v_mov_b32_e32 v18, v2
	v_mov_b32_e32 v19, v2
	v_mov_b32_e32 v20, v2
	v_mov_b32_e32 v21, v2
	v_mov_b32_e32 v22, v2
	v_mov_b32_e32 v23, v2
	v_mov_b32_e32 v24, v2
	v_mov_b32_e32 v25, v2
	v_mov_b32_e32 v26, v2
	v_mov_b32_e32 v27, v2
	v_mov_b32_e32 v28, v2
	v_mov_b32_e32 v29, v2
	v_mov_b32_e32 v30, v2
	v_mov_b32_e32 v31, v2
	v_mov_b32_e32 v32, v2
	v_mov_b32_e32 v33, v2
	v_mov_b32_e32 v34, v2
	v_mov_b32_e32 v35, v2
	v_mov_b32_e32 v36, v2
	v_mov_b32_e32 v37, v2
	v_mov_b32_e32 v38, v2
	v_mov_b32_e32 v39, v2
	v_mov_b32_e32 v40, v2
	v_mov_b32_e32 v41, v2
	v_mov_b32_e32 v42, v2
	v_mov_b32_e32 v43, v2
	v_mov_b32_e32 v44, v2
	v_mov_b32_e32 v45, v2
	v_mov_b32_e32 v46, v2
	v_mov_b32_e32 v47, v2
	v_mov_b32_e32 v48, v2
	v_mov_b32_e32 v49, v2
	v_mov_b32_e32 v50, v2
	v_mov_b32_e32 v51, v2
	v_mov_b32_e32 v52, v2
	v_mov_b32_e32 v53, v2
	v_mov_b32_e32 v54, v2
	v_mov_b32_e32 v55, v2
	v_mov_b32_e32 v56, v2
	v_mov_b32_e32 v57, v2
	v_mov_b32_e32 v58, v2
	v_mov_b32_e32 v59, v2
	v_mov_b32_e32 v60, v2
	v_mov_b32_e32 v61, v2
	v_mov_b32_e32 v62, v2
	v_mov_b32_e32 v63, v2
	v_mov_b32_e32 v64, v2
	v_mov_b32_e32 v65, v2
	s_waitcnt lgkmcnt(0)
	s_barrier
